# v18: v16 + work redistribution: norm-phase context rows (with slab fold) spread over all workgroups (even waves) instead of XCDs 0-3 only
# speedup vs baseline: 1.0067x; 1.0067x over previous
; #define GAS __attribute__((address_space(1)))
; #define LAS __attribute__((address_space(3)))
; #define NR_LOAD(dst, k_) do { const GAS v2u* xr_ = (const GAS v2u*)(X + (size_t)(nw + 2048 * (k_)) * D) + F.lane; \
;         _Pragma("unroll") for (int j = 0; j < 8; ++j) dst[j] = __builtin_nontemporal_load(xr_ + 64 * j); } while (0)
; __device__ __forceinline__ void norm_mod_phase2(const Args& a, Frame& F, const float* gain, const float* modl, int sh_off, int sc_off, int nrows, const float* slab_gate) {
;     ...
;     const int nw = F.vcu * NWAVES + F.wave;
;     bf16* X = (bf16*)(a.ws + WS_X); bf16* HN = (bf16*)(a.ws + WS_HN);
;     LAS float* CA = (LAS float*)F.lds; LAS float* CB = CA + 5 * D;
;     v2u r0[8], r1[8], r2[8], r3[8], r4[8], r5[8], r6[8], r7[8];
;     ...
;     NR_LOAD(r0, 0); NR_LOAD(r1, 1); NR_LOAD(r2, 2); NR_LOAD(r3, 3); NR_LOAD(r4, 4); NR_LOAD(r5, 5); NR_LOAD(r6, 6); NR_LOAD(r7, 7);
;     { const GAS f32x4* g4 = (const GAS f32x4*)gain;
;       for (int q = F.tid; q < 5 * D / 4; q += NWAVES * 64) { const int bq = q >> 9, cq = q & 511; const GAS f32x4* mb4 = (const GAS f32x4*)(modl + (size_t)bq * MOD_LD);
;           ((LAS f32x4*)CA)[q] = g4[cq] * (mb4[sc_off / 4 + cq] + 1.0f); ((LAS f32x4*)CB)[q] = mb4[sh_off / 4 + cq]; } }
.LBB0_215:
	s_andn2_b64 vcc, exec, s[4:5]
	s_cbranch_vccnz .LBB0_224
	s_getreg_b32 s4, hwreg(HW_REG_HW_ID, 0, 6)
	s_lshl_b32 s4, s4, 2
	s_add_i32 s4, s4, 0
	s_add_i32 s4, s4, 0x20540
	v_mov_b32_e32 v0, s4
	ds_read_b32 v0, v0
	v_mov_b64_e32 v[2:3], s[0:1]
	v_mbcnt_lo_u32_b32 v4, -1, 0
	v_mbcnt_hi_u32_b32 v4, -1, v4
	s_mov_b64 s[20:21], 0x400000
	v_mov_b32_e32 v7, v1
	s_waitcnt lgkmcnt(0)
	v_readfirstlane_b32 s4, v0
	s_nop 1
	v_lshl_add_u32 v142, s4, 6, v4
	v_mov_b32_e32 v128, s72
	v_mov_b32_e32 v129, s73
	v_readfirstlane_b32 s4, v142
	s_ashr_i32 s4, s4, 6
	s_add_i32 s4, s4, s91
	s_ashr_i32 s5, s4, 31
	s_add_i32 s36, s4, 0x800
	s_add_i32 s30, s4, 0x1000
	s_add_i32 s26, s4, 0x1800
	s_add_i32 s22, s4, 0x2000
	s_add_i32 s18, s4, 0x2800
	v_and_b32_e32 v143, 63, v142
	s_lshl_b64 s[6:7], s[4:5], 12
	s_ashr_i32 s37, s36, 31
	s_ashr_i32 s31, s30, 31
	s_ashr_i32 s27, s26, 31
	s_ashr_i32 s23, s22, 31
	s_ashr_i32 s19, s18, 31
	v_lshlrev_b32_e32 v6, 3, v143
	s_lshl_b64 s[8:9], s[36:37], 12
	s_lshl_b64 s[10:11], s[30:31], 12
	s_lshl_b64 s[12:13], s[26:27], 12
	s_lshl_b64 s[14:15], s[22:23], 12
	s_lshl_b64 s[16:17], s[18:19], 12
	s_waitcnt vmcnt(0) lgkmcnt(0)
	v_lshl_add_u64 v[8:9], v[128:129], 0, s[20:21]
	v_lshl_add_u64 v[2:3], v[8:9], 0, s[6:7]
	v_lshl_add_u64 v[4:5], v[8:9], 0, s[8:9]
	v_lshl_add_u64 v[10:11], v[8:9], 0, s[10:11]
	v_lshl_add_u64 v[12:13], v[8:9], 0, s[12:13]
	v_lshl_add_u64 v[14:15], v[8:9], 0, s[14:15]
	v_lshl_add_u64 v[16:17], v[8:9], 0, s[16:17]
	v_lshl_add_u64 v[2:3], v[2:3], 0, v[6:7]
	v_lshl_add_u64 v[4:5], v[4:5], 0, v[6:7]
	v_lshl_add_u64 v[10:11], v[10:11], 0, v[6:7]
	v_lshl_add_u64 v[12:13], v[12:13], 0, v[6:7]
	v_lshl_add_u64 v[14:15], v[14:15], 0, v[6:7]
	v_lshl_add_u64 v[16:17], v[16:17], 0, v[6:7]
	v_and_b32_e32 v184, 0x1ff, v142
	v_lshlrev_b32_e32 v184, 4, v184
	v_mov_b32_e32 v185, 0
	v_mov_b32_e32 v186, s76
	v_lshlrev_b32_e32 v186, 13, v186
	v_mov_b32_e32 v187, 0
	v_lshl_add_u64 v[188:189], v[74:75], 0, v[186:187]
	v_lshl_add_u64 v[188:189], v[188:189], 0, v[184:185]
	global_load_dwordx4 v[192:195], v[188:189], off
	v_add_u32_e32 v196, 0x2000, v184
	v_mov_b32_e32 v201, v184
	v_add_u32_e32 v197, 0xe000, v184
	v_add_u32_e32 v202, 0xc000, v184
	v_add_u32_e32 v198, 0x1a000, v184
	v_add_u32_e32 v203, 0x18000, v184
	v_add_u32_e32 v199, 0x26000, v184
	v_add_u32_e32 v204, 0x24000, v184
	v_add_u32_e32 v200, 0x32000, v184
	v_add_u32_e32 v205, 0x30000, v184
	global_load_dwordx4 v[208:211], v196, s[86:87]
	global_load_dwordx4 v[228:231], v201, s[86:87]
	global_load_dwordx4 v[212:215], v197, s[86:87]
	global_load_dwordx4 v[232:235], v202, s[86:87]
	global_load_dwordx4 v[216:219], v198, s[86:87]
	global_load_dwordx4 v[236:239], v203, s[86:87]
	global_load_dwordx4 v[220:223], v199, s[86:87]
	global_load_dwordx4 v[240:243], v204, s[86:87]
	global_load_dwordx4 v[224:227], v200, s[86:87]
	global_load_dwordx4 v[244:247], v205, s[86:87]
	global_load_dwordx2 v[140:141], v[2:3], off nt
	global_load_dwordx2 v[138:139], v[2:3], off offset:512 nt
	global_load_dwordx2 v[136:137], v[2:3], off offset:1024 nt
	global_load_dwordx2 v[132:133], v[2:3], off offset:1536 nt
	global_load_dwordx2 v[134:135], v[2:3], off offset:2048 nt
	global_load_dwordx2 v[124:125], v[2:3], off offset:2560 nt
	global_load_dwordx2 v[126:127], v[2:3], off offset:3072 nt
	global_load_dwordx2 v[130:131], v[2:3], off offset:3584 nt
	global_load_dwordx2 v[122:123], v[4:5], off nt
	global_load_dwordx2 v[120:121], v[4:5], off offset:512 nt
	global_load_dwordx2 v[118:119], v[4:5], off offset:1024 nt
	global_load_dwordx2 v[116:117], v[4:5], off offset:1536 nt
	global_load_dwordx2 v[114:115], v[4:5], off offset:2048 nt
	global_load_dwordx2 v[112:113], v[4:5], off offset:2560 nt
	global_load_dwordx2 v[110:111], v[4:5], off offset:3072 nt
	global_load_dwordx2 v[108:109], v[4:5], off offset:3584 nt
	global_load_dwordx2 v[106:107], v[10:11], off nt
	global_load_dwordx2 v[104:105], v[10:11], off offset:512 nt
	global_load_dwordx2 v[102:103], v[10:11], off offset:1024 nt
	global_load_dwordx2 v[100:101], v[10:11], off offset:1536 nt
	global_load_dwordx2 v[98:99], v[10:11], off offset:2048 nt
	global_load_dwordx2 v[96:97], v[10:11], off offset:2560 nt
	global_load_dwordx2 v[94:95], v[10:11], off offset:3072 nt
	global_load_dwordx2 v[92:93], v[10:11], off offset:3584 nt
	global_load_dwordx2 v[90:91], v[12:13], off nt
	global_load_dwordx2 v[88:89], v[12:13], off offset:512 nt
	global_load_dwordx2 v[86:87], v[12:13], off offset:1024 nt
	global_load_dwordx2 v[84:85], v[12:13], off offset:1536 nt
	global_load_dwordx2 v[82:83], v[12:13], off offset:2048 nt
	global_load_dwordx2 v[80:81], v[12:13], off offset:2560 nt
	global_load_dwordx2 v[78:79], v[12:13], off offset:3072 nt
	global_load_dwordx2 v[76:77], v[12:13], off offset:3584 nt
	global_load_dwordx2 v[72:73], v[14:15], off nt
	global_load_dwordx2 v[70:71], v[14:15], off offset:512 nt
	global_load_dwordx2 v[68:69], v[14:15], off offset:1024 nt
	global_load_dwordx2 v[66:67], v[14:15], off offset:1536 nt
	global_load_dwordx2 v[64:65], v[14:15], off offset:2048 nt
	global_load_dwordx2 v[62:63], v[14:15], off offset:2560 nt
	global_load_dwordx2 v[60:61], v[14:15], off offset:3072 nt
	global_load_dwordx2 v[58:59], v[14:15], off offset:3584 nt
	global_load_dwordx2 v[56:57], v[16:17], off nt
	global_load_dwordx2 v[54:55], v[16:17], off offset:512 nt
	global_load_dwordx2 v[52:53], v[16:17], off offset:1024 nt
	global_load_dwordx2 v[50:51], v[16:17], off offset:1536 nt
	global_load_dwordx2 v[48:49], v[16:17], off offset:2048 nt
	global_load_dwordx2 v[46:47], v[16:17], off offset:2560 nt
	global_load_dwordx2 v[44:45], v[16:17], off offset:3072 nt
	global_load_dwordx2 v[42:43], v[16:17], off offset:3584 nt
	s_add_i32 s14, s4, 0x3000
	s_ashr_i32 s15, s14, 31
	s_lshl_b64 s[6:7], s[14:15], 12
	s_add_i32 s10, s4, 0x3800
	v_lshl_add_u64 v[2:3], v[8:9], 0, s[6:7]
	s_ashr_i32 s11, s10, 31
	v_lshl_add_u64 v[2:3], v[2:3], 0, v[6:7]
	s_lshl_b64 s[6:7], s[10:11], 12
	global_load_dwordx2 v[40:41], v[2:3], off nt
	global_load_dwordx2 v[38:39], v[2:3], off offset:512 nt
	global_load_dwordx2 v[36:37], v[2:3], off offset:1024 nt
	global_load_dwordx2 v[34:35], v[2:3], off offset:1536 nt
	global_load_dwordx2 v[32:33], v[2:3], off offset:2048 nt
	global_load_dwordx2 v[30:31], v[2:3], off offset:2560 nt
	global_load_dwordx2 v[28:29], v[2:3], off offset:3072 nt
	global_load_dwordx2 v[26:27], v[2:3], off offset:3584 nt
	v_lshl_add_u64 v[2:3], v[8:9], 0, s[6:7]
	v_lshl_add_u64 v[2:3], v[2:3], 0, v[6:7]
	global_load_dwordx2 v[24:25], v[2:3], off nt
	global_load_dwordx2 v[22:23], v[2:3], off offset:512 nt
	global_load_dwordx2 v[20:21], v[2:3], off offset:1024 nt
	global_load_dwordx2 v[18:19], v[2:3], off offset:1536 nt
	global_load_dwordx2 v[16:17], v[2:3], off offset:2048 nt
	global_load_dwordx2 v[14:15], v[2:3], off offset:2560 nt
	global_load_dwordx2 v[12:13], v[2:3], off offset:3072 nt
	global_load_dwordx2 v[10:11], v[2:3], off offset:3584 nt
	s_waitcnt vmcnt(62)
; #define GAS __attribute__((address_space(1)))
; #define LAS __attribute__((address_space(3)))
; #define NR_LOAD(dst, k_) do { const GAS v2u* xr_ = (const GAS v2u*)(X + (size_t)(nw + 2048 * (k_)) * D) + F.lane; \
;         _Pragma("unroll") for (int j = 0; j < 8; ++j) dst[j] = __builtin_nontemporal_load(xr_ + 64 * j); } while (0)
; __device__ __forceinline__ void norm_mod_phase2(const Args& a, Frame& F, const float* gain, const float* modl, int sh_off, int sc_off, int nrows, const float* slab_gate) {
;     ...
;     NR_LOAD(r0, 0); NR_LOAD(r1, 1); NR_LOAD(r2, 2); NR_LOAD(r3, 3); NR_LOAD(r4, 4); NR_LOAD(r5, 5); NR_LOAD(r6, 6); NR_LOAD(r7, 7);
;     { const GAS f32x4* g4 = (const GAS f32x4*)gain;
;       for (int q = F.tid; q < 5 * D / 4; q += NWAVES * 64) { const int bq = q >> 9, cq = q & 511; const GAS f32x4* mb4 = (const GAS f32x4*)(modl + (size_t)bq * MOD_LD);
;           ((LAS f32x4*)CA)[q] = g4[cq] * (mb4[sc_off / 4 + cq] + 1.0f); ((LAS f32x4*)CB)[q] = mb4[sh_off / 4 + cq]; } }
;     asm volatile("s_waitcnt lgkmcnt(0)" ::: "memory"); __builtin_amdgcn_s_barrier(); asm volatile("" ::: "memory");
	v_lshl_add_u32 v184, v142, 4, 0
	v_add_u32_e32 v185, 0xa000, v184
	v_pk_add_f32 v[210:211], v[210:211], 1.0 op_sel_hi:[1,0]
	v_pk_add_f32 v[208:209], v[208:209], 1.0 op_sel_hi:[1,0]
	v_pk_mul_f32 v[210:211], v[194:195], v[210:211]
	v_pk_mul_f32 v[208:209], v[192:193], v[208:209]
	ds_write_b128 v184, v[208:211]
	ds_write_b128 v185, v[228:231]
	v_pk_add_f32 v[214:215], v[214:215], 1.0 op_sel_hi:[1,0]
	v_pk_add_f32 v[212:213], v[212:213], 1.0 op_sel_hi:[1,0]
	v_pk_mul_f32 v[214:215], v[194:195], v[214:215]
	v_pk_mul_f32 v[212:213], v[192:193], v[212:213]
	ds_write_b128 v184, v[212:215] offset:8192
	ds_write_b128 v185, v[232:235] offset:8192
	v_pk_add_f32 v[218:219], v[218:219], 1.0 op_sel_hi:[1,0]
	v_pk_add_f32 v[216:217], v[216:217], 1.0 op_sel_hi:[1,0]
	v_pk_mul_f32 v[218:219], v[194:195], v[218:219]
	v_pk_mul_f32 v[216:217], v[192:193], v[216:217]
	ds_write_b128 v184, v[216:219] offset:16384
	ds_write_b128 v185, v[236:239] offset:16384
	v_pk_add_f32 v[222:223], v[222:223], 1.0 op_sel_hi:[1,0]
	v_pk_add_f32 v[220:221], v[220:221], 1.0 op_sel_hi:[1,0]
	v_pk_mul_f32 v[222:223], v[194:195], v[222:223]
	v_pk_mul_f32 v[220:221], v[192:193], v[220:221]
	ds_write_b128 v184, v[220:223] offset:24576
	ds_write_b128 v185, v[240:243] offset:24576
	v_pk_add_f32 v[226:227], v[226:227], 1.0 op_sel_hi:[1,0]
	v_pk_add_f32 v[224:225], v[224:225], 1.0 op_sel_hi:[1,0]
	v_pk_mul_f32 v[226:227], v[194:195], v[226:227]
	v_pk_mul_f32 v[224:225], v[192:193], v[224:225]
	ds_write_b128 v184, v[224:227] offset:32768
	ds_write_b128 v185, v[244:247] offset:32768
	s_waitcnt vmcnt(62)
	v_cvt_f32_f16_sdwa v153, v140 dst_sel:DWORD dst_unused:UNUSED_PAD src0_sel:WORD_1
	v_cvt_f32_f16_sdwa v149, v138 dst_sel:DWORD dst_unused:UNUSED_PAD src0_sel:WORD_1
	v_cvt_f32_f16_e32 v152, v140
	v_cvt_f32_f16_sdwa v155, v141 dst_sel:DWORD dst_unused:UNUSED_PAD src0_sel:WORD_1
	v_cvt_f32_f16_e32 v148, v138
	v_cvt_f32_f16_sdwa v151, v139 dst_sel:DWORD dst_unused:UNUSED_PAD src0_sel:WORD_1
	v_cvt_f32_f16_e32 v154, v141
	v_cvt_f32_f16_e32 v150, v139
	s_waitcnt vmcnt(61)
	v_cvt_f32_f16_sdwa v139, v136 dst_sel:DWORD dst_unused:UNUSED_PAD src0_sel:WORD_1
	v_cvt_f32_f16_sdwa v141, v137 dst_sel:DWORD dst_unused:UNUSED_PAD src0_sel:WORD_1
	s_mov_b64 s[6:7], 0x8c00000
	v_mov_b32_e32 v74, v153
	v_mov_b32_e32 v75, v149
	v_cvt_f32_f16_e32 v138, v136
	v_cvt_f32_f16_e32 v140, v137
	v_lshl_add_u64 v[2:3], v[128:129], 0, s[6:7]
	v_mov_b32_e32 v4, v152
	v_mov_b32_e32 v5, v148
	v_pk_mul_f32 v[74:75], v[74:75], v[74:75]
	v_mov_b32_e32 v128, v155
	v_mov_b32_e32 v129, v151
	v_pk_fma_f32 v[4:5], v[4:5], v[4:5], v[74:75]
	v_mov_b32_e32 v74, v154
	v_mov_b32_e32 v75, v150
	v_pk_mul_f32 v[128:129], v[128:129], v[128:129]
	s_waitcnt vmcnt(60)
	v_cvt_f32_f16_sdwa v145, v132 dst_sel:DWORD dst_unused:UNUSED_PAD src0_sel:WORD_1
	v_pk_fma_f32 v[74:75], v[74:75], v[74:75], v[128:129]
	v_mov_b32_e32 v128, v139
	v_mov_b32_e32 v129, v141
	v_pk_add_f32 v[4:5], v[4:5], v[74:75]
	v_mov_b32_e32 v74, v138
	v_mov_b32_e32 v75, v140
	v_pk_mul_f32 v[128:129], v[128:129], v[128:129]
	v_cvt_f32_f16_e32 v144, v132
	v_cvt_f32_f16_sdwa v147, v133 dst_sel:DWORD dst_unused:UNUSED_PAD src0_sel:WORD_1
	v_pk_fma_f32 v[74:75], v[74:75], v[74:75], v[128:129]
	v_cvt_f32_f16_e32 v146, v133
	s_waitcnt vmcnt(59)
	v_cvt_f32_f16_sdwa v129, v134 dst_sel:DWORD dst_unused:UNUSED_PAD src0_sel:WORD_1
	v_cvt_f32_f16_e32 v128, v134
	v_cvt_f32_f16_sdwa v133, v135 dst_sel:DWORD dst_unused:UNUSED_PAD src0_sel:WORD_1
	v_cvt_f32_f16_e32 v132, v135
	v_mul_f32_e32 v0, v145, v145
	v_pk_fma_f32 v[136:137], v[144:145], v[144:145], v[0:1] op_sel_hi:[1,1,0]
	v_mul_f32_e32 v0, v147, v147
	v_pk_add_f32 v[4:5], v[4:5], v[4:5] op_sel:[0,1] op_sel_hi:[1,0]
	v_pk_add_f32 v[74:75], v[74:75], v[74:75] op_sel:[0,1] op_sel_hi:[1,0]
	v_pk_fma_f32 v[156:157], v[146:147], v[146:147], v[0:1] op_sel_hi:[1,1,0]
	v_pk_mul_f32 v[134:135], v[128:129], v[128:129]
	v_pk_mul_f32 v[158:159], v[132:133], v[132:133]
	v_mov_b32_e32 v5, v134
	v_mov_b32_e32 v75, v135
	v_mov_b32_e32 v137, v158
	v_mov_b32_e32 v157, v159
	v_pk_add_f32 v[4:5], v[4:5], v[74:75]
	v_pk_add_f32 v[74:75], v[136:137], v[156:157]
	s_waitcnt vmcnt(58)
	v_cvt_f32_f16_sdwa v135, v124 dst_sel:DWORD dst_unused:UNUSED_PAD src0_sel:WORD_1
	v_cvt_f32_f16_sdwa v137, v125 dst_sel:DWORD dst_unused:UNUSED_PAD src0_sel:WORD_1
	v_cvt_f32_f16_e32 v134, v124
	v_cvt_f32_f16_e32 v136, v125
	v_pk_add_f32 v[4:5], v[4:5], v[74:75]
	v_mov_b32_e32 v74, v135
	v_mov_b32_e32 v75, v137
	v_pk_add_f32 v[156:157], v[4:5], v[4:5] op_sel:[0,1] op_sel_hi:[1,0]
	v_mov_b32_e32 v4, v134
	v_mov_b32_e32 v5, v136
	v_pk_mul_f32 v[74:75], v[74:75], v[74:75]
	s_waitcnt vmcnt(57)
	v_cvt_f32_f16_sdwa v125, v127 dst_sel:DWORD dst_unused:UNUSED_PAD src0_sel:WORD_1
	v_pk_fma_f32 v[4:5], v[4:5], v[4:5], v[74:75]
	v_cvt_f32_f16_e32 v124, v127
	v_pk_add_f32 v[158:159], v[4:5], v[4:5] op_sel:[0,1] op_sel_hi:[1,0]
	v_cvt_f32_f16_sdwa v5, v126 dst_sel:DWORD dst_unused:UNUSED_PAD src0_sel:WORD_1
	v_cvt_f32_f16_e32 v4, v126
	s_waitcnt vmcnt(56)
	v_cvt_f32_f16_sdwa v75, v130 dst_sel:DWORD dst_unused:UNUSED_PAD src0_sel:WORD_1
	v_cvt_f32_f16_e32 v74, v130
	v_cvt_f32_f16_sdwa v127, v131 dst_sel:DWORD dst_unused:UNUSED_PAD src0_sel:WORD_1
	v_cvt_f32_f16_e32 v126, v131
	v_mul_f32_e32 v0, v5, v5
	v_pk_fma_f32 v[160:161], v[4:5], v[4:5], v[0:1] op_sel_hi:[1,1,0]
	v_mul_f32_e32 v0, v125, v125
	v_pk_fma_f32 v[162:163], v[124:125], v[124:125], v[0:1] op_sel_hi:[1,1,0]
	v_pk_mul_f32 v[130:131], v[74:75], v[74:75]
	v_pk_mul_f32 v[164:165], v[126:127], v[126:127]
	v_mov_b32_e32 v157, v130
	v_mov_b32_e32 v159, v131
	v_mov_b32_e32 v161, v164
	v_mov_b32_e32 v163, v165
	v_pk_add_f32 v[130:131], v[156:157], v[158:159]
	v_pk_add_f32 v[156:157], v[160:161], v[162:163]
	s_lshl_b64 s[8:9], s[4:5], 11
	v_pk_add_f32 v[130:131], v[130:131], v[156:157]
	s_lshl_b64 s[12:13], s[10:11], 11
	v_add_f32_e32 v0, v130, v131
	s_waitcnt lgkmcnt(0)
	s_barrier
; template <int CTRL> __device__ __forceinline__ float dpp_mov(float v) { return __builtin_bit_cast(float, __builtin_amdgcn_update_dpp(0, __builtin_bit_cast(int, v), CTRL, 0xF, 0xF, true)); }
; __device__ __forceinline__ float wave_sum(float v) {
;     v += dpp_mov<0xB1>(v);
;     v += dpp_mov<0x4E>(v);
;     v += dpp_mov<0x141>(v);
;     v += dpp_mov<0x140>(v);
;     const int iv = __builtin_bit_cast(int, v);
;     const float a = __builtin_bit_cast(float, __builtin_amdgcn_readlane(iv, 0)), b = __builtin_bit_cast(float, __builtin_amdgcn_readlane(iv, 16));
;     const float c = __builtin_bit_cast(float, __builtin_amdgcn_readlane(iv, 32)), d = __builtin_bit_cast(float, __builtin_amdgcn_readlane(iv, 48));
;     return (a + b) + (c + d);
	s_lshl_b64 s[40:41], s[36:37], 11
	v_add_f32_dpp v0, v0, v0 quad_perm:[1,0,3,2] row_mask:0xf bank_mask:0xf bound_ctrl:1
	s_lshl_b64 s[34:35], s[30:31], 11
	s_lshl_b64 s[28:29], s[26:27], 11
	v_add_f32_dpp v0, v0, v0 quad_perm:[2,3,0,1] row_mask:0xf bank_mask:0xf bound_ctrl:1
	s_lshl_b64 s[24:25], s[22:23], 11
	s_lshl_b64 s[20:21], s[18:19], 11
	v_add_f32_dpp v0, v0, v0 row_half_mirror row_mask:0xf bank_mask:0xf bound_ctrl:1
	s_lshl_b64 s[16:17], s[14:15], 11
	s_nop 0
	v_add_f32_dpp v0, v0, v0 row_mirror row_mask:0xf bank_mask:0xf bound_ctrl:1
	s_nop 0
	v_readlane_b32 s5, v0, 16
	v_readlane_b32 s11, v0, 48
	v_readlane_b32 s6, v0, 0
	v_readlane_b32 s7, v0, 32
	v_mov_b32_e32 v130, s5
	v_mov_b32_e32 v131, s11
	v_pk_add_f32 v[130:131], s[6:7], v[130:131]
	s_lshl_b32 s5, s4, 1
	v_add_f32_e32 v0, v130, v131
	v_fmamk_f32 v0, v0, 0x3a000000, v252
	v_cmp_gt_f32_e32 vcc, s55, v0
	v_mul_f32_e32 v7, 0x4f800000, v0
	s_and_b32 s5, s5, 0xffffe000
	v_cndmask_b32_e32 v0, v0, v7, vcc
	v_sqrt_f32_e32 v7, v0
	s_add_i32 s5, s5, 0
	v_add_u32_e32 v130, -1, v7
	v_fma_f32 v131, -v130, v7, v0
	v_cmp_ge_f32_e64 s[6:7], 0, v131
	v_add_u32_e32 v131, 1, v7
	s_nop 0
	v_cndmask_b32_e64 v130, v7, v130, s[6:7]
	v_fma_f32 v7, -v131, v7, v0
	v_cmp_lt_f32_e64 s[6:7], 0, v7
	s_nop 1
	v_cndmask_b32_e64 v7, v130, v131, s[6:7]
	v_mul_f32_e32 v130, 0x37800000, v7
	v_cndmask_b32_e32 v7, v7, v130, vcc
	v_cmp_class_f32_e32 vcc, v0, v253
	s_nop 1
	v_cndmask_b32_e32 v0, v7, v0, vcc
	v_div_scale_f32 v7, s[6:7], v0, v0, 1.0
	v_rcp_f32_e32 v130, v7
	s_nop 0
	v_fma_f32 v131, -v7, v130, 1.0
	v_fmac_f32_e32 v130, v131, v130
	v_div_scale_f32 v131, vcc, 1.0, v0, 1.0
	v_mul_f32_e32 v142, v131, v130
	v_fma_f32 v156, -v7, v142, v131
	v_fmac_f32_e32 v142, v156, v130
	v_fma_f32 v7, -v7, v142, v131
	v_div_fmas_f32 v7, v7, v130, v142
	v_div_fixup_f32 v142, v7, v0, 1.0
	v_lshlrev_b32_e32 v0, 4, v143
	v_add_u32_e32 v164, s5, v0
	v_pk_mul_f32 v[160:161], v[152:153], v[142:143] op_sel_hi:[1,0]
	v_pk_mul_f32 v[162:163], v[154:155], v[142:143] op_sel_hi:[1,0]
	ds_read_b128 v[152:155], v164
	ds_read_b128 v[156:159], v164 offset:40960
	v_lshl_add_u64 v[130:131], s[8:9], 1, v[2:3]
	v_mov_b32_e32 v7, v1
	v_lshl_add_u64 v[130:131], v[130:131], 0, v[6:7]
	v_pk_mul_f32 v[128:129], v[128:129], v[142:143] op_sel_hi:[1,0]
	s_waitcnt lgkmcnt(0)
	v_pk_fma_f32 v[154:155], v[154:155], v[162:163], v[158:159]
	v_pk_fma_f32 v[152:153], v[152:153], v[160:161], v[156:157]
	v_pk_mul_f32 v[156:157], v[148:149], v[142:143] op_sel_hi:[1,0]
	v_cvt_pk_bf16_f32 v152, v152, v153
	v_cvt_pk_bf16_f32 v153, v154, v155
	global_store_dwordx2 v[130:131], v[152:153], off
	v_pk_mul_f32 v[158:159], v[150:151], v[142:143] op_sel_hi:[1,0]
	ds_read_b128 v[148:151], v164 offset:1024
	ds_read_b128 v[152:155], v164 offset:41984
	v_pk_mul_f32 v[132:133], v[132:133], v[142:143] op_sel_hi:[1,0]
	v_pk_mul_f32 v[4:5], v[4:5], v[142:143] op_sel_hi:[1,0]
	v_pk_mul_f32 v[124:125], v[124:125], v[142:143] op_sel_hi:[1,0]
	s_waitcnt lgkmcnt(0)
	v_pk_fma_f32 v[150:151], v[150:151], v[158:159], v[154:155]
	v_pk_fma_f32 v[148:149], v[148:149], v[156:157], v[152:153]
	v_pk_mul_f32 v[152:153], v[138:139], v[142:143] op_sel_hi:[1,0]
	v_cvt_pk_bf16_f32 v148, v148, v149
	v_cvt_pk_bf16_f32 v149, v150, v151
	global_store_dwordx2 v[130:131], v[148:149], off offset:512
	v_pk_mul_f32 v[154:155], v[140:141], v[142:143] op_sel_hi:[1,0]
	ds_read_b128 v[138:141], v164 offset:2048
	ds_read_b128 v[148:151], v164 offset:43008
	s_waitcnt lgkmcnt(0)
	v_pk_fma_f32 v[140:141], v[140:141], v[154:155], v[150:151]
	v_pk_fma_f32 v[138:139], v[138:139], v[152:153], v[148:149]
	v_pk_mul_f32 v[148:149], v[144:145], v[142:143] op_sel_hi:[1,0]
	v_cvt_pk_bf16_f32 v138, v138, v139
	v_cvt_pk_bf16_f32 v139, v140, v141
	global_store_dwordx2 v[130:131], v[138:139], off offset:1024
	v_pk_mul_f32 v[150:151], v[146:147], v[142:143] op_sel_hi:[1,0]
	ds_read_b128 v[138:141], v164 offset:3072
	ds_read_b128 v[144:147], v164 offset:44032
	s_waitcnt lgkmcnt(0)
	v_pk_fma_f32 v[140:141], v[150:151], v[140:141], v[146:147]
	v_pk_fma_f32 v[138:139], v[148:149], v[138:139], v[144:145]
	s_nop 0
	v_cvt_pk_bf16_f32 v138, v138, v139
	v_cvt_pk_bf16_f32 v139, v140, v141
	global_store_dwordx2 v[130:131], v[138:139], off offset:1536
	ds_read_b128 v[138:141], v164 offset:4096
	ds_read_b128 v[144:147], v164 offset:45056
	s_waitcnt lgkmcnt(0)
	v_pk_fma_f32 v[132:133], v[132:133], v[140:141], v[146:147]
	v_pk_fma_f32 v[128:129], v[128:129], v[138:139], v[144:145]
	v_pk_mul_f32 v[140:141], v[136:137], v[142:143] op_sel_hi:[1,0]
	v_cvt_pk_bf16_f32 v128, v128, v129
	v_cvt_pk_bf16_f32 v129, v132, v133
	global_store_dwordx2 v[130:131], v[128:129], off offset:2048
	v_pk_mul_f32 v[128:129], v[134:135], v[142:143] op_sel_hi:[1,0]
	ds_read_b128 v[132:135], v164 offset:5120
	ds_read_b128 v[136:139], v164 offset:46080
	s_waitcnt lgkmcnt(0)
	v_pk_fma_f32 v[134:135], v[140:141], v[134:135], v[138:139]
	v_pk_fma_f32 v[128:129], v[128:129], v[132:133], v[136:137]
	s_nop 0
	v_cvt_pk_bf16_f32 v128, v128, v129
	v_cvt_pk_bf16_f32 v129, v134, v135
	global_store_dwordx2 v[130:131], v[128:129], off offset:2560
	ds_read_b128 v[132:135], v164 offset:6144
	ds_read_b128 v[136:139], v164 offset:47104
	s_waitcnt vmcnt(58)
	v_cvt_f32_f16_sdwa v129, v117 dst_sel:DWORD dst_unused:UNUSED_PAD src0_sel:WORD_1
	v_cvt_f32_f16_e32 v128, v117
	s_waitcnt lgkmcnt(0)
	v_pk_fma_f32 v[124:125], v[124:125], v[134:135], v[138:139]
	v_pk_fma_f32 v[4:5], v[4:5], v[132:133], v[136:137]
	v_cvt_f32_f16_sdwa v137, v122 dst_sel:DWORD dst_unused:UNUSED_PAD src0_sel:WORD_1
	v_cvt_pk_bf16_f32 v4, v4, v5
	v_cvt_pk_bf16_f32 v5, v124, v125
	global_store_dwordx2 v[130:131], v[4:5], off offset:3072
	v_pk_mul_f32 v[4:5], v[74:75], v[142:143] op_sel_hi:[1,0]
	v_pk_mul_f32 v[74:75], v[126:127], v[142:143] op_sel_hi:[1,0]
	ds_read_b128 v[124:127], v164 offset:7168
	ds_read_b128 v[132:135], v164 offset:48128
	v_cvt_f32_f16_e32 v136, v122
	v_cvt_f32_f16_sdwa v139, v123 dst_sel:DWORD dst_unused:UNUSED_PAD src0_sel:WORD_1
	v_cvt_f32_f16_e32 v138, v123
	v_cvt_f32_f16_sdwa v123, v118 dst_sel:DWORD dst_unused:UNUSED_PAD src0_sel:WORD_1
	s_waitcnt lgkmcnt(0)
	v_pk_fma_f32 v[4:5], v[4:5], v[124:125], v[132:133]
	v_cvt_f32_f16_sdwa v133, v120 dst_sel:DWORD dst_unused:UNUSED_PAD src0_sel:WORD_1
	v_pk_fma_f32 v[74:75], v[74:75], v[126:127], v[134:135]
	v_cvt_f32_f16_e32 v132, v120
	v_cvt_f32_f16_sdwa v135, v121 dst_sel:DWORD dst_unused:UNUSED_PAD src0_sel:WORD_1
	v_cvt_f32_f16_e32 v134, v121
	v_cvt_f32_f16_sdwa v125, v119 dst_sel:DWORD dst_unused:UNUSED_PAD src0_sel:WORD_1
	v_cvt_f32_f16_sdwa v127, v116 dst_sel:DWORD dst_unused:UNUSED_PAD src0_sel:WORD_1
	v_cvt_pk_bf16_f32 v4, v4, v5
	v_cvt_pk_bf16_f32 v5, v74, v75
	v_mov_b32_e32 v74, v137
	v_mov_b32_e32 v75, v133
	v_cvt_f32_f16_e32 v122, v118
	v_cvt_f32_f16_e32 v124, v119
	v_cvt_f32_f16_e32 v126, v116
	global_store_dwordx2 v[130:131], v[4:5], off offset:3584
	v_mov_b32_e32 v4, v136
	v_mov_b32_e32 v5, v132
	v_pk_mul_f32 v[74:75], v[74:75], v[74:75]
	v_mov_b32_e32 v120, v139
	v_mov_b32_e32 v121, v135
	v_pk_fma_f32 v[4:5], v[4:5], v[4:5], v[74:75]
	v_mov_b32_e32 v74, v138
	v_mov_b32_e32 v75, v134
	v_pk_mul_f32 v[120:121], v[120:121], v[120:121]
	v_mov_b32_e32 v118, v123
	v_pk_fma_f32 v[74:75], v[74:75], v[74:75], v[120:121]
	v_mov_b32_e32 v119, v125
	v_mul_f32_e32 v116, v127, v127
	v_pk_add_f32 v[4:5], v[4:5], v[74:75]
	v_mov_b32_e32 v74, v122
	v_mov_b32_e32 v75, v124
	v_pk_mul_f32 v[118:119], v[118:119], v[118:119]
	v_pk_fma_f32 v[120:121], v[126:127], v[126:127], v[116:117] op_sel_hi:[1,1,0]
	v_mul_f32_e32 v116, v129, v129
	v_pk_fma_f32 v[74:75], v[74:75], v[74:75], v[118:119]
	v_pk_fma_f32 v[130:131], v[128:129], v[128:129], v[116:117] op_sel_hi:[1,1,0]
	s_waitcnt vmcnt(59)
	v_cvt_f32_f16_sdwa v117, v114 dst_sel:DWORD dst_unused:UNUSED_PAD src0_sel:WORD_1
	v_cvt_f32_f16_e32 v116, v114
	v_cvt_f32_f16_sdwa v119, v115 dst_sel:DWORD dst_unused:UNUSED_PAD src0_sel:WORD_1
	v_cvt_f32_f16_e32 v118, v115
	v_pk_add_f32 v[4:5], v[4:5], v[4:5] op_sel:[0,1] op_sel_hi:[1,0]
	v_pk_add_f32 v[74:75], v[74:75], v[74:75] op_sel:[0,1] op_sel_hi:[1,0]
	v_pk_mul_f32 v[114:115], v[116:117], v[116:117]
	v_pk_mul_f32 v[140:141], v[118:119], v[118:119]
	v_mov_b32_e32 v5, v114
	v_mov_b32_e32 v75, v115
	v_mov_b32_e32 v121, v140
	v_mov_b32_e32 v131, v141
	v_pk_add_f32 v[4:5], v[4:5], v[74:75]
	v_pk_add_f32 v[74:75], v[120:121], v[130:131]
	s_waitcnt vmcnt(58)
	v_cvt_f32_f16_sdwa v115, v112 dst_sel:DWORD dst_unused:UNUSED_PAD src0_sel:WORD_1
	v_cvt_f32_f16_sdwa v121, v113 dst_sel:DWORD dst_unused:UNUSED_PAD src0_sel:WORD_1
	v_cvt_f32_f16_e32 v114, v112
	v_cvt_f32_f16_e32 v120, v113
	v_pk_add_f32 v[4:5], v[4:5], v[74:75]
	v_mov_b32_e32 v74, v115
	v_mov_b32_e32 v75, v121
	v_pk_add_f32 v[130:131], v[4:5], v[4:5] op_sel:[0,1] op_sel_hi:[1,0]
	v_mov_b32_e32 v4, v114
	v_mov_b32_e32 v5, v120
	v_pk_mul_f32 v[74:75], v[74:75], v[74:75]
	s_waitcnt vmcnt(57)
	v_cvt_f32_f16_sdwa v113, v111 dst_sel:DWORD dst_unused:UNUSED_PAD src0_sel:WORD_1
	v_pk_fma_f32 v[4:5], v[4:5], v[4:5], v[74:75]
	v_cvt_f32_f16_e32 v112, v111
	v_pk_add_f32 v[140:141], v[4:5], v[4:5] op_sel:[0,1] op_sel_hi:[1,0]
	v_cvt_f32_f16_sdwa v5, v110 dst_sel:DWORD dst_unused:UNUSED_PAD src0_sel:WORD_1
	v_cvt_f32_f16_e32 v4, v110
	s_waitcnt vmcnt(56)
	v_cvt_f32_f16_sdwa v111, v109 dst_sel:DWORD dst_unused:UNUSED_PAD src0_sel:WORD_1
	v_cvt_f32_f16_e32 v110, v109
	v_mul_f32_e32 v74, v5, v5
	v_pk_fma_f32 v[144:145], v[4:5], v[4:5], v[74:75] op_sel_hi:[1,1,0]
	v_mul_f32_e32 v74, v113, v113
	v_pk_fma_f32 v[146:147], v[112:113], v[112:113], v[74:75] op_sel_hi:[1,1,0]
	v_cvt_f32_f16_sdwa v75, v108 dst_sel:DWORD dst_unused:UNUSED_PAD src0_sel:WORD_1
	v_cvt_f32_f16_e32 v74, v108
	v_pk_mul_f32 v[148:149], v[110:111], v[110:111]
	v_pk_mul_f32 v[108:109], v[74:75], v[74:75]
	s_nop 0
	v_mov_b32_e32 v131, v108
	v_mov_b32_e32 v141, v109
	v_mov_b32_e32 v145, v148
	v_mov_b32_e32 v147, v149
	v_pk_add_f32 v[108:109], v[130:131], v[140:141]
	v_pk_add_f32 v[130:131], v[144:145], v[146:147]
	s_nop 0
	v_pk_add_f32 v[108:109], v[108:109], v[130:131]
	s_nop 0
	v_add_f32_e32 v108, v108, v109
	s_nop 1
	v_add_f32_dpp v108, v108, v108 quad_perm:[1,0,3,2] row_mask:0xf bank_mask:0xf bound_ctrl:1
	s_nop 1
	v_add_f32_dpp v108, v108, v108 quad_perm:[2,3,0,1] row_mask:0xf bank_mask:0xf bound_ctrl:1
	s_nop 1
	v_add_f32_dpp v108, v108, v108 row_half_mirror row_mask:0xf bank_mask:0xf bound_ctrl:1
	s_nop 1
	v_add_f32_dpp v108, v108, v108 row_mirror row_mask:0xf bank_mask:0xf bound_ctrl:1
	s_nop 0
	v_readlane_b32 s5, v108, 16
	v_readlane_b32 s11, v108, 48
	v_readlane_b32 s6, v108, 0
	v_readlane_b32 s7, v108, 32
	v_mov_b32_e32 v108, s5
	v_mov_b32_e32 v109, s11
	v_pk_add_f32 v[108:109], s[6:7], v[108:109]
	s_lshl_b32 s5, s36, 1
	v_add_f32_e32 v108, v108, v109
	v_fmamk_f32 v108, v108, 0x3a000000, v252
	v_cmp_gt_f32_e32 vcc, s55, v108
	v_mul_f32_e32 v109, 0x4f800000, v108
	s_and_b32 s5, s5, 0xffffe000
	v_cndmask_b32_e32 v108, v108, v109, vcc
	v_sqrt_f32_e32 v109, v108
	s_add_i32 s5, s5, 0
	v_add_u32_e32 v130, -1, v109
	v_fma_f32 v131, -v130, v109, v108
	v_cmp_ge_f32_e64 s[6:7], 0, v131
	v_add_u32_e32 v131, 1, v109
	s_nop 0
	v_cndmask_b32_e64 v130, v109, v130, s[6:7]
	v_fma_f32 v109, -v131, v109, v108
	v_cmp_lt_f32_e64 s[6:7], 0, v109
	s_nop 1
	v_cndmask_b32_e64 v109, v130, v131, s[6:7]
	v_mul_f32_e32 v130, 0x37800000, v109
	v_cndmask_b32_e32 v109, v109, v130, vcc
	v_cmp_class_f32_e32 vcc, v108, v253
	s_nop 1
	v_cndmask_b32_e32 v108, v109, v108, vcc
	v_div_scale_f32 v109, s[6:7], v108, v108, 1.0
	v_rcp_f32_e32 v130, v109
	s_nop 0
	v_fma_f32 v131, -v109, v130, 1.0
	v_fmac_f32_e32 v130, v131, v130
	v_div_scale_f32 v131, vcc, 1.0, v108, 1.0
	v_mul_f32_e32 v140, v131, v130
	v_fma_f32 v141, -v109, v140, v131
	v_fmac_f32_e32 v140, v141, v130
	v_fma_f32 v109, -v109, v140, v131
	v_div_fmas_f32 v109, v109, v130, v140
	v_div_fixup_f32 v130, v109, v108, 1.0
	v_pk_mul_f32 v[140:141], v[136:137], v[130:131] op_sel_hi:[1,0]
	v_pk_mul_f32 v[148:149], v[138:139], v[130:131] op_sel_hi:[1,0]
	v_add_u32_e32 v131, s5, v0
	ds_read_b128 v[136:139], v131
	ds_read_b128 v[144:147], v131 offset:40960
	v_lshl_add_u64 v[108:109], s[40:41], 1, v[2:3]
	v_lshl_add_u64 v[108:109], v[108:109], 0, v[6:7]
	v_pk_mul_f32 v[4:5], v[4:5], v[130:131] op_sel_hi:[1,0]
	s_waitcnt lgkmcnt(0)
	v_pk_fma_f32 v[138:139], v[138:139], v[148:149], v[146:147]
	v_pk_fma_f32 v[136:137], v[136:137], v[140:141], v[144:145]
	v_pk_mul_f32 v[140:141], v[132:133], v[130:131] op_sel_hi:[1,0]
	v_cvt_pk_bf16_f32 v136, v136, v137
	v_cvt_pk_bf16_f32 v137, v138, v139
	global_store_dwordx2 v[108:109], v[136:137], off
	v_pk_mul_f32 v[144:145], v[134:135], v[130:131] op_sel_hi:[1,0]
	ds_read_b128 v[132:135], v131 offset:1024
	ds_read_b128 v[136:139], v131 offset:41984
	s_waitcnt lgkmcnt(0)
	v_pk_fma_f32 v[134:135], v[134:135], v[144:145], v[138:139]
	v_pk_fma_f32 v[132:133], v[132:133], v[140:141], v[136:137]
	v_pk_mul_f32 v[136:137], v[122:123], v[130:131] op_sel_hi:[1,0]
	v_cvt_pk_bf16_f32 v132, v132, v133
	v_cvt_pk_bf16_f32 v133, v134, v135
	global_store_dwordx2 v[108:109], v[132:133], off offset:512
	v_pk_mul_f32 v[138:139], v[124:125], v[130:131] op_sel_hi:[1,0]
	ds_read_b128 v[122:125], v131 offset:2048
	ds_read_b128 v[132:135], v131 offset:43008
	s_waitcnt lgkmcnt(0)
	v_pk_fma_f32 v[124:125], v[124:125], v[138:139], v[134:135]
	v_pk_fma_f32 v[122:123], v[122:123], v[136:137], v[132:133]
	v_pk_mul_f32 v[132:133], v[126:127], v[130:131] op_sel_hi:[1,0]
	v_cvt_pk_bf16_f32 v122, v122, v123
	v_cvt_pk_bf16_f32 v123, v124, v125
	global_store_dwordx2 v[108:109], v[122:123], off offset:1024
	v_pk_mul_f32 v[134:135], v[128:129], v[130:131] op_sel_hi:[1,0]
	ds_read_b128 v[122:125], v131 offset:3072
	ds_read_b128 v[126:129], v131 offset:44032
	s_waitcnt lgkmcnt(0)
	v_pk_fma_f32 v[124:125], v[134:135], v[124:125], v[128:129]
	v_pk_fma_f32 v[122:123], v[132:133], v[122:123], v[126:127]
	v_pk_mul_f32 v[126:127], v[116:117], v[130:131] op_sel_hi:[1,0]
	v_cvt_pk_bf16_f32 v122, v122, v123
	v_cvt_pk_bf16_f32 v123, v124, v125
	global_store_dwordx2 v[108:109], v[122:123], off offset:1536
	v_pk_mul_f32 v[128:129], v[118:119], v[130:131] op_sel_hi:[1,0]
	ds_read_b128 v[116:119], v131 offset:4096
	ds_read_b128 v[122:125], v131 offset:45056
	s_waitcnt lgkmcnt(0)
	v_pk_fma_f32 v[118:119], v[128:129], v[118:119], v[124:125]
	v_pk_fma_f32 v[116:117], v[126:127], v[116:117], v[122:123]
	v_pk_mul_f32 v[122:123], v[114:115], v[130:131] op_sel_hi:[1,0]
	v_cvt_pk_bf16_f32 v116, v116, v117
	v_cvt_pk_bf16_f32 v117, v118, v119
	global_store_dwordx2 v[108:109], v[116:117], off offset:2048
	v_pk_mul_f32 v[124:125], v[120:121], v[130:131] op_sel_hi:[1,0]
	ds_read_b128 v[114:117], v131 offset:5120
	ds_read_b128 v[118:121], v131 offset:46080
	s_waitcnt lgkmcnt(0)
	v_pk_fma_f32 v[116:117], v[124:125], v[116:117], v[120:121]
	v_pk_fma_f32 v[114:115], v[122:123], v[114:115], v[118:119]
	v_pk_mul_f32 v[120:121], v[112:113], v[130:131] op_sel_hi:[1,0]
	v_cvt_pk_bf16_f32 v114, v114, v115
	v_cvt_pk_bf16_f32 v115, v116, v117
	global_store_dwordx2 v[108:109], v[114:115], off offset:2560
	ds_read_b128 v[112:115], v131 offset:6144
	ds_read_b128 v[116:119], v131 offset:47104
	s_waitcnt vmcnt(61)
	v_cvt_f32_f16_sdwa v123, v107 dst_sel:DWORD dst_unused:UNUSED_PAD src0_sel:WORD_1
	v_cvt_f32_f16_e32 v122, v107
	s_waitcnt vmcnt(59)
	v_cvt_f32_f16_sdwa v107, v102 dst_sel:DWORD dst_unused:UNUSED_PAD src0_sel:WORD_1
	s_waitcnt lgkmcnt(0)
	v_pk_fma_f32 v[114:115], v[120:121], v[114:115], v[118:119]
	v_pk_fma_f32 v[4:5], v[4:5], v[112:113], v[116:117]
	v_cvt_f32_f16_sdwa v121, v106 dst_sel:DWORD dst_unused:UNUSED_PAD src0_sel:WORD_1
	v_cvt_pk_bf16_f32 v4, v4, v5
	v_cvt_pk_bf16_f32 v5, v114, v115
	global_store_dwordx2 v[108:109], v[4:5], off offset:3072
	v_pk_mul_f32 v[4:5], v[74:75], v[130:131] op_sel_hi:[1,0]
	v_pk_mul_f32 v[74:75], v[110:111], v[130:131] op_sel_hi:[1,0]
	ds_read_b128 v[110:113], v131 offset:7168
	ds_read_b128 v[114:117], v131 offset:48128
	v_cvt_f32_f16_e32 v120, v106
	v_cvt_f32_f16_sdwa v119, v105 dst_sel:DWORD dst_unused:UNUSED_PAD src0_sel:WORD_1
	v_cvt_f32_f16_e32 v118, v105
	v_cvt_f32_f16_e32 v106, v102
	s_waitcnt lgkmcnt(0)
	v_pk_fma_f32 v[74:75], v[74:75], v[112:113], v[116:117]
	v_cvt_f32_f16_sdwa v117, v104 dst_sel:DWORD dst_unused:UNUSED_PAD src0_sel:WORD_1
	v_pk_fma_f32 v[4:5], v[4:5], v[110:111], v[114:115]
	v_cvt_f32_f16_e32 v116, v104
	v_cvt_pk_bf16_f32 v4, v4, v5
	v_cvt_pk_bf16_f32 v5, v74, v75
	global_store_dwordx2 v[108:109], v[4:5], off offset:3584
	v_cvt_f32_f16_sdwa v109, v103 dst_sel:DWORD dst_unused:UNUSED_PAD src0_sel:WORD_1
	s_waitcnt vmcnt(60)
	v_cvt_f32_f16_sdwa v111, v100 dst_sel:DWORD dst_unused:UNUSED_PAD src0_sel:WORD_1
	v_mov_b32_e32 v74, v121
	v_mov_b32_e32 v75, v117
	v_cvt_f32_f16_e32 v108, v103
	v_cvt_f32_f16_e32 v110, v100
	v_cvt_f32_f16_sdwa v113, v101 dst_sel:DWORD dst_unused:UNUSED_PAD src0_sel:WORD_1
	v_mov_b32_e32 v4, v120
	v_mov_b32_e32 v5, v116
	v_pk_mul_f32 v[74:75], v[74:75], v[74:75]
	v_mov_b32_e32 v104, v123
	v_mov_b32_e32 v105, v119
	v_cvt_f32_f16_e32 v112, v101
	v_pk_fma_f32 v[4:5], v[4:5], v[4:5], v[74:75]
	v_mov_b32_e32 v74, v122
	v_mov_b32_e32 v75, v118
	v_pk_mul_f32 v[104:105], v[104:105], v[104:105]
	v_mov_b32_e32 v102, v107
	v_pk_fma_f32 v[74:75], v[74:75], v[74:75], v[104:105]
	v_mov_b32_e32 v103, v109
	v_mul_f32_e32 v100, v111, v111
	v_pk_add_f32 v[4:5], v[4:5], v[74:75]
	v_mov_b32_e32 v74, v106
	v_mov_b32_e32 v75, v108
	v_pk_mul_f32 v[102:103], v[102:103], v[102:103]
	v_pk_fma_f32 v[104:105], v[110:111], v[110:111], v[100:101] op_sel_hi:[1,1,0]
	v_mul_f32_e32 v100, v113, v113
	v_pk_fma_f32 v[74:75], v[74:75], v[74:75], v[102:103]
	v_pk_fma_f32 v[114:115], v[112:113], v[112:113], v[100:101] op_sel_hi:[1,1,0]
	s_waitcnt vmcnt(59)
	v_cvt_f32_f16_sdwa v101, v98 dst_sel:DWORD dst_unused:UNUSED_PAD src0_sel:WORD_1
	v_cvt_f32_f16_e32 v100, v98
	v_cvt_f32_f16_sdwa v103, v99 dst_sel:DWORD dst_unused:UNUSED_PAD src0_sel:WORD_1
	v_cvt_f32_f16_e32 v102, v99
	v_pk_add_f32 v[4:5], v[4:5], v[4:5] op_sel:[0,1] op_sel_hi:[1,0]
	v_pk_add_f32 v[74:75], v[74:75], v[74:75] op_sel:[0,1] op_sel_hi:[1,0]
	v_pk_mul_f32 v[98:99], v[100:101], v[100:101]
	v_pk_mul_f32 v[124:125], v[102:103], v[102:103]
	v_mov_b32_e32 v5, v98
	v_mov_b32_e32 v75, v99
	v_mov_b32_e32 v105, v124
	v_mov_b32_e32 v115, v125
	v_pk_add_f32 v[4:5], v[4:5], v[74:75]
	v_pk_add_f32 v[74:75], v[104:105], v[114:115]
	s_waitcnt vmcnt(58)
	v_cvt_f32_f16_sdwa v99, v96 dst_sel:DWORD dst_unused:UNUSED_PAD src0_sel:WORD_1
	v_cvt_f32_f16_sdwa v105, v97 dst_sel:DWORD dst_unused:UNUSED_PAD src0_sel:WORD_1
	v_cvt_f32_f16_e32 v98, v96
	v_cvt_f32_f16_e32 v104, v97
	v_pk_add_f32 v[4:5], v[4:5], v[74:75]
	v_mov_b32_e32 v74, v99
	v_mov_b32_e32 v75, v105
	v_pk_add_f32 v[114:115], v[4:5], v[4:5] op_sel:[0,1] op_sel_hi:[1,0]
	v_mov_b32_e32 v4, v98
	v_mov_b32_e32 v5, v104
	v_pk_mul_f32 v[74:75], v[74:75], v[74:75]
	s_waitcnt vmcnt(57)
	v_cvt_f32_f16_sdwa v97, v95 dst_sel:DWORD dst_unused:UNUSED_PAD src0_sel:WORD_1
	v_pk_fma_f32 v[4:5], v[4:5], v[4:5], v[74:75]
	v_cvt_f32_f16_e32 v96, v95
	v_pk_add_f32 v[124:125], v[4:5], v[4:5] op_sel:[0,1] op_sel_hi:[1,0]
	v_cvt_f32_f16_sdwa v5, v94 dst_sel:DWORD dst_unused:UNUSED_PAD src0_sel:WORD_1
	v_cvt_f32_f16_e32 v4, v94
	s_waitcnt vmcnt(56)
	v_cvt_f32_f16_sdwa v95, v93 dst_sel:DWORD dst_unused:UNUSED_PAD src0_sel:WORD_1
	v_cvt_f32_f16_e32 v94, v93
	v_mul_f32_e32 v74, v5, v5
	v_pk_fma_f32 v[126:127], v[4:5], v[4:5], v[74:75] op_sel_hi:[1,1,0]
	v_mul_f32_e32 v74, v97, v97
	v_pk_fma_f32 v[128:129], v[96:97], v[96:97], v[74:75] op_sel_hi:[1,1,0]
	v_cvt_f32_f16_sdwa v75, v92 dst_sel:DWORD dst_unused:UNUSED_PAD src0_sel:WORD_1
	v_cvt_f32_f16_e32 v74, v92
	v_pk_mul_f32 v[130:131], v[94:95], v[94:95]
	v_pk_mul_f32 v[92:93], v[74:75], v[74:75]
	s_nop 0
	v_mov_b32_e32 v115, v92
	v_mov_b32_e32 v125, v93
	v_mov_b32_e32 v127, v130
	v_mov_b32_e32 v129, v131
	v_pk_add_f32 v[92:93], v[114:115], v[124:125]
	v_pk_add_f32 v[114:115], v[126:127], v[128:129]
	s_nop 0
	v_pk_add_f32 v[92:93], v[92:93], v[114:115]
	s_nop 0
	v_add_f32_e32 v92, v92, v93
	s_nop 1
	v_add_f32_dpp v92, v92, v92 quad_perm:[1,0,3,2] row_mask:0xf bank_mask:0xf bound_ctrl:1
	s_nop 1
	v_add_f32_dpp v92, v92, v92 quad_perm:[2,3,0,1] row_mask:0xf bank_mask:0xf bound_ctrl:1
	s_nop 1
	v_add_f32_dpp v92, v92, v92 row_half_mirror row_mask:0xf bank_mask:0xf bound_ctrl:1
	s_nop 1
	v_add_f32_dpp v92, v92, v92 row_mirror row_mask:0xf bank_mask:0xf bound_ctrl:1
	s_nop 0
	v_readlane_b32 s5, v92, 16
	v_readlane_b32 s11, v92, 48
	v_readlane_b32 s6, v92, 0
	v_readlane_b32 s7, v92, 32
	v_mov_b32_e32 v92, s5
	v_mov_b32_e32 v93, s11
	v_pk_add_f32 v[92:93], s[6:7], v[92:93]
	s_lshl_b32 s5, s30, 1
	v_add_f32_e32 v92, v92, v93
	v_fmamk_f32 v92, v92, 0x3a000000, v252
	v_cmp_gt_f32_e32 vcc, s55, v92
	v_mul_f32_e32 v93, 0x4f800000, v92
	s_and_b32 s5, s5, 0xffffe000
	v_cndmask_b32_e32 v92, v92, v93, vcc
	v_sqrt_f32_e32 v93, v92
	s_add_i32 s5, s5, 0
	v_add_u32_e32 v114, -1, v93
	v_fma_f32 v115, -v114, v93, v92
	v_cmp_ge_f32_e64 s[6:7], 0, v115
	v_add_u32_e32 v115, 1, v93
	s_nop 0
	v_cndmask_b32_e64 v114, v93, v114, s[6:7]
	v_fma_f32 v93, -v115, v93, v92
	v_cmp_lt_f32_e64 s[6:7], 0, v93
	s_nop 1
	v_cndmask_b32_e64 v93, v114, v115, s[6:7]
	v_mul_f32_e32 v114, 0x37800000, v93
	v_cndmask_b32_e32 v93, v93, v114, vcc
	v_cmp_class_f32_e32 vcc, v92, v253
	s_nop 1
	v_cndmask_b32_e32 v92, v93, v92, vcc
	v_div_scale_f32 v93, s[6:7], v92, v92, 1.0
	v_rcp_f32_e32 v114, v93
	s_nop 0
	v_fma_f32 v115, -v93, v114, 1.0
	v_fmac_f32_e32 v114, v115, v114
	v_div_scale_f32 v115, vcc, 1.0, v92, 1.0
	v_mul_f32_e32 v124, v115, v114
	v_fma_f32 v125, -v93, v124, v115
	v_fmac_f32_e32 v124, v125, v114
	v_fma_f32 v93, -v93, v124, v115
	v_div_fmas_f32 v93, v93, v114, v124
	v_div_fixup_f32 v114, v93, v92, 1.0
	v_pk_mul_f32 v[128:129], v[120:121], v[114:115] op_sel_hi:[1,0]
	v_pk_mul_f32 v[130:131], v[122:123], v[114:115] op_sel_hi:[1,0]
	v_add_u32_e32 v115, s5, v0
	ds_read_b128 v[120:123], v115
	ds_read_b128 v[124:127], v115 offset:40960
	v_lshl_add_u64 v[92:93], s[34:35], 1, v[2:3]
	v_lshl_add_u64 v[92:93], v[92:93], 0, v[6:7]
	v_pk_mul_f32 v[4:5], v[4:5], v[114:115] op_sel_hi:[1,0]
	s_waitcnt lgkmcnt(0)
	v_pk_fma_f32 v[122:123], v[122:123], v[130:131], v[126:127]
	v_pk_fma_f32 v[120:121], v[120:121], v[128:129], v[124:125]
	v_pk_mul_f32 v[124:125], v[116:117], v[114:115] op_sel_hi:[1,0]
	v_cvt_pk_bf16_f32 v120, v120, v121
	v_cvt_pk_bf16_f32 v121, v122, v123
	global_store_dwordx2 v[92:93], v[120:121], off
	v_pk_mul_f32 v[126:127], v[118:119], v[114:115] op_sel_hi:[1,0]
	ds_read_b128 v[116:119], v115 offset:1024
	ds_read_b128 v[120:123], v115 offset:41984
	s_waitcnt lgkmcnt(0)
	v_pk_fma_f32 v[118:119], v[118:119], v[126:127], v[122:123]
	v_pk_fma_f32 v[116:117], v[116:117], v[124:125], v[120:121]
	v_pk_mul_f32 v[120:121], v[106:107], v[114:115] op_sel_hi:[1,0]
	v_cvt_pk_bf16_f32 v116, v116, v117
	v_cvt_pk_bf16_f32 v117, v118, v119
	global_store_dwordx2 v[92:93], v[116:117], off offset:512
	v_pk_mul_f32 v[122:123], v[108:109], v[114:115] op_sel_hi:[1,0]
	ds_read_b128 v[106:109], v115 offset:2048
	ds_read_b128 v[116:119], v115 offset:43008
	s_waitcnt lgkmcnt(0)
	v_pk_fma_f32 v[108:109], v[108:109], v[122:123], v[118:119]
	v_pk_fma_f32 v[106:107], v[106:107], v[120:121], v[116:117]
	v_pk_mul_f32 v[116:117], v[110:111], v[114:115] op_sel_hi:[1,0]
	v_cvt_pk_bf16_f32 v106, v106, v107
	v_cvt_pk_bf16_f32 v107, v108, v109
	global_store_dwordx2 v[92:93], v[106:107], off offset:1024
	v_pk_mul_f32 v[118:119], v[112:113], v[114:115] op_sel_hi:[1,0]
	ds_read_b128 v[106:109], v115 offset:3072
	ds_read_b128 v[110:113], v115 offset:44032
	s_waitcnt lgkmcnt(0)
	v_pk_fma_f32 v[108:109], v[118:119], v[108:109], v[112:113]
	v_pk_fma_f32 v[106:107], v[116:117], v[106:107], v[110:111]
	v_pk_mul_f32 v[110:111], v[100:101], v[114:115] op_sel_hi:[1,0]
	v_cvt_pk_bf16_f32 v106, v106, v107
	v_cvt_pk_bf16_f32 v107, v108, v109
	global_store_dwordx2 v[92:93], v[106:107], off offset:1536
	v_pk_mul_f32 v[112:113], v[102:103], v[114:115] op_sel_hi:[1,0]
	ds_read_b128 v[100:103], v115 offset:4096
	ds_read_b128 v[106:109], v115 offset:45056
	s_waitcnt lgkmcnt(0)
	v_pk_fma_f32 v[102:103], v[112:113], v[102:103], v[108:109]
	v_pk_fma_f32 v[100:101], v[110:111], v[100:101], v[106:107]
	v_pk_mul_f32 v[106:107], v[98:99], v[114:115] op_sel_hi:[1,0]
	v_cvt_pk_bf16_f32 v100, v100, v101
	v_cvt_pk_bf16_f32 v101, v102, v103
	global_store_dwordx2 v[92:93], v[100:101], off offset:2048
	v_pk_mul_f32 v[108:109], v[104:105], v[114:115] op_sel_hi:[1,0]
	ds_read_b128 v[98:101], v115 offset:5120
	ds_read_b128 v[102:105], v115 offset:46080
	s_waitcnt lgkmcnt(0)
	v_pk_fma_f32 v[100:101], v[108:109], v[100:101], v[104:105]
	v_pk_fma_f32 v[98:99], v[106:107], v[98:99], v[102:103]
	v_pk_mul_f32 v[104:105], v[96:97], v[114:115] op_sel_hi:[1,0]
	v_cvt_pk_bf16_f32 v98, v98, v99
	v_cvt_pk_bf16_f32 v99, v100, v101
	global_store_dwordx2 v[92:93], v[98:99], off offset:2560
	ds_read_b128 v[96:99], v115 offset:6144
	ds_read_b128 v[100:103], v115 offset:47104
	s_waitcnt vmcnt(61)
	v_cvt_f32_f16_sdwa v107, v91 dst_sel:DWORD dst_unused:UNUSED_PAD src0_sel:WORD_1
	v_cvt_f32_f16_e32 v106, v91
	s_waitcnt vmcnt(59)
	v_cvt_f32_f16_sdwa v91, v86 dst_sel:DWORD dst_unused:UNUSED_PAD src0_sel:WORD_1
	s_waitcnt lgkmcnt(0)
	v_pk_fma_f32 v[98:99], v[104:105], v[98:99], v[102:103]
	v_pk_fma_f32 v[4:5], v[4:5], v[96:97], v[100:101]
	v_cvt_f32_f16_sdwa v105, v90 dst_sel:DWORD dst_unused:UNUSED_PAD src0_sel:WORD_1
	v_cvt_pk_bf16_f32 v4, v4, v5
	v_cvt_pk_bf16_f32 v5, v98, v99
	global_store_dwordx2 v[92:93], v[4:5], off offset:3072
	v_pk_mul_f32 v[4:5], v[74:75], v[114:115] op_sel_hi:[1,0]
	v_pk_mul_f32 v[74:75], v[94:95], v[114:115] op_sel_hi:[1,0]
	ds_read_b128 v[94:97], v115 offset:7168
	ds_read_b128 v[98:101], v115 offset:48128
	v_cvt_f32_f16_e32 v104, v90
	v_cvt_f32_f16_sdwa v103, v89 dst_sel:DWORD dst_unused:UNUSED_PAD src0_sel:WORD_1
	v_cvt_f32_f16_e32 v102, v89
	v_cvt_f32_f16_e32 v90, v86
	s_waitcnt lgkmcnt(0)
	v_pk_fma_f32 v[74:75], v[74:75], v[96:97], v[100:101]
	v_cvt_f32_f16_sdwa v101, v88 dst_sel:DWORD dst_unused:UNUSED_PAD src0_sel:WORD_1
	v_pk_fma_f32 v[4:5], v[4:5], v[94:95], v[98:99]
	v_cvt_f32_f16_e32 v100, v88
	v_cvt_pk_bf16_f32 v4, v4, v5
	v_cvt_pk_bf16_f32 v5, v74, v75
	global_store_dwordx2 v[92:93], v[4:5], off offset:3584
	v_cvt_f32_f16_sdwa v93, v87 dst_sel:DWORD dst_unused:UNUSED_PAD src0_sel:WORD_1
	s_waitcnt vmcnt(60)
	v_cvt_f32_f16_sdwa v95, v84 dst_sel:DWORD dst_unused:UNUSED_PAD src0_sel:WORD_1
	v_mov_b32_e32 v74, v105
	v_mov_b32_e32 v75, v101
	v_cvt_f32_f16_e32 v92, v87
	v_cvt_f32_f16_e32 v94, v84
	v_cvt_f32_f16_sdwa v97, v85 dst_sel:DWORD dst_unused:UNUSED_PAD src0_sel:WORD_1
	v_mov_b32_e32 v4, v104
	v_mov_b32_e32 v5, v100
	v_pk_mul_f32 v[74:75], v[74:75], v[74:75]
	v_mov_b32_e32 v88, v107
	v_mov_b32_e32 v89, v103
	v_cvt_f32_f16_e32 v96, v85
	v_pk_fma_f32 v[4:5], v[4:5], v[4:5], v[74:75]
	v_mov_b32_e32 v74, v106
	v_mov_b32_e32 v75, v102
	v_pk_mul_f32 v[88:89], v[88:89], v[88:89]
	v_mov_b32_e32 v86, v91
	v_pk_fma_f32 v[74:75], v[74:75], v[74:75], v[88:89]
	v_mov_b32_e32 v87, v93
	v_mul_f32_e32 v84, v95, v95
	v_pk_add_f32 v[4:5], v[4:5], v[74:75]
	v_mov_b32_e32 v74, v90
	v_mov_b32_e32 v75, v92
	v_pk_mul_f32 v[86:87], v[86:87], v[86:87]
	v_pk_fma_f32 v[88:89], v[94:95], v[94:95], v[84:85] op_sel_hi:[1,1,0]
	v_mul_f32_e32 v84, v97, v97
	v_pk_fma_f32 v[74:75], v[74:75], v[74:75], v[86:87]
	v_pk_fma_f32 v[98:99], v[96:97], v[96:97], v[84:85] op_sel_hi:[1,1,0]
	s_waitcnt vmcnt(59)
	v_cvt_f32_f16_sdwa v85, v82 dst_sel:DWORD dst_unused:UNUSED_PAD src0_sel:WORD_1
	v_cvt_f32_f16_e32 v84, v82
	v_cvt_f32_f16_sdwa v87, v83 dst_sel:DWORD dst_unused:UNUSED_PAD src0_sel:WORD_1
	v_cvt_f32_f16_e32 v86, v83
	v_pk_add_f32 v[4:5], v[4:5], v[4:5] op_sel:[0,1] op_sel_hi:[1,0]
	v_pk_add_f32 v[74:75], v[74:75], v[74:75] op_sel:[0,1] op_sel_hi:[1,0]
	v_pk_mul_f32 v[82:83], v[84:85], v[84:85]
	v_pk_mul_f32 v[108:109], v[86:87], v[86:87]
	v_mov_b32_e32 v5, v82
	v_mov_b32_e32 v75, v83
	v_mov_b32_e32 v89, v108
	v_mov_b32_e32 v99, v109
	v_pk_add_f32 v[4:5], v[4:5], v[74:75]
	v_pk_add_f32 v[74:75], v[88:89], v[98:99]
	s_waitcnt vmcnt(58)
	v_cvt_f32_f16_sdwa v83, v80 dst_sel:DWORD dst_unused:UNUSED_PAD src0_sel:WORD_1
	v_cvt_f32_f16_sdwa v89, v81 dst_sel:DWORD dst_unused:UNUSED_PAD src0_sel:WORD_1
	v_cvt_f32_f16_e32 v82, v80
	v_cvt_f32_f16_e32 v88, v81
	v_pk_add_f32 v[4:5], v[4:5], v[74:75]
	v_mov_b32_e32 v74, v83
	v_mov_b32_e32 v75, v89
	v_pk_add_f32 v[98:99], v[4:5], v[4:5] op_sel:[0,1] op_sel_hi:[1,0]
	v_mov_b32_e32 v4, v82
	v_mov_b32_e32 v5, v88
	v_pk_mul_f32 v[74:75], v[74:75], v[74:75]
	s_waitcnt vmcnt(57)
	v_cvt_f32_f16_sdwa v81, v79 dst_sel:DWORD dst_unused:UNUSED_PAD src0_sel:WORD_1
	v_pk_fma_f32 v[4:5], v[4:5], v[4:5], v[74:75]
	v_cvt_f32_f16_e32 v80, v79
	v_pk_add_f32 v[108:109], v[4:5], v[4:5] op_sel:[0,1] op_sel_hi:[1,0]
	v_cvt_f32_f16_sdwa v5, v78 dst_sel:DWORD dst_unused:UNUSED_PAD src0_sel:WORD_1
	v_cvt_f32_f16_e32 v4, v78
	s_waitcnt vmcnt(56)
	v_cvt_f32_f16_sdwa v79, v77 dst_sel:DWORD dst_unused:UNUSED_PAD src0_sel:WORD_1
	v_cvt_f32_f16_e32 v78, v77
	v_mul_f32_e32 v74, v5, v5
	v_pk_fma_f32 v[110:111], v[4:5], v[4:5], v[74:75] op_sel_hi:[1,1,0]
	v_mul_f32_e32 v74, v81, v81
	v_pk_fma_f32 v[112:113], v[80:81], v[80:81], v[74:75] op_sel_hi:[1,1,0]
	v_cvt_f32_f16_sdwa v75, v76 dst_sel:DWORD dst_unused:UNUSED_PAD src0_sel:WORD_1
	v_cvt_f32_f16_e32 v74, v76
	v_pk_mul_f32 v[114:115], v[78:79], v[78:79]
	v_pk_mul_f32 v[76:77], v[74:75], v[74:75]
	s_nop 0
	v_mov_b32_e32 v99, v76
	v_mov_b32_e32 v109, v77
	v_mov_b32_e32 v111, v114
	v_mov_b32_e32 v113, v115
	v_pk_add_f32 v[76:77], v[98:99], v[108:109]
	v_pk_add_f32 v[98:99], v[110:111], v[112:113]
	s_nop 0
	v_pk_add_f32 v[76:77], v[76:77], v[98:99]
	s_nop 0
	v_add_f32_e32 v76, v76, v77
	s_nop 1
	v_add_f32_dpp v76, v76, v76 quad_perm:[1,0,3,2] row_mask:0xf bank_mask:0xf bound_ctrl:1
	s_nop 1
	v_add_f32_dpp v76, v76, v76 quad_perm:[2,3,0,1] row_mask:0xf bank_mask:0xf bound_ctrl:1
	s_nop 1
	v_add_f32_dpp v76, v76, v76 row_half_mirror row_mask:0xf bank_mask:0xf bound_ctrl:1
	s_nop 1
	v_add_f32_dpp v76, v76, v76 row_mirror row_mask:0xf bank_mask:0xf bound_ctrl:1
	s_nop 0
	v_readlane_b32 s5, v76, 16
	v_readlane_b32 s11, v76, 48
	v_readlane_b32 s6, v76, 0
	v_readlane_b32 s7, v76, 32
	v_mov_b32_e32 v76, s5
	v_mov_b32_e32 v77, s11
	v_pk_add_f32 v[76:77], s[6:7], v[76:77]
	s_lshl_b32 s5, s26, 1
	v_add_f32_e32 v76, v76, v77
	v_fmamk_f32 v76, v76, 0x3a000000, v252
	v_cmp_gt_f32_e32 vcc, s55, v76
	v_mul_f32_e32 v77, 0x4f800000, v76
	s_and_b32 s5, s5, 0xffffe000
	v_cndmask_b32_e32 v76, v76, v77, vcc
	v_sqrt_f32_e32 v77, v76
	s_add_i32 s5, s5, 0
	v_add_u32_e32 v98, -1, v77
	v_fma_f32 v99, -v98, v77, v76
	v_cmp_ge_f32_e64 s[6:7], 0, v99
	v_add_u32_e32 v99, 1, v77
	s_nop 0
	v_cndmask_b32_e64 v98, v77, v98, s[6:7]
	v_fma_f32 v77, -v99, v77, v76
	v_cmp_lt_f32_e64 s[6:7], 0, v77
	s_nop 1
	v_cndmask_b32_e64 v77, v98, v99, s[6:7]
	v_mul_f32_e32 v98, 0x37800000, v77
	v_cndmask_b32_e32 v77, v77, v98, vcc
	v_cmp_class_f32_e32 vcc, v76, v253
	s_nop 1
	v_cndmask_b32_e32 v76, v77, v76, vcc
	v_div_scale_f32 v77, s[6:7], v76, v76, 1.0
	v_rcp_f32_e32 v98, v77
	s_nop 0
	v_fma_f32 v99, -v77, v98, 1.0
	v_fmac_f32_e32 v98, v99, v98
	v_div_scale_f32 v99, vcc, 1.0, v76, 1.0
	v_mul_f32_e32 v108, v99, v98
	v_fma_f32 v109, -v77, v108, v99
	v_fmac_f32_e32 v108, v109, v98
	v_fma_f32 v77, -v77, v108, v99
	v_div_fmas_f32 v77, v77, v98, v108
	v_div_fixup_f32 v98, v77, v76, 1.0
	v_pk_mul_f32 v[112:113], v[104:105], v[98:99] op_sel_hi:[1,0]
	v_pk_mul_f32 v[114:115], v[106:107], v[98:99] op_sel_hi:[1,0]
	v_add_u32_e32 v99, s5, v0
	ds_read_b128 v[104:107], v99
	ds_read_b128 v[108:111], v99 offset:40960
	v_lshl_add_u64 v[76:77], s[28:29], 1, v[2:3]
	v_lshl_add_u64 v[76:77], v[76:77], 0, v[6:7]
	v_pk_mul_f32 v[4:5], v[4:5], v[98:99] op_sel_hi:[1,0]
	s_waitcnt lgkmcnt(0)
	v_pk_fma_f32 v[106:107], v[106:107], v[114:115], v[110:111]
	v_pk_fma_f32 v[104:105], v[104:105], v[112:113], v[108:109]
	v_pk_mul_f32 v[108:109], v[100:101], v[98:99] op_sel_hi:[1,0]
	v_cvt_pk_bf16_f32 v104, v104, v105
	v_cvt_pk_bf16_f32 v105, v106, v107
	global_store_dwordx2 v[76:77], v[104:105], off
	v_pk_mul_f32 v[110:111], v[102:103], v[98:99] op_sel_hi:[1,0]
	ds_read_b128 v[100:103], v99 offset:1024
	ds_read_b128 v[104:107], v99 offset:41984
	s_waitcnt lgkmcnt(0)
	v_pk_fma_f32 v[102:103], v[102:103], v[110:111], v[106:107]
	v_pk_fma_f32 v[100:101], v[100:101], v[108:109], v[104:105]
	v_pk_mul_f32 v[104:105], v[90:91], v[98:99] op_sel_hi:[1,0]
	v_cvt_pk_bf16_f32 v100, v100, v101
	v_cvt_pk_bf16_f32 v101, v102, v103
	global_store_dwordx2 v[76:77], v[100:101], off offset:512
	v_pk_mul_f32 v[106:107], v[92:93], v[98:99] op_sel_hi:[1,0]
	ds_read_b128 v[90:93], v99 offset:2048
	ds_read_b128 v[100:103], v99 offset:43008
	s_waitcnt lgkmcnt(0)
	v_pk_fma_f32 v[92:93], v[92:93], v[106:107], v[102:103]
	v_pk_fma_f32 v[90:91], v[90:91], v[104:105], v[100:101]
	v_pk_mul_f32 v[100:101], v[94:95], v[98:99] op_sel_hi:[1,0]
	v_cvt_pk_bf16_f32 v90, v90, v91
	v_cvt_pk_bf16_f32 v91, v92, v93
	global_store_dwordx2 v[76:77], v[90:91], off offset:1024
	v_pk_mul_f32 v[102:103], v[96:97], v[98:99] op_sel_hi:[1,0]
	ds_read_b128 v[90:93], v99 offset:3072
	ds_read_b128 v[94:97], v99 offset:44032
	s_waitcnt lgkmcnt(0)
	v_pk_fma_f32 v[92:93], v[102:103], v[92:93], v[96:97]
	v_pk_fma_f32 v[90:91], v[100:101], v[90:91], v[94:95]
	v_pk_mul_f32 v[94:95], v[84:85], v[98:99] op_sel_hi:[1,0]
	v_cvt_pk_bf16_f32 v90, v90, v91
	v_cvt_pk_bf16_f32 v91, v92, v93
	global_store_dwordx2 v[76:77], v[90:91], off offset:1536
	v_pk_mul_f32 v[96:97], v[86:87], v[98:99] op_sel_hi:[1,0]
	ds_read_b128 v[84:87], v99 offset:4096
	ds_read_b128 v[90:93], v99 offset:45056
	s_waitcnt lgkmcnt(0)
	v_pk_fma_f32 v[86:87], v[96:97], v[86:87], v[92:93]
	v_pk_fma_f32 v[84:85], v[94:95], v[84:85], v[90:91]
	v_pk_mul_f32 v[90:91], v[82:83], v[98:99] op_sel_hi:[1,0]
	v_cvt_pk_bf16_f32 v84, v84, v85
	v_cvt_pk_bf16_f32 v85, v86, v87
	global_store_dwordx2 v[76:77], v[84:85], off offset:2048
	v_pk_mul_f32 v[92:93], v[88:89], v[98:99] op_sel_hi:[1,0]
	ds_read_b128 v[82:85], v99 offset:5120
	ds_read_b128 v[86:89], v99 offset:46080
	s_waitcnt lgkmcnt(0)
	v_pk_fma_f32 v[84:85], v[92:93], v[84:85], v[88:89]
	v_pk_fma_f32 v[82:83], v[90:91], v[82:83], v[86:87]
	v_pk_mul_f32 v[88:89], v[80:81], v[98:99] op_sel_hi:[1,0]
	v_cvt_pk_bf16_f32 v82, v82, v83
	v_cvt_pk_bf16_f32 v83, v84, v85
	global_store_dwordx2 v[76:77], v[82:83], off offset:2560
	ds_read_b128 v[80:83], v99 offset:6144
	ds_read_b128 v[84:87], v99 offset:47104
	s_waitcnt vmcnt(61)
	v_cvt_f32_f16_sdwa v91, v73 dst_sel:DWORD dst_unused:UNUSED_PAD src0_sel:WORD_1
	v_cvt_f32_f16_e32 v90, v73
	s_waitcnt lgkmcnt(0)
	v_pk_fma_f32 v[82:83], v[88:89], v[82:83], v[86:87]
	v_pk_fma_f32 v[4:5], v[4:5], v[80:81], v[84:85]
	v_cvt_f32_f16_sdwa v89, v72 dst_sel:DWORD dst_unused:UNUSED_PAD src0_sel:WORD_1
	v_cvt_pk_bf16_f32 v4, v4, v5
	v_cvt_pk_bf16_f32 v5, v82, v83
	global_store_dwordx2 v[76:77], v[4:5], off offset:3072
	v_pk_mul_f32 v[4:5], v[74:75], v[98:99] op_sel_hi:[1,0]
	v_pk_mul_f32 v[74:75], v[78:79], v[98:99] op_sel_hi:[1,0]
	ds_read_b128 v[78:81], v99 offset:7168
	ds_read_b128 v[82:85], v99 offset:48128
	v_cvt_f32_f16_e32 v88, v72
	s_waitcnt vmcnt(61)
	v_cvt_f32_f16_sdwa v87, v71 dst_sel:DWORD dst_unused:UNUSED_PAD src0_sel:WORD_1
	v_cvt_f32_f16_e32 v86, v71
	v_mov_b32_e32 v72, v91
	s_waitcnt lgkmcnt(0)
	v_pk_fma_f32 v[74:75], v[74:75], v[80:81], v[84:85]
	v_cvt_f32_f16_sdwa v85, v70 dst_sel:DWORD dst_unused:UNUSED_PAD src0_sel:WORD_1
	v_cvt_f32_f16_e32 v84, v70
	v_pk_fma_f32 v[4:5], v[4:5], v[78:79], v[82:83]
	v_mov_b32_e32 v70, v89
	v_cvt_pk_bf16_f32 v4, v4, v5
	v_cvt_pk_bf16_f32 v5, v74, v75
	global_store_dwordx2 v[76:77], v[4:5], off offset:3584
	v_mov_b32_e32 v71, v85
	s_waitcnt vmcnt(61)
	v_cvt_f32_f16_sdwa v75, v68 dst_sel:DWORD dst_unused:UNUSED_PAD src0_sel:WORD_1
	v_cvt_f32_f16_sdwa v77, v69 dst_sel:DWORD dst_unused:UNUSED_PAD src0_sel:WORD_1
	v_mov_b32_e32 v4, v88
	v_mov_b32_e32 v5, v84
	v_pk_mul_f32 v[70:71], v[70:71], v[70:71]
	v_mov_b32_e32 v73, v87
	v_cvt_f32_f16_e32 v74, v68
	v_cvt_f32_f16_e32 v76, v69
	s_waitcnt vmcnt(60)
	v_cvt_f32_f16_sdwa v79, v66 dst_sel:DWORD dst_unused:UNUSED_PAD src0_sel:WORD_1
	v_pk_fma_f32 v[4:5], v[4:5], v[4:5], v[70:71]
	v_mov_b32_e32 v70, v90
	v_mov_b32_e32 v71, v86
	v_pk_mul_f32 v[72:73], v[72:73], v[72:73]
	v_cvt_f32_f16_e32 v78, v66
	v_cvt_f32_f16_sdwa v81, v67 dst_sel:DWORD dst_unused:UNUSED_PAD src0_sel:WORD_1
	v_pk_fma_f32 v[70:71], v[70:71], v[70:71], v[72:73]
	v_cvt_f32_f16_e32 v80, v67
	v_pk_add_f32 v[4:5], v[4:5], v[70:71]
	v_mov_b32_e32 v70, v75
	v_mov_b32_e32 v71, v77
	v_mov_b32_e32 v68, v74
	v_mov_b32_e32 v69, v76
	v_pk_mul_f32 v[70:71], v[70:71], v[70:71]
	v_mul_f32_e32 v66, v79, v79
	v_pk_fma_f32 v[68:69], v[68:69], v[68:69], v[70:71]
	v_pk_fma_f32 v[72:73], v[78:79], v[78:79], v[66:67] op_sel_hi:[1,1,0]
	v_mul_f32_e32 v66, v81, v81
	v_pk_add_f32 v[70:71], v[68:69], v[68:69] op_sel:[0,1] op_sel_hi:[1,0]
	v_pk_fma_f32 v[82:83], v[80:81], v[80:81], v[66:67] op_sel_hi:[1,1,0]
	s_waitcnt vmcnt(59)
	v_cvt_f32_f16_sdwa v67, v64 dst_sel:DWORD dst_unused:UNUSED_PAD src0_sel:WORD_1
	v_cvt_f32_f16_e32 v66, v64
	v_cvt_f32_f16_sdwa v69, v65 dst_sel:DWORD dst_unused:UNUSED_PAD src0_sel:WORD_1
	v_cvt_f32_f16_e32 v68, v65
	v_pk_add_f32 v[4:5], v[4:5], v[4:5] op_sel:[0,1] op_sel_hi:[1,0]
	v_pk_mul_f32 v[64:65], v[66:67], v[66:67]
	v_pk_mul_f32 v[92:93], v[68:69], v[68:69]
	v_mov_b32_e32 v5, v64
	v_mov_b32_e32 v71, v65
	v_mov_b32_e32 v73, v92
	v_mov_b32_e32 v83, v93
	v_pk_add_f32 v[4:5], v[4:5], v[70:71]
	v_pk_add_f32 v[64:65], v[72:73], v[82:83]
	s_waitcnt vmcnt(58)
	v_cvt_f32_f16_sdwa v71, v62 dst_sel:DWORD dst_unused:UNUSED_PAD src0_sel:WORD_1
	v_cvt_f32_f16_sdwa v73, v63 dst_sel:DWORD dst_unused:UNUSED_PAD src0_sel:WORD_1
	v_cvt_f32_f16_e32 v70, v62
	v_cvt_f32_f16_e32 v72, v63
	v_pk_add_f32 v[4:5], v[4:5], v[64:65]
	v_mov_b32_e32 v62, v71
	v_mov_b32_e32 v63, v73
	v_pk_add_f32 v[82:83], v[4:5], v[4:5] op_sel:[0,1] op_sel_hi:[1,0]
	v_mov_b32_e32 v4, v70
	v_mov_b32_e32 v5, v72
	v_pk_mul_f32 v[62:63], v[62:63], v[62:63]
	s_waitcnt vmcnt(56)
	v_cvt_f32_f16_sdwa v65, v59 dst_sel:DWORD dst_unused:UNUSED_PAD src0_sel:WORD_1
	v_pk_fma_f32 v[4:5], v[4:5], v[4:5], v[62:63]
	v_cvt_f32_f16_sdwa v63, v61 dst_sel:DWORD dst_unused:UNUSED_PAD src0_sel:WORD_1
	v_pk_add_f32 v[92:93], v[4:5], v[4:5] op_sel:[0,1] op_sel_hi:[1,0]
	v_cvt_f32_f16_sdwa v5, v60 dst_sel:DWORD dst_unused:UNUSED_PAD src0_sel:WORD_1
	v_cvt_f32_f16_e32 v4, v60
	v_cvt_f32_f16_e32 v62, v61
	v_cvt_f32_f16_e32 v64, v59
	v_mul_f32_e32 v60, v5, v5
	v_pk_fma_f32 v[94:95], v[4:5], v[4:5], v[60:61] op_sel_hi:[1,1,0]
	v_mul_f32_e32 v60, v63, v63
	v_pk_fma_f32 v[96:97], v[62:63], v[62:63], v[60:61] op_sel_hi:[1,1,0]
	v_cvt_f32_f16_sdwa v61, v58 dst_sel:DWORD dst_unused:UNUSED_PAD src0_sel:WORD_1
	v_cvt_f32_f16_e32 v60, v58
	v_pk_mul_f32 v[98:99], v[64:65], v[64:65]
	v_pk_mul_f32 v[58:59], v[60:61], v[60:61]
	s_nop 0
	v_mov_b32_e32 v83, v58
	v_mov_b32_e32 v93, v59
	v_mov_b32_e32 v95, v98
	v_mov_b32_e32 v97, v99
	v_pk_add_f32 v[58:59], v[82:83], v[92:93]
	v_pk_add_f32 v[82:83], v[94:95], v[96:97]
	s_nop 0
	v_pk_add_f32 v[58:59], v[58:59], v[82:83]
	s_nop 0
	v_add_f32_e32 v58, v58, v59
	s_nop 1
	v_add_f32_dpp v58, v58, v58 quad_perm:[1,0,3,2] row_mask:0xf bank_mask:0xf bound_ctrl:1
	s_nop 1
	v_add_f32_dpp v58, v58, v58 quad_perm:[2,3,0,1] row_mask:0xf bank_mask:0xf bound_ctrl:1
	s_nop 1
	v_add_f32_dpp v58, v58, v58 row_half_mirror row_mask:0xf bank_mask:0xf bound_ctrl:1
	s_nop 1
	v_add_f32_dpp v58, v58, v58 row_mirror row_mask:0xf bank_mask:0xf bound_ctrl:1
	s_nop 0
	v_readlane_b32 s5, v58, 16
	v_readlane_b32 s11, v58, 48
	v_readlane_b32 s6, v58, 0
	v_readlane_b32 s7, v58, 32
	v_mov_b32_e32 v58, s5
	v_mov_b32_e32 v59, s11
	v_pk_add_f32 v[58:59], s[6:7], v[58:59]
	s_lshl_b32 s5, s22, 1
	v_add_f32_e32 v58, v58, v59
	v_fmamk_f32 v58, v58, 0x3a000000, v252
	v_cmp_gt_f32_e32 vcc, s55, v58
	v_mul_f32_e32 v59, 0x4f800000, v58
	s_and_b32 s5, s5, 0xffffe000
	v_cndmask_b32_e32 v58, v58, v59, vcc
	v_sqrt_f32_e32 v59, v58
	s_add_i32 s5, s5, 0
	v_add_u32_e32 v82, -1, v59
	v_fma_f32 v83, -v82, v59, v58
	v_cmp_ge_f32_e64 s[6:7], 0, v83
	v_add_u32_e32 v83, 1, v59
	s_nop 0
	v_cndmask_b32_e64 v82, v59, v82, s[6:7]
	v_fma_f32 v59, -v83, v59, v58
	v_cmp_lt_f32_e64 s[6:7], 0, v59
	s_nop 1
	v_cndmask_b32_e64 v59, v82, v83, s[6:7]
	v_mul_f32_e32 v82, 0x37800000, v59
	v_cndmask_b32_e32 v59, v59, v82, vcc
	v_cmp_class_f32_e32 vcc, v58, v253
	s_nop 1
	v_cndmask_b32_e32 v58, v59, v58, vcc
	v_div_scale_f32 v59, s[6:7], v58, v58, 1.0
	v_rcp_f32_e32 v82, v59
	s_nop 0
	v_fma_f32 v83, -v59, v82, 1.0
	v_fmac_f32_e32 v82, v83, v82
	v_div_scale_f32 v83, vcc, 1.0, v58, 1.0
	v_mul_f32_e32 v92, v83, v82
	v_fma_f32 v93, -v59, v92, v83
	v_fmac_f32_e32 v92, v93, v82
	v_fma_f32 v59, -v59, v92, v83
	v_div_fmas_f32 v59, v59, v82, v92
	v_div_fixup_f32 v82, v59, v58, 1.0
	v_pk_mul_f32 v[96:97], v[88:89], v[82:83] op_sel_hi:[1,0]
	v_pk_mul_f32 v[98:99], v[90:91], v[82:83] op_sel_hi:[1,0]
	v_add_u32_e32 v83, s5, v0
	ds_read_b128 v[88:91], v83
	ds_read_b128 v[92:95], v83 offset:40960
	v_lshl_add_u64 v[58:59], s[24:25], 1, v[2:3]
	v_lshl_add_u64 v[58:59], v[58:59], 0, v[6:7]
	v_pk_mul_f32 v[4:5], v[4:5], v[82:83] op_sel_hi:[1,0]
	v_pk_mul_f32 v[62:63], v[62:63], v[82:83] op_sel_hi:[1,0]
	s_waitcnt lgkmcnt(0)
	v_pk_fma_f32 v[90:91], v[90:91], v[98:99], v[94:95]
	v_pk_fma_f32 v[88:89], v[88:89], v[96:97], v[92:93]
	v_pk_mul_f32 v[92:93], v[84:85], v[82:83] op_sel_hi:[1,0]
	v_cvt_pk_bf16_f32 v88, v88, v89
	v_cvt_pk_bf16_f32 v89, v90, v91
	global_store_dwordx2 v[58:59], v[88:89], off
	v_pk_mul_f32 v[94:95], v[86:87], v[82:83] op_sel_hi:[1,0]
	ds_read_b128 v[84:87], v83 offset:1024
	ds_read_b128 v[88:91], v83 offset:41984
	s_waitcnt lgkmcnt(0)
	v_pk_fma_f32 v[86:87], v[86:87], v[94:95], v[90:91]
	v_pk_fma_f32 v[84:85], v[84:85], v[92:93], v[88:89]
	v_pk_mul_f32 v[88:89], v[74:75], v[82:83] op_sel_hi:[1,0]
	v_cvt_pk_bf16_f32 v84, v84, v85
	v_cvt_pk_bf16_f32 v85, v86, v87
	global_store_dwordx2 v[58:59], v[84:85], off offset:512
	v_pk_mul_f32 v[90:91], v[76:77], v[82:83] op_sel_hi:[1,0]
	ds_read_b128 v[74:77], v83 offset:2048
	ds_read_b128 v[84:87], v83 offset:43008
	s_waitcnt lgkmcnt(0)
	v_pk_fma_f32 v[76:77], v[76:77], v[90:91], v[86:87]
	v_pk_fma_f32 v[74:75], v[74:75], v[88:89], v[84:85]
	v_pk_mul_f32 v[84:85], v[78:79], v[82:83] op_sel_hi:[1,0]
	v_cvt_pk_bf16_f32 v74, v74, v75
	v_cvt_pk_bf16_f32 v75, v76, v77
	global_store_dwordx2 v[58:59], v[74:75], off offset:1024
	v_pk_mul_f32 v[86:87], v[80:81], v[82:83] op_sel_hi:[1,0]
	ds_read_b128 v[74:77], v83 offset:3072
	ds_read_b128 v[78:81], v83 offset:44032
	s_waitcnt lgkmcnt(0)
	v_pk_fma_f32 v[76:77], v[86:87], v[76:77], v[80:81]
	v_pk_fma_f32 v[74:75], v[84:85], v[74:75], v[78:79]
	v_pk_mul_f32 v[78:79], v[66:67], v[82:83] op_sel_hi:[1,0]
	v_cvt_pk_bf16_f32 v74, v74, v75
	v_cvt_pk_bf16_f32 v75, v76, v77
	global_store_dwordx2 v[58:59], v[74:75], off offset:1536
	v_pk_mul_f32 v[80:81], v[68:69], v[82:83] op_sel_hi:[1,0]
	ds_read_b128 v[66:69], v83 offset:4096
	ds_read_b128 v[74:77], v83 offset:45056
	s_waitcnt lgkmcnt(0)
	v_pk_fma_f32 v[68:69], v[80:81], v[68:69], v[76:77]
	v_pk_fma_f32 v[66:67], v[78:79], v[66:67], v[74:75]
	v_pk_mul_f32 v[74:75], v[70:71], v[82:83] op_sel_hi:[1,0]
	v_cvt_pk_bf16_f32 v66, v66, v67
	v_cvt_pk_bf16_f32 v67, v68, v69
	global_store_dwordx2 v[58:59], v[66:67], off offset:2048
	v_pk_mul_f32 v[76:77], v[72:73], v[82:83] op_sel_hi:[1,0]
	ds_read_b128 v[66:69], v83 offset:5120
	ds_read_b128 v[70:73], v83 offset:46080
	s_waitcnt lgkmcnt(0)
	v_pk_fma_f32 v[68:69], v[76:77], v[68:69], v[72:73]
	v_pk_fma_f32 v[66:67], v[74:75], v[66:67], v[70:71]
	s_waitcnt vmcnt(60)
	v_cvt_f32_f16_sdwa v75, v57 dst_sel:DWORD dst_unused:UNUSED_PAD src0_sel:WORD_1
	v_cvt_pk_bf16_f32 v66, v66, v67
	v_cvt_pk_bf16_f32 v67, v68, v69
	global_store_dwordx2 v[58:59], v[66:67], off offset:2560
	ds_read_b128 v[66:69], v83 offset:6144
	ds_read_b128 v[70:73], v83 offset:47104
	v_cvt_f32_f16_e32 v74, v57
	s_waitcnt lgkmcnt(0)
	v_pk_fma_f32 v[62:63], v[62:63], v[68:69], v[72:73]
	v_pk_fma_f32 v[4:5], v[4:5], v[66:67], v[70:71]
	v_pk_mul_f32 v[68:69], v[64:65], v[82:83] op_sel_hi:[1,0]
	v_cvt_pk_bf16_f32 v4, v4, v5
	v_cvt_pk_bf16_f32 v5, v62, v63
	global_store_dwordx2 v[58:59], v[4:5], off offset:3072
	v_pk_mul_f32 v[4:5], v[60:61], v[82:83] op_sel_hi:[1,0]
	ds_read_b128 v[60:63], v83 offset:7168
	ds_read_b128 v[64:67], v83 offset:48128
	v_cvt_f32_f16_sdwa v73, v56 dst_sel:DWORD dst_unused:UNUSED_PAD src0_sel:WORD_1
	v_cvt_f32_f16_e32 v72, v56
	s_waitcnt vmcnt(61)
	v_cvt_f32_f16_sdwa v71, v55 dst_sel:DWORD dst_unused:UNUSED_PAD src0_sel:WORD_1
	v_cvt_f32_f16_e32 v70, v55
	s_waitcnt lgkmcnt(0)
	v_pk_fma_f32 v[62:63], v[68:69], v[62:63], v[66:67]
	v_cvt_f32_f16_sdwa v69, v54 dst_sel:DWORD dst_unused:UNUSED_PAD src0_sel:WORD_1
	v_cvt_f32_f16_e32 v68, v54
	v_pk_fma_f32 v[4:5], v[4:5], v[60:61], v[64:65]
	v_mov_b32_e32 v54, v73
	v_cvt_pk_bf16_f32 v4, v4, v5
	v_cvt_pk_bf16_f32 v5, v62, v63
	global_store_dwordx2 v[58:59], v[4:5], off offset:3584
	v_mov_b32_e32 v55, v69
	s_waitcnt vmcnt(61)
	v_cvt_f32_f16_sdwa v59, v52 dst_sel:DWORD dst_unused:UNUSED_PAD src0_sel:WORD_1
	v_cvt_f32_f16_sdwa v61, v53 dst_sel:DWORD dst_unused:UNUSED_PAD src0_sel:WORD_1
	v_mov_b32_e32 v4, v72
	v_mov_b32_e32 v5, v68
	v_pk_mul_f32 v[54:55], v[54:55], v[54:55]
	v_mov_b32_e32 v56, v75
	v_mov_b32_e32 v57, v71
	v_cvt_f32_f16_e32 v58, v52
	v_cvt_f32_f16_e32 v60, v53
	s_waitcnt vmcnt(60)
	v_cvt_f32_f16_sdwa v63, v50 dst_sel:DWORD dst_unused:UNUSED_PAD src0_sel:WORD_1
	v_pk_fma_f32 v[4:5], v[4:5], v[4:5], v[54:55]
	v_mov_b32_e32 v54, v74
	v_mov_b32_e32 v55, v70
	v_pk_mul_f32 v[56:57], v[56:57], v[56:57]
	v_cvt_f32_f16_e32 v62, v50
	v_cvt_f32_f16_sdwa v65, v51 dst_sel:DWORD dst_unused:UNUSED_PAD src0_sel:WORD_1
	v_pk_fma_f32 v[54:55], v[54:55], v[54:55], v[56:57]
	v_cvt_f32_f16_e32 v64, v51
	v_pk_add_f32 v[4:5], v[4:5], v[54:55]
	v_mov_b32_e32 v54, v59
	v_mov_b32_e32 v55, v61
	v_mov_b32_e32 v52, v58
	v_mov_b32_e32 v53, v60
	v_pk_mul_f32 v[54:55], v[54:55], v[54:55]
	v_mul_f32_e32 v50, v63, v63
	v_pk_fma_f32 v[52:53], v[52:53], v[52:53], v[54:55]
	v_pk_fma_f32 v[56:57], v[62:63], v[62:63], v[50:51] op_sel_hi:[1,1,0]
	v_mul_f32_e32 v50, v65, v65
	v_pk_add_f32 v[54:55], v[52:53], v[52:53] op_sel:[0,1] op_sel_hi:[1,0]
	v_pk_fma_f32 v[66:67], v[64:65], v[64:65], v[50:51] op_sel_hi:[1,1,0]
	s_waitcnt vmcnt(59)
	v_cvt_f32_f16_sdwa v51, v48 dst_sel:DWORD dst_unused:UNUSED_PAD src0_sel:WORD_1
	v_cvt_f32_f16_e32 v50, v48
	v_cvt_f32_f16_sdwa v53, v49 dst_sel:DWORD dst_unused:UNUSED_PAD src0_sel:WORD_1
	v_cvt_f32_f16_e32 v52, v49
	v_pk_add_f32 v[4:5], v[4:5], v[4:5] op_sel:[0,1] op_sel_hi:[1,0]
	v_pk_mul_f32 v[48:49], v[50:51], v[50:51]
	v_pk_mul_f32 v[76:77], v[52:53], v[52:53]
	v_mov_b32_e32 v5, v48
	v_mov_b32_e32 v55, v49
	v_mov_b32_e32 v57, v76
	v_mov_b32_e32 v67, v77
	v_pk_add_f32 v[4:5], v[4:5], v[54:55]
	v_pk_add_f32 v[48:49], v[56:57], v[66:67]
	s_waitcnt vmcnt(58)
	v_cvt_f32_f16_sdwa v55, v46 dst_sel:DWORD dst_unused:UNUSED_PAD src0_sel:WORD_1
	v_cvt_f32_f16_sdwa v57, v47 dst_sel:DWORD dst_unused:UNUSED_PAD src0_sel:WORD_1
	v_cvt_f32_f16_e32 v54, v46
	v_cvt_f32_f16_e32 v56, v47
	v_pk_add_f32 v[4:5], v[4:5], v[48:49]
	v_mov_b32_e32 v46, v55
	v_mov_b32_e32 v47, v57
	v_pk_add_f32 v[66:67], v[4:5], v[4:5] op_sel:[0,1] op_sel_hi:[1,0]
	v_mov_b32_e32 v4, v54
	v_mov_b32_e32 v5, v56
	v_pk_mul_f32 v[46:47], v[46:47], v[46:47]
	s_waitcnt vmcnt(56)
	v_cvt_f32_f16_sdwa v49, v43 dst_sel:DWORD dst_unused:UNUSED_PAD src0_sel:WORD_1
	v_pk_fma_f32 v[4:5], v[4:5], v[4:5], v[46:47]
	v_cvt_f32_f16_sdwa v47, v45 dst_sel:DWORD dst_unused:UNUSED_PAD src0_sel:WORD_1
	v_pk_add_f32 v[76:77], v[4:5], v[4:5] op_sel:[0,1] op_sel_hi:[1,0]
	v_cvt_f32_f16_sdwa v5, v44 dst_sel:DWORD dst_unused:UNUSED_PAD src0_sel:WORD_1
	v_cvt_f32_f16_e32 v4, v44
	v_cvt_f32_f16_e32 v46, v45
	v_cvt_f32_f16_e32 v48, v43
	v_mul_f32_e32 v44, v5, v5
	v_pk_fma_f32 v[78:79], v[4:5], v[4:5], v[44:45] op_sel_hi:[1,1,0]
	v_mul_f32_e32 v44, v47, v47
	v_pk_fma_f32 v[80:81], v[46:47], v[46:47], v[44:45] op_sel_hi:[1,1,0]
	v_cvt_f32_f16_sdwa v45, v42 dst_sel:DWORD dst_unused:UNUSED_PAD src0_sel:WORD_1
	v_cvt_f32_f16_e32 v44, v42
	v_pk_mul_f32 v[82:83], v[48:49], v[48:49]
	v_pk_mul_f32 v[42:43], v[44:45], v[44:45]
	s_nop 0
	v_mov_b32_e32 v67, v42
	v_mov_b32_e32 v77, v43
	v_mov_b32_e32 v79, v82
	v_mov_b32_e32 v81, v83
	v_pk_add_f32 v[42:43], v[66:67], v[76:77]
	v_pk_add_f32 v[66:67], v[78:79], v[80:81]
	s_nop 0
	v_pk_add_f32 v[42:43], v[42:43], v[66:67]
	s_nop 0
	v_add_f32_e32 v42, v42, v43
	s_nop 1
	v_add_f32_dpp v42, v42, v42 quad_perm:[1,0,3,2] row_mask:0xf bank_mask:0xf bound_ctrl:1
	s_nop 1
	v_add_f32_dpp v42, v42, v42 quad_perm:[2,3,0,1] row_mask:0xf bank_mask:0xf bound_ctrl:1
	s_nop 1
	v_add_f32_dpp v42, v42, v42 row_half_mirror row_mask:0xf bank_mask:0xf bound_ctrl:1
	s_nop 1
	v_add_f32_dpp v42, v42, v42 row_mirror row_mask:0xf bank_mask:0xf bound_ctrl:1
	s_nop 0
	v_readlane_b32 s5, v42, 16
	v_readlane_b32 s11, v42, 48
	v_readlane_b32 s6, v42, 0
	v_readlane_b32 s7, v42, 32
	v_mov_b32_e32 v42, s5
	v_mov_b32_e32 v43, s11
	v_pk_add_f32 v[42:43], s[6:7], v[42:43]
	s_lshl_b32 s5, s18, 1
	v_add_f32_e32 v42, v42, v43
	v_fmamk_f32 v42, v42, 0x3a000000, v252
	v_cmp_gt_f32_e32 vcc, s55, v42
	v_mul_f32_e32 v43, 0x4f800000, v42
	s_and_b32 s5, s5, 0xffffe000
	v_cndmask_b32_e32 v42, v42, v43, vcc
	v_sqrt_f32_e32 v43, v42
	s_add_i32 s5, s5, 0
	v_add_u32_e32 v66, -1, v43
	v_fma_f32 v67, -v66, v43, v42
	v_cmp_ge_f32_e64 s[6:7], 0, v67
	v_add_u32_e32 v67, 1, v43
	s_nop 0
	v_cndmask_b32_e64 v66, v43, v66, s[6:7]
	v_fma_f32 v43, -v67, v43, v42
	v_cmp_lt_f32_e64 s[6:7], 0, v43
	s_nop 1
	v_cndmask_b32_e64 v43, v66, v67, s[6:7]
	v_mul_f32_e32 v66, 0x37800000, v43
	v_cndmask_b32_e32 v43, v43, v66, vcc
	v_cmp_class_f32_e32 vcc, v42, v253
	s_nop 1
	v_cndmask_b32_e32 v42, v43, v42, vcc
	v_div_scale_f32 v43, s[6:7], v42, v42, 1.0
	v_rcp_f32_e32 v66, v43
	s_nop 0
	v_fma_f32 v67, -v43, v66, 1.0
	v_fmac_f32_e32 v66, v67, v66
	v_div_scale_f32 v67, vcc, 1.0, v42, 1.0
	v_mul_f32_e32 v76, v67, v66
	v_fma_f32 v77, -v43, v76, v67
	v_fmac_f32_e32 v76, v77, v66
	v_fma_f32 v43, -v43, v76, v67
	v_div_fmas_f32 v43, v43, v66, v76
	v_div_fixup_f32 v66, v43, v42, 1.0
	v_pk_mul_f32 v[80:81], v[72:73], v[66:67] op_sel_hi:[1,0]
	v_pk_mul_f32 v[82:83], v[74:75], v[66:67] op_sel_hi:[1,0]
	v_add_u32_e32 v67, s5, v0
	ds_read_b128 v[72:75], v67
	ds_read_b128 v[76:79], v67 offset:40960
	v_lshl_add_u64 v[42:43], s[20:21], 1, v[2:3]
	v_lshl_add_u64 v[42:43], v[42:43], 0, v[6:7]
	v_pk_mul_f32 v[4:5], v[4:5], v[66:67] op_sel_hi:[1,0]
	v_pk_mul_f32 v[46:47], v[46:47], v[66:67] op_sel_hi:[1,0]
	s_waitcnt lgkmcnt(0)
	v_pk_fma_f32 v[74:75], v[74:75], v[82:83], v[78:79]
	v_pk_fma_f32 v[72:73], v[72:73], v[80:81], v[76:77]
	v_pk_mul_f32 v[76:77], v[68:69], v[66:67] op_sel_hi:[1,0]
	v_cvt_pk_bf16_f32 v72, v72, v73
	v_cvt_pk_bf16_f32 v73, v74, v75
	global_store_dwordx2 v[42:43], v[72:73], off
	v_pk_mul_f32 v[78:79], v[70:71], v[66:67] op_sel_hi:[1,0]
	ds_read_b128 v[68:71], v67 offset:1024
	ds_read_b128 v[72:75], v67 offset:41984
	s_waitcnt lgkmcnt(0)
	v_pk_fma_f32 v[70:71], v[70:71], v[78:79], v[74:75]
	v_pk_fma_f32 v[68:69], v[68:69], v[76:77], v[72:73]
	v_pk_mul_f32 v[72:73], v[58:59], v[66:67] op_sel_hi:[1,0]
	v_cvt_pk_bf16_f32 v68, v68, v69
	v_cvt_pk_bf16_f32 v69, v70, v71
	global_store_dwordx2 v[42:43], v[68:69], off offset:512
	v_pk_mul_f32 v[74:75], v[60:61], v[66:67] op_sel_hi:[1,0]
	ds_read_b128 v[58:61], v67 offset:2048
	ds_read_b128 v[68:71], v67 offset:43008
	s_waitcnt lgkmcnt(0)
	v_pk_fma_f32 v[60:61], v[60:61], v[74:75], v[70:71]
	v_pk_fma_f32 v[58:59], v[58:59], v[72:73], v[68:69]
	v_pk_mul_f32 v[68:69], v[62:63], v[66:67] op_sel_hi:[1,0]
	v_cvt_pk_bf16_f32 v58, v58, v59
	v_cvt_pk_bf16_f32 v59, v60, v61
	global_store_dwordx2 v[42:43], v[58:59], off offset:1024
	v_pk_mul_f32 v[70:71], v[64:65], v[66:67] op_sel_hi:[1,0]
	ds_read_b128 v[58:61], v67 offset:3072
	ds_read_b128 v[62:65], v67 offset:44032
	s_waitcnt lgkmcnt(0)
	v_pk_fma_f32 v[60:61], v[70:71], v[60:61], v[64:65]
	v_pk_fma_f32 v[58:59], v[68:69], v[58:59], v[62:63]
	v_pk_mul_f32 v[62:63], v[50:51], v[66:67] op_sel_hi:[1,0]
	v_cvt_pk_bf16_f32 v58, v58, v59
	v_cvt_pk_bf16_f32 v59, v60, v61
	global_store_dwordx2 v[42:43], v[58:59], off offset:1536
	v_pk_mul_f32 v[64:65], v[52:53], v[66:67] op_sel_hi:[1,0]
	ds_read_b128 v[50:53], v67 offset:4096
	ds_read_b128 v[58:61], v67 offset:45056
	s_waitcnt lgkmcnt(0)
	v_pk_fma_f32 v[52:53], v[64:65], v[52:53], v[60:61]
	v_pk_fma_f32 v[50:51], v[62:63], v[50:51], v[58:59]
	v_pk_mul_f32 v[58:59], v[54:55], v[66:67] op_sel_hi:[1,0]
	v_cvt_pk_bf16_f32 v50, v50, v51
	v_cvt_pk_bf16_f32 v51, v52, v53
	global_store_dwordx2 v[42:43], v[50:51], off offset:2048
	v_pk_mul_f32 v[60:61], v[56:57], v[66:67] op_sel_hi:[1,0]
	ds_read_b128 v[50:53], v67 offset:5120
	ds_read_b128 v[54:57], v67 offset:46080
	s_waitcnt lgkmcnt(0)
	v_pk_fma_f32 v[52:53], v[60:61], v[52:53], v[56:57]
	v_pk_fma_f32 v[50:51], v[58:59], v[50:51], v[54:55]
	s_waitcnt vmcnt(60)
	v_cvt_f32_f16_sdwa v59, v41 dst_sel:DWORD dst_unused:UNUSED_PAD src0_sel:WORD_1
	v_cvt_pk_bf16_f32 v50, v50, v51
	v_cvt_pk_bf16_f32 v51, v52, v53
	global_store_dwordx2 v[42:43], v[50:51], off offset:2560
	ds_read_b128 v[50:53], v67 offset:6144
	ds_read_b128 v[54:57], v67 offset:47104
	v_cvt_f32_f16_e32 v58, v41
	s_waitcnt lgkmcnt(0)
	v_pk_fma_f32 v[46:47], v[46:47], v[52:53], v[56:57]
	v_pk_fma_f32 v[4:5], v[4:5], v[50:51], v[54:55]
	v_pk_mul_f32 v[52:53], v[48:49], v[66:67] op_sel_hi:[1,0]
	v_cvt_pk_bf16_f32 v4, v4, v5
	v_cvt_pk_bf16_f32 v5, v46, v47
	global_store_dwordx2 v[42:43], v[4:5], off offset:3072
	v_pk_mul_f32 v[4:5], v[44:45], v[66:67] op_sel_hi:[1,0]
	ds_read_b128 v[44:47], v67 offset:7168
	ds_read_b128 v[48:51], v67 offset:48128
	v_cvt_f32_f16_sdwa v57, v40 dst_sel:DWORD dst_unused:UNUSED_PAD src0_sel:WORD_1
	v_cvt_f32_f16_e32 v56, v40
	s_waitcnt vmcnt(61)
	v_cvt_f32_f16_sdwa v55, v39 dst_sel:DWORD dst_unused:UNUSED_PAD src0_sel:WORD_1
	v_cvt_f32_f16_e32 v54, v39
	s_waitcnt lgkmcnt(0)
	v_pk_fma_f32 v[46:47], v[52:53], v[46:47], v[50:51]
	v_cvt_f32_f16_sdwa v53, v38 dst_sel:DWORD dst_unused:UNUSED_PAD src0_sel:WORD_1
	v_cvt_f32_f16_e32 v52, v38
	v_pk_fma_f32 v[4:5], v[4:5], v[44:45], v[48:49]
	v_mov_b32_e32 v38, v57
	v_cvt_pk_bf16_f32 v4, v4, v5
	v_cvt_pk_bf16_f32 v5, v46, v47
	global_store_dwordx2 v[42:43], v[4:5], off offset:3584
	v_mov_b32_e32 v39, v53
	s_waitcnt vmcnt(61)
	v_cvt_f32_f16_sdwa v43, v36 dst_sel:DWORD dst_unused:UNUSED_PAD src0_sel:WORD_1
	v_cvt_f32_f16_sdwa v45, v37 dst_sel:DWORD dst_unused:UNUSED_PAD src0_sel:WORD_1
	v_mov_b32_e32 v4, v56
	v_mov_b32_e32 v5, v52
	v_pk_mul_f32 v[38:39], v[38:39], v[38:39]
	v_mov_b32_e32 v40, v59
	v_mov_b32_e32 v41, v55
	v_cvt_f32_f16_e32 v42, v36
	v_cvt_f32_f16_e32 v44, v37
	s_waitcnt vmcnt(60)
	v_cvt_f32_f16_sdwa v47, v34 dst_sel:DWORD dst_unused:UNUSED_PAD src0_sel:WORD_1
	v_pk_fma_f32 v[4:5], v[4:5], v[4:5], v[38:39]
	v_mov_b32_e32 v38, v58
	v_mov_b32_e32 v39, v54
	v_pk_mul_f32 v[40:41], v[40:41], v[40:41]
	v_cvt_f32_f16_e32 v46, v34
	v_cvt_f32_f16_sdwa v49, v35 dst_sel:DWORD dst_unused:UNUSED_PAD src0_sel:WORD_1
	v_pk_fma_f32 v[38:39], v[38:39], v[38:39], v[40:41]
	v_cvt_f32_f16_e32 v48, v35
	v_pk_add_f32 v[4:5], v[4:5], v[38:39]
	v_mov_b32_e32 v38, v43
	v_mov_b32_e32 v39, v45
	v_mov_b32_e32 v36, v42
	v_mov_b32_e32 v37, v44
	v_pk_mul_f32 v[38:39], v[38:39], v[38:39]
	v_mul_f32_e32 v34, v47, v47
	v_pk_fma_f32 v[36:37], v[36:37], v[36:37], v[38:39]
	v_pk_fma_f32 v[40:41], v[46:47], v[46:47], v[34:35] op_sel_hi:[1,1,0]
	v_mul_f32_e32 v34, v49, v49
	v_pk_add_f32 v[38:39], v[36:37], v[36:37] op_sel:[0,1] op_sel_hi:[1,0]
	v_pk_fma_f32 v[50:51], v[48:49], v[48:49], v[34:35] op_sel_hi:[1,1,0]
	s_waitcnt vmcnt(59)
	v_cvt_f32_f16_sdwa v35, v32 dst_sel:DWORD dst_unused:UNUSED_PAD src0_sel:WORD_1
	v_cvt_f32_f16_e32 v34, v32
	v_cvt_f32_f16_sdwa v37, v33 dst_sel:DWORD dst_unused:UNUSED_PAD src0_sel:WORD_1
	v_cvt_f32_f16_e32 v36, v33
	v_pk_add_f32 v[4:5], v[4:5], v[4:5] op_sel:[0,1] op_sel_hi:[1,0]
	v_pk_mul_f32 v[32:33], v[34:35], v[34:35]
	v_pk_mul_f32 v[60:61], v[36:37], v[36:37]
	v_mov_b32_e32 v5, v32
	v_mov_b32_e32 v39, v33
	v_mov_b32_e32 v41, v60
	v_mov_b32_e32 v51, v61
	v_pk_add_f32 v[4:5], v[4:5], v[38:39]
	v_pk_add_f32 v[32:33], v[40:41], v[50:51]
	s_waitcnt vmcnt(58)
	v_cvt_f32_f16_sdwa v39, v30 dst_sel:DWORD dst_unused:UNUSED_PAD src0_sel:WORD_1
	v_cvt_f32_f16_sdwa v41, v31 dst_sel:DWORD dst_unused:UNUSED_PAD src0_sel:WORD_1
	v_cvt_f32_f16_e32 v38, v30
	v_cvt_f32_f16_e32 v40, v31
	v_pk_add_f32 v[4:5], v[4:5], v[32:33]
	v_mov_b32_e32 v30, v39
	v_mov_b32_e32 v31, v41
	v_pk_add_f32 v[50:51], v[4:5], v[4:5] op_sel:[0,1] op_sel_hi:[1,0]
	v_mov_b32_e32 v4, v38
	v_mov_b32_e32 v5, v40
	v_pk_mul_f32 v[30:31], v[30:31], v[30:31]
	s_waitcnt vmcnt(56)
	v_cvt_f32_f16_sdwa v33, v27 dst_sel:DWORD dst_unused:UNUSED_PAD src0_sel:WORD_1
	v_pk_fma_f32 v[4:5], v[4:5], v[4:5], v[30:31]
	v_cvt_f32_f16_sdwa v31, v29 dst_sel:DWORD dst_unused:UNUSED_PAD src0_sel:WORD_1
	v_pk_add_f32 v[60:61], v[4:5], v[4:5] op_sel:[0,1] op_sel_hi:[1,0]
	v_cvt_f32_f16_sdwa v5, v28 dst_sel:DWORD dst_unused:UNUSED_PAD src0_sel:WORD_1
	v_cvt_f32_f16_e32 v4, v28
	v_cvt_f32_f16_e32 v30, v29
	v_cvt_f32_f16_e32 v32, v27
	v_mul_f32_e32 v28, v5, v5
	v_pk_fma_f32 v[62:63], v[4:5], v[4:5], v[28:29] op_sel_hi:[1,1,0]
	v_mul_f32_e32 v28, v31, v31
	v_pk_fma_f32 v[64:65], v[30:31], v[30:31], v[28:29] op_sel_hi:[1,1,0]
	v_cvt_f32_f16_sdwa v29, v26 dst_sel:DWORD dst_unused:UNUSED_PAD src0_sel:WORD_1
	v_cvt_f32_f16_e32 v28, v26
	v_pk_mul_f32 v[66:67], v[32:33], v[32:33]
	v_pk_mul_f32 v[26:27], v[28:29], v[28:29]
	s_nop 0
	v_mov_b32_e32 v51, v26
	v_mov_b32_e32 v61, v27
	v_mov_b32_e32 v63, v66
	v_mov_b32_e32 v65, v67
	v_pk_add_f32 v[26:27], v[50:51], v[60:61]
	v_pk_add_f32 v[50:51], v[62:63], v[64:65]
	s_nop 0
	v_pk_add_f32 v[26:27], v[26:27], v[50:51]
	s_nop 0
	v_add_f32_e32 v26, v26, v27
	s_nop 1
	v_add_f32_dpp v26, v26, v26 quad_perm:[1,0,3,2] row_mask:0xf bank_mask:0xf bound_ctrl:1
	s_nop 1
	v_add_f32_dpp v26, v26, v26 quad_perm:[2,3,0,1] row_mask:0xf bank_mask:0xf bound_ctrl:1
	s_nop 1
	v_add_f32_dpp v26, v26, v26 row_half_mirror row_mask:0xf bank_mask:0xf bound_ctrl:1
	s_nop 1
	v_add_f32_dpp v26, v26, v26 row_mirror row_mask:0xf bank_mask:0xf bound_ctrl:1
	s_nop 0
	v_readlane_b32 s5, v26, 16
	v_readlane_b32 s11, v26, 48
	v_readlane_b32 s6, v26, 0
	v_readlane_b32 s7, v26, 32
	v_mov_b32_e32 v26, s5
	v_mov_b32_e32 v27, s11
	v_pk_add_f32 v[26:27], s[6:7], v[26:27]
	s_lshl_b32 s5, s14, 1
	v_add_f32_e32 v26, v26, v27
	v_fmamk_f32 v26, v26, 0x3a000000, v252
	v_cmp_gt_f32_e32 vcc, s55, v26
	v_mul_f32_e32 v27, 0x4f800000, v26
	s_and_b32 s5, s5, 0xffffe000
	v_cndmask_b32_e32 v26, v26, v27, vcc
	v_sqrt_f32_e32 v27, v26
	s_add_i32 s5, s5, 0
	v_add_u32_e32 v50, -1, v27
	v_fma_f32 v51, -v50, v27, v26
	v_cmp_ge_f32_e64 s[6:7], 0, v51
	v_add_u32_e32 v51, 1, v27
	s_nop 0
	v_cndmask_b32_e64 v50, v27, v50, s[6:7]
	v_fma_f32 v27, -v51, v27, v26
	v_cmp_lt_f32_e64 s[6:7], 0, v27
	s_nop 1
	v_cndmask_b32_e64 v27, v50, v51, s[6:7]
	v_mul_f32_e32 v50, 0x37800000, v27
	v_cndmask_b32_e32 v27, v27, v50, vcc
	v_cmp_class_f32_e32 vcc, v26, v253
	s_nop 1
	v_cndmask_b32_e32 v26, v27, v26, vcc
	v_div_scale_f32 v27, s[6:7], v26, v26, 1.0
	v_rcp_f32_e32 v50, v27
	s_nop 0
	v_fma_f32 v51, -v27, v50, 1.0
	v_fmac_f32_e32 v50, v51, v50
	v_div_scale_f32 v51, vcc, 1.0, v26, 1.0
	v_mul_f32_e32 v60, v51, v50
	v_fma_f32 v61, -v27, v60, v51
	v_fmac_f32_e32 v60, v61, v50
	v_fma_f32 v27, -v27, v60, v51
	v_div_fmas_f32 v27, v27, v50, v60
	v_div_fixup_f32 v50, v27, v26, 1.0
	v_pk_mul_f32 v[64:65], v[56:57], v[50:51] op_sel_hi:[1,0]
	v_pk_mul_f32 v[66:67], v[58:59], v[50:51] op_sel_hi:[1,0]
	v_add_u32_e32 v51, s5, v0
	ds_read_b128 v[56:59], v51
	ds_read_b128 v[60:63], v51 offset:40960
	v_lshl_add_u64 v[26:27], s[16:17], 1, v[2:3]
	v_lshl_add_u64 v[26:27], v[26:27], 0, v[6:7]
	v_pk_mul_f32 v[4:5], v[4:5], v[50:51] op_sel_hi:[1,0]
	v_pk_mul_f32 v[30:31], v[30:31], v[50:51] op_sel_hi:[1,0]
	s_waitcnt lgkmcnt(0)
	v_pk_fma_f32 v[58:59], v[58:59], v[66:67], v[62:63]
	v_pk_fma_f32 v[56:57], v[56:57], v[64:65], v[60:61]
	v_pk_mul_f32 v[60:61], v[52:53], v[50:51] op_sel_hi:[1,0]
	v_cvt_pk_bf16_f32 v56, v56, v57
	v_cvt_pk_bf16_f32 v57, v58, v59
	global_store_dwordx2 v[26:27], v[56:57], off
	v_pk_mul_f32 v[62:63], v[54:55], v[50:51] op_sel_hi:[1,0]
	ds_read_b128 v[52:55], v51 offset:1024
	ds_read_b128 v[56:59], v51 offset:41984
	s_waitcnt lgkmcnt(0)
	v_pk_fma_f32 v[54:55], v[54:55], v[62:63], v[58:59]
	v_pk_fma_f32 v[52:53], v[52:53], v[60:61], v[56:57]
	v_pk_mul_f32 v[56:57], v[42:43], v[50:51] op_sel_hi:[1,0]
	v_cvt_pk_bf16_f32 v52, v52, v53
	v_cvt_pk_bf16_f32 v53, v54, v55
	global_store_dwordx2 v[26:27], v[52:53], off offset:512
	v_pk_mul_f32 v[58:59], v[44:45], v[50:51] op_sel_hi:[1,0]
	ds_read_b128 v[42:45], v51 offset:2048
	ds_read_b128 v[52:55], v51 offset:43008
	s_waitcnt lgkmcnt(0)
	v_pk_fma_f32 v[44:45], v[44:45], v[58:59], v[54:55]
	v_pk_fma_f32 v[42:43], v[42:43], v[56:57], v[52:53]
	v_pk_mul_f32 v[52:53], v[46:47], v[50:51] op_sel_hi:[1,0]
	v_cvt_pk_bf16_f32 v42, v42, v43
	v_cvt_pk_bf16_f32 v43, v44, v45
	global_store_dwordx2 v[26:27], v[42:43], off offset:1024
	v_pk_mul_f32 v[54:55], v[48:49], v[50:51] op_sel_hi:[1,0]
	ds_read_b128 v[42:45], v51 offset:3072
	ds_read_b128 v[46:49], v51 offset:44032
	s_waitcnt lgkmcnt(0)
	v_pk_fma_f32 v[44:45], v[54:55], v[44:45], v[48:49]
	v_pk_fma_f32 v[42:43], v[52:53], v[42:43], v[46:47]
	v_pk_mul_f32 v[46:47], v[34:35], v[50:51] op_sel_hi:[1,0]
	v_cvt_pk_bf16_f32 v42, v42, v43
	v_cvt_pk_bf16_f32 v43, v44, v45
	global_store_dwordx2 v[26:27], v[42:43], off offset:1536
	v_pk_mul_f32 v[48:49], v[36:37], v[50:51] op_sel_hi:[1,0]
	ds_read_b128 v[34:37], v51 offset:4096
	ds_read_b128 v[42:45], v51 offset:45056
	s_waitcnt lgkmcnt(0)
	v_pk_fma_f32 v[36:37], v[48:49], v[36:37], v[44:45]
	v_pk_fma_f32 v[34:35], v[46:47], v[34:35], v[42:43]
	v_pk_mul_f32 v[42:43], v[38:39], v[50:51] op_sel_hi:[1,0]
	v_cvt_pk_bf16_f32 v34, v34, v35
	v_cvt_pk_bf16_f32 v35, v36, v37
	global_store_dwordx2 v[26:27], v[34:35], off offset:2048
	v_pk_mul_f32 v[44:45], v[40:41], v[50:51] op_sel_hi:[1,0]
	ds_read_b128 v[34:37], v51 offset:5120
	ds_read_b128 v[38:41], v51 offset:46080
	s_waitcnt lgkmcnt(0)
	v_pk_fma_f32 v[36:37], v[44:45], v[36:37], v[40:41]
	v_pk_fma_f32 v[34:35], v[42:43], v[34:35], v[38:39]
	s_waitcnt vmcnt(60)
; #define GAS __attribute__((address_space(1)))
; #define LAS __attribute__((address_space(3)))
; #define NR_LOAD(dst, k_) do { const GAS v2u* xr_ = (const GAS v2u*)(X + (size_t)(nw + 2048 * (k_)) * D) + F.lane; \
;         _Pragma("unroll") for (int j = 0; j < 8; ++j) dst[j] = __builtin_nontemporal_load(xr_ + 64 * j); } while (0)
; __device__ __forceinline__ void norm_mod_phase2(const Args& a, Frame& F, const float* gain, const float* modl, int sh_off, int sc_off, int nrows, const float* slab_gate) {
;     ...
;     NR_LOAD(r0, 0); NR_LOAD(r1, 1); NR_LOAD(r2, 2); NR_LOAD(r3, 3); NR_LOAD(r4, 4); NR_LOAD(r5, 5); NR_LOAD(r6, 6); NR_LOAD(r7, 7);
;     { const GAS f32x4* g4 = (const GAS f32x4*)gain;
;       for (int q = F.tid; q < 5 * D / 4; q += NWAVES * 64) { const int bq = q >> 9, cq = q & 511; const GAS f32x4* mb4 = (const GAS f32x4*)(modl + (size_t)bq * MOD_LD);
;           ((LAS f32x4*)CA)[q] = g4[cq] * (mb4[sc_off / 4 + cq] + 1.0f); ((LAS f32x4*)CB)[q] = mb4[sh_off / 4 + cq]; } }
;     asm volatile("s_waitcnt lgkmcnt(0)" ::: "memory"); __builtin_amdgcn_s_barrier(); asm volatile("" ::: "memory");
;     NR_FINISH(r0, nw,            (nw) >> 12);
;     NR_FINISH(r1, nw + 2048,     (nw + 2048) >> 12);
;     NR_FINISH(r2, nw + 2 * 2048, (nw + 2 * 2048) >> 12);
;     NR_FINISH(r3, nw + 3 * 2048, (nw + 3 * 2048) >> 12);
;     NR_FINISH(r4, nw + 4 * 2048, (nw + 4 * 2048) >> 12);
;     NR_FINISH(r5, nw + 5 * 2048, (nw + 5 * 2048) >> 12);
;     NR_FINISH(r6, nw + 6 * 2048, (nw + 6 * 2048) >> 12);
;     NR_FINISH(r7, nw + 7 * 2048, (nw + 7 * 2048) >> 12);
;     if (ML + nw < nrows) {
	v_cvt_f32_f16_sdwa v43, v25 dst_sel:DWORD dst_unused:UNUSED_PAD src0_sel:WORD_1
	v_cvt_pk_bf16_f32 v34, v34, v35
	v_cvt_pk_bf16_f32 v35, v36, v37
	global_store_dwordx2 v[26:27], v[34:35], off offset:2560
	ds_read_b128 v[34:37], v51 offset:6144
	ds_read_b128 v[38:41], v51 offset:47104
	v_cvt_f32_f16_e32 v42, v25
	s_waitcnt lgkmcnt(0)
	v_pk_fma_f32 v[30:31], v[30:31], v[36:37], v[40:41]
	v_pk_fma_f32 v[4:5], v[4:5], v[34:35], v[38:39]
	v_pk_mul_f32 v[36:37], v[32:33], v[50:51] op_sel_hi:[1,0]
	v_cvt_pk_bf16_f32 v4, v4, v5
	v_cvt_pk_bf16_f32 v5, v30, v31
	global_store_dwordx2 v[26:27], v[4:5], off offset:3072
	v_pk_mul_f32 v[4:5], v[28:29], v[50:51] op_sel_hi:[1,0]
	ds_read_b128 v[28:31], v51 offset:7168
	ds_read_b128 v[32:35], v51 offset:48128
	v_cvt_f32_f16_sdwa v41, v24 dst_sel:DWORD dst_unused:UNUSED_PAD src0_sel:WORD_1
	v_cvt_f32_f16_e32 v40, v24
	s_waitcnt vmcnt(61)
	v_cvt_f32_f16_sdwa v39, v23 dst_sel:DWORD dst_unused:UNUSED_PAD src0_sel:WORD_1
	v_cvt_f32_f16_e32 v38, v23
	s_waitcnt lgkmcnt(0)
	v_pk_fma_f32 v[30:31], v[36:37], v[30:31], v[34:35]
	v_cvt_f32_f16_sdwa v37, v22 dst_sel:DWORD dst_unused:UNUSED_PAD src0_sel:WORD_1
	v_cvt_f32_f16_e32 v36, v22
	v_pk_fma_f32 v[4:5], v[4:5], v[28:29], v[32:33]
	v_mov_b32_e32 v22, v41
	v_cvt_pk_bf16_f32 v4, v4, v5
	v_cvt_pk_bf16_f32 v5, v30, v31
	global_store_dwordx2 v[26:27], v[4:5], off offset:3584
	v_mov_b32_e32 v23, v37
	s_waitcnt vmcnt(61)
	v_cvt_f32_f16_sdwa v27, v20 dst_sel:DWORD dst_unused:UNUSED_PAD src0_sel:WORD_1
	v_cvt_f32_f16_sdwa v29, v21 dst_sel:DWORD dst_unused:UNUSED_PAD src0_sel:WORD_1
	v_mov_b32_e32 v4, v40
	v_mov_b32_e32 v5, v36
	v_pk_mul_f32 v[22:23], v[22:23], v[22:23]
	v_mov_b32_e32 v24, v43
	v_mov_b32_e32 v25, v39
	v_cvt_f32_f16_e32 v26, v20
	v_cvt_f32_f16_e32 v28, v21
	s_waitcnt vmcnt(60)
	v_cvt_f32_f16_sdwa v31, v18 dst_sel:DWORD dst_unused:UNUSED_PAD src0_sel:WORD_1
	v_pk_fma_f32 v[4:5], v[4:5], v[4:5], v[22:23]
	v_mov_b32_e32 v22, v42
	v_mov_b32_e32 v23, v38
	v_pk_mul_f32 v[24:25], v[24:25], v[24:25]
	v_cvt_f32_f16_e32 v30, v18
	v_cvt_f32_f16_sdwa v33, v19 dst_sel:DWORD dst_unused:UNUSED_PAD src0_sel:WORD_1
	v_pk_fma_f32 v[22:23], v[22:23], v[22:23], v[24:25]
	v_cvt_f32_f16_e32 v32, v19
	v_pk_add_f32 v[4:5], v[4:5], v[22:23]
	v_mov_b32_e32 v22, v27
	v_mov_b32_e32 v23, v29
	v_mov_b32_e32 v20, v26
	v_mov_b32_e32 v21, v28
	v_pk_mul_f32 v[22:23], v[22:23], v[22:23]
	v_mul_f32_e32 v18, v31, v31
	v_pk_fma_f32 v[20:21], v[20:21], v[20:21], v[22:23]
	v_pk_fma_f32 v[24:25], v[30:31], v[30:31], v[18:19] op_sel_hi:[1,1,0]
	v_mul_f32_e32 v18, v33, v33
	v_pk_add_f32 v[22:23], v[20:21], v[20:21] op_sel:[0,1] op_sel_hi:[1,0]
	v_pk_fma_f32 v[34:35], v[32:33], v[32:33], v[18:19] op_sel_hi:[1,1,0]
	s_waitcnt vmcnt(59)
	v_cvt_f32_f16_sdwa v19, v16 dst_sel:DWORD dst_unused:UNUSED_PAD src0_sel:WORD_1
	v_cvt_f32_f16_e32 v18, v16
	v_cvt_f32_f16_sdwa v21, v17 dst_sel:DWORD dst_unused:UNUSED_PAD src0_sel:WORD_1
	v_cvt_f32_f16_e32 v20, v17
	v_pk_add_f32 v[4:5], v[4:5], v[4:5] op_sel:[0,1] op_sel_hi:[1,0]
	v_pk_mul_f32 v[16:17], v[18:19], v[18:19]
	v_pk_mul_f32 v[44:45], v[20:21], v[20:21]
	v_mov_b32_e32 v5, v16
	v_mov_b32_e32 v23, v17
	v_mov_b32_e32 v25, v44
	v_mov_b32_e32 v35, v45
	v_pk_add_f32 v[4:5], v[4:5], v[22:23]
	v_pk_add_f32 v[16:17], v[24:25], v[34:35]
	s_waitcnt vmcnt(58)
	v_cvt_f32_f16_sdwa v23, v14 dst_sel:DWORD dst_unused:UNUSED_PAD src0_sel:WORD_1
	v_cvt_f32_f16_sdwa v25, v15 dst_sel:DWORD dst_unused:UNUSED_PAD src0_sel:WORD_1
	v_cvt_f32_f16_e32 v22, v14
	v_cvt_f32_f16_e32 v24, v15
	v_pk_add_f32 v[4:5], v[4:5], v[16:17]
	v_mov_b32_e32 v14, v23
	v_mov_b32_e32 v15, v25
	v_pk_add_f32 v[34:35], v[4:5], v[4:5] op_sel:[0,1] op_sel_hi:[1,0]
	v_mov_b32_e32 v4, v22
	v_mov_b32_e32 v5, v24
	v_pk_mul_f32 v[14:15], v[14:15], v[14:15]
	s_waitcnt vmcnt(56)
	v_cvt_f32_f16_sdwa v17, v11 dst_sel:DWORD dst_unused:UNUSED_PAD src0_sel:WORD_1
	v_pk_fma_f32 v[4:5], v[4:5], v[4:5], v[14:15]
	v_cvt_f32_f16_sdwa v15, v13 dst_sel:DWORD dst_unused:UNUSED_PAD src0_sel:WORD_1
	v_pk_add_f32 v[44:45], v[4:5], v[4:5] op_sel:[0,1] op_sel_hi:[1,0]
	v_cvt_f32_f16_sdwa v5, v12 dst_sel:DWORD dst_unused:UNUSED_PAD src0_sel:WORD_1
	v_cvt_f32_f16_e32 v4, v12
	v_cvt_f32_f16_e32 v14, v13
	v_cvt_f32_f16_e32 v16, v11
	v_mul_f32_e32 v12, v5, v5
	v_pk_fma_f32 v[46:47], v[4:5], v[4:5], v[12:13] op_sel_hi:[1,1,0]
	v_mul_f32_e32 v12, v15, v15
	v_pk_fma_f32 v[48:49], v[14:15], v[14:15], v[12:13] op_sel_hi:[1,1,0]
	v_cvt_f32_f16_sdwa v13, v10 dst_sel:DWORD dst_unused:UNUSED_PAD src0_sel:WORD_1
	v_cvt_f32_f16_e32 v12, v10
	v_pk_mul_f32 v[50:51], v[16:17], v[16:17]
	v_pk_mul_f32 v[10:11], v[12:13], v[12:13]
	s_nop 0
	v_mov_b32_e32 v35, v10
	v_mov_b32_e32 v45, v11
	v_mov_b32_e32 v47, v50
	v_mov_b32_e32 v49, v51
	v_pk_add_f32 v[10:11], v[34:35], v[44:45]
	v_pk_add_f32 v[34:35], v[46:47], v[48:49]
	s_nop 0
	v_pk_add_f32 v[10:11], v[10:11], v[34:35]
	s_nop 0
	v_add_f32_e32 v10, v10, v11
	s_nop 1
	v_add_f32_dpp v10, v10, v10 quad_perm:[1,0,3,2] row_mask:0xf bank_mask:0xf bound_ctrl:1
	s_nop 1
	v_add_f32_dpp v10, v10, v10 quad_perm:[2,3,0,1] row_mask:0xf bank_mask:0xf bound_ctrl:1
	s_nop 1
	v_add_f32_dpp v10, v10, v10 row_half_mirror row_mask:0xf bank_mask:0xf bound_ctrl:1
	s_nop 1
	v_add_f32_dpp v10, v10, v10 row_mirror row_mask:0xf bank_mask:0xf bound_ctrl:1
	s_nop 0
	v_readlane_b32 s5, v10, 16
	v_readlane_b32 s11, v10, 48
	v_readlane_b32 s6, v10, 0
	v_readlane_b32 s7, v10, 32
	v_mov_b32_e32 v10, s5
	v_mov_b32_e32 v11, s11
	v_pk_add_f32 v[10:11], s[6:7], v[10:11]
	s_lshl_b32 s5, s10, 1
	v_add_f32_e32 v10, v10, v11
	v_fmamk_f32 v10, v10, 0x3a000000, v252
	v_cmp_gt_f32_e32 vcc, s55, v10
	v_mul_f32_e32 v11, 0x4f800000, v10
	s_and_b32 s5, s5, 0xffffe000
	v_cndmask_b32_e32 v10, v10, v11, vcc
	v_sqrt_f32_e32 v11, v10
	s_add_i32 s5, s5, 0
	s_bitcmp0_b32 s4, 0
	v_add_u32_e32 v34, -1, v11
	v_fma_f32 v35, -v34, v11, v10
	v_cmp_ge_f32_e64 s[6:7], 0, v35
	v_add_u32_e32 v35, 1, v11
	s_nop 0
	v_cndmask_b32_e64 v34, v11, v34, s[6:7]
	v_fma_f32 v11, -v35, v11, v10
	v_cmp_lt_f32_e64 s[6:7], 0, v11
	s_nop 1
	v_cndmask_b32_e64 v11, v34, v35, s[6:7]
	v_mul_f32_e32 v34, 0x37800000, v11
	v_cndmask_b32_e32 v11, v11, v34, vcc
	v_cmp_class_f32_e32 vcc, v10, v253
	s_nop 1
	v_cndmask_b32_e32 v10, v11, v10, vcc
	v_div_scale_f32 v11, s[6:7], v10, v10, 1.0
	v_rcp_f32_e32 v34, v11
	s_nop 0
	v_fma_f32 v35, -v11, v34, 1.0
	v_fmac_f32_e32 v34, v35, v34
	v_div_scale_f32 v35, vcc, 1.0, v10, 1.0
	v_mul_f32_e32 v44, v35, v34
	v_fma_f32 v45, -v11, v44, v35
	v_fmac_f32_e32 v44, v45, v34
	v_fma_f32 v11, -v11, v44, v35
	v_div_fmas_f32 v11, v11, v34, v44
	v_div_fixup_f32 v34, v11, v10, 1.0
	v_pk_mul_f32 v[48:49], v[40:41], v[34:35] op_sel_hi:[1,0]
	v_pk_mul_f32 v[50:51], v[42:43], v[34:35] op_sel_hi:[1,0]
	v_add_u32_e32 v35, s5, v0
	ds_read_b128 v[40:43], v35
	ds_read_b128 v[44:47], v35 offset:40960
	v_lshl_add_u64 v[10:11], s[12:13], 1, v[2:3]
	v_lshl_add_u64 v[10:11], v[10:11], 0, v[6:7]
	v_pk_mul_f32 v[4:5], v[4:5], v[34:35] op_sel_hi:[1,0]
	v_pk_mul_f32 v[14:15], v[14:15], v[34:35] op_sel_hi:[1,0]
	s_waitcnt lgkmcnt(0)
; #define GAS __attribute__((address_space(1)))
; __device__ __forceinline__ unsigned xpk2(float lo, float hi) { if (XRES_F16) { const f32x2_t v = {lo, hi}; const f16x2_t h = __builtin_convertvector(v, f16x2_t); return __builtin_bit_cast(unsigned, h); } return pk2(lo, hi); }
; __device__ __forceinline__ float xlo(unsigned w) { if (XRES_F16) { const f16x2_t h = __builtin_bit_cast(f16x2_t, w); return (float)h[0]; } return __builtin_bit_cast(float, w << 16); }
; __device__ __forceinline__ float xhi(unsigned w) { if (XRES_F16) { const f16x2_t h = __builtin_bit_cast(f16x2_t, w); return (float)h[1]; } return __builtin_bit_cast(float, w & 0xffff0000u); }
; __device__ __forceinline__ void norm_mod_phase2(const Args& a, Frame& F, const float* gain, const float* modl, int sh_off, int sc_off, int nrows, const float* slab_gate) {
;     ...
;     if (ML + nw < nrows) {
;         const int r = ML + nw, rc = nw;
;         const GAS v2u* xr = (const GAS v2u*)(X + (size_t)r * D) + F.lane;
; #pragma unroll
;         for (int j = 0; j < 8; ++j) r0[j] = xr[64 * j];
;         if (slab_gate != nullptr) { const GAS f32x4* sl = (const GAS f32x4*)((const float*)(a.ws + WS_SLAB) + (size_t)rc * D) + F.lane;
; #pragma unroll
;             for (int j = 0; j < 8; ++j) { const f32x4 p = (sl[64 * j] + sl[64 * j + (size_t)MC * D / 4]) + (sl[64 * j + 2 * ((size_t)MC * D / 4)] + sl[64 * j + 3 * ((size_t)MC * D / 4)]);
;                 const f32x4 x = (f32x4){xlo(r0[j].x), xhi(r0[j].x), xlo(r0[j].y), xhi(r0[j].y)} + *(const GAS f32x4*)(slab_gate + 256 * j + 4 * F.lane) * p;
;                 v2u w; w.x = xpk2(x[0], x[1]); w.y = xpk2(x[2], x[3]); ((GAS v2u*)(X + (size_t)r * D) + F.lane)[64 * j] = w; r0[j] = w; } }
	v_pk_fma_f32 v[42:43], v[42:43], v[50:51], v[46:47]
	v_pk_fma_f32 v[40:41], v[40:41], v[48:49], v[44:45]
	v_pk_mul_f32 v[44:45], v[36:37], v[34:35] op_sel_hi:[1,0]
	v_cvt_pk_bf16_f32 v40, v40, v41
	v_cvt_pk_bf16_f32 v41, v42, v43
	global_store_dwordx2 v[10:11], v[40:41], off
	v_pk_mul_f32 v[46:47], v[38:39], v[34:35] op_sel_hi:[1,0]
	ds_read_b128 v[36:39], v35 offset:1024
	ds_read_b128 v[40:43], v35 offset:41984
	s_waitcnt lgkmcnt(0)
	v_pk_fma_f32 v[38:39], v[38:39], v[46:47], v[42:43]
	v_pk_fma_f32 v[36:37], v[36:37], v[44:45], v[40:41]
	v_pk_mul_f32 v[40:41], v[26:27], v[34:35] op_sel_hi:[1,0]
	v_cvt_pk_bf16_f32 v36, v36, v37
	v_cvt_pk_bf16_f32 v37, v38, v39
	global_store_dwordx2 v[10:11], v[36:37], off offset:512
	v_pk_mul_f32 v[42:43], v[28:29], v[34:35] op_sel_hi:[1,0]
	ds_read_b128 v[26:29], v35 offset:2048
	ds_read_b128 v[36:39], v35 offset:43008
	s_waitcnt lgkmcnt(0)
	v_pk_fma_f32 v[28:29], v[28:29], v[42:43], v[38:39]
	v_pk_fma_f32 v[26:27], v[26:27], v[40:41], v[36:37]
	v_pk_mul_f32 v[36:37], v[30:31], v[34:35] op_sel_hi:[1,0]
	v_cvt_pk_bf16_f32 v26, v26, v27
	v_cvt_pk_bf16_f32 v27, v28, v29
	global_store_dwordx2 v[10:11], v[26:27], off offset:1024
	v_pk_mul_f32 v[38:39], v[32:33], v[34:35] op_sel_hi:[1,0]
	ds_read_b128 v[26:29], v35 offset:3072
	ds_read_b128 v[30:33], v35 offset:44032
	s_waitcnt lgkmcnt(0)
	v_pk_fma_f32 v[28:29], v[38:39], v[28:29], v[32:33]
	v_pk_fma_f32 v[26:27], v[36:37], v[26:27], v[30:31]
	v_pk_mul_f32 v[30:31], v[18:19], v[34:35] op_sel_hi:[1,0]
	v_cvt_pk_bf16_f32 v26, v26, v27
	v_cvt_pk_bf16_f32 v27, v28, v29
	global_store_dwordx2 v[10:11], v[26:27], off offset:1536
	v_pk_mul_f32 v[32:33], v[20:21], v[34:35] op_sel_hi:[1,0]
	ds_read_b128 v[18:21], v35 offset:4096
	ds_read_b128 v[26:29], v35 offset:45056
	s_waitcnt lgkmcnt(0)
	v_pk_fma_f32 v[20:21], v[32:33], v[20:21], v[28:29]
	v_pk_fma_f32 v[18:19], v[30:31], v[18:19], v[26:27]
	v_pk_mul_f32 v[26:27], v[22:23], v[34:35] op_sel_hi:[1,0]
	v_cvt_pk_bf16_f32 v18, v18, v19
	v_cvt_pk_bf16_f32 v19, v20, v21
	global_store_dwordx2 v[10:11], v[18:19], off offset:2048
	v_pk_mul_f32 v[28:29], v[24:25], v[34:35] op_sel_hi:[1,0]
	ds_read_b128 v[18:21], v35 offset:5120
	ds_read_b128 v[22:25], v35 offset:46080
	s_waitcnt lgkmcnt(0)
	v_pk_fma_f32 v[20:21], v[28:29], v[20:21], v[24:25]
	v_pk_fma_f32 v[18:19], v[26:27], v[18:19], v[22:23]
	s_nop 0
	v_cvt_pk_bf16_f32 v18, v18, v19
	v_cvt_pk_bf16_f32 v19, v20, v21
	global_store_dwordx2 v[10:11], v[18:19], off offset:2560
	ds_read_b128 v[18:21], v35 offset:6144
	ds_read_b128 v[22:25], v35 offset:47104
	s_waitcnt lgkmcnt(0)
	v_pk_fma_f32 v[14:15], v[14:15], v[20:21], v[24:25]
	v_pk_fma_f32 v[4:5], v[4:5], v[18:19], v[22:23]
	v_pk_mul_f32 v[20:21], v[16:17], v[34:35] op_sel_hi:[1,0]
	v_cvt_pk_bf16_f32 v4, v4, v5
	v_cvt_pk_bf16_f32 v5, v14, v15
	global_store_dwordx2 v[10:11], v[4:5], off offset:3072
	v_pk_mul_f32 v[4:5], v[12:13], v[34:35] op_sel_hi:[1,0]
	ds_read_b128 v[12:15], v35 offset:7168
	ds_read_b128 v[16:19], v35 offset:48128
	s_waitcnt lgkmcnt(0)
	v_pk_fma_f32 v[14:15], v[20:21], v[14:15], v[18:19]
	v_pk_fma_f32 v[4:5], v[4:5], v[12:13], v[16:17]
	s_nop 0
	v_cvt_pk_bf16_f32 v4, v4, v5
	v_cvt_pk_bf16_f32 v5, v14, v15
	global_store_dwordx2 v[10:11], v[4:5], off offset:3584
	s_cbranch_scc0 .LBB0_223
	s_lshr_b32 s4, s4, 1
	s_addk_i32 s4, 0x4000
	s_ashr_i32 s5, s4, 31
	s_lshl_b64 s[6:7], s[4:5], 12
	v_lshl_add_u64 v[4:5], v[8:9], 0, s[6:7]
	v_lshl_add_u64 v[18:19], v[4:5], 0, v[6:7]
	global_load_dwordx2 v[22:23], v[18:19], off
	global_load_dwordx2 v[20:21], v[18:19], off offset:512
	global_load_dwordx2 v[16:17], v[18:19], off offset:1024
	global_load_dwordx2 v[12:13], v[18:19], off offset:1536
	global_load_dwordx2 v[14:15], v[18:19], off offset:2048
	global_load_dwordx2 v[10:11], v[18:19], off offset:2560
	global_load_dwordx2 v[8:9], v[18:19], off offset:3072
	global_load_dwordx2 v[4:5], v[18:19], off offset:3584
	v_lshlrev_b32_e32 v40, 2, v143
	s_cmp_eq_u32 s76, 0
	s_cbranch_scc1 .LBB0_222
	s_sub_i32 s6, s4, 0x4000
	s_lshl_b32 s6, s6, 11
	s_mov_b32 s7, 0
	v_mov_b32_e32 v24, s72
	v_mov_b32_e32 v25, s73
	v_lshl_add_u64 v[24:25], s[6:7], 2, v[24:25]
	v_lshl_add_u64 v[24:25], v[24:25], 0, v[0:1]
	v_lshlrev_b32_e32 v0, 2, v40
	v_lshl_add_u64 v[26:27], s[86:87], 0, v[0:1]
	v_add_co_u32_e32 v28, vcc, 0x58400000, v24
	s_nop 1
	v_addc_co_u32_e32 v29, vcc, 0, v25, vcc
	v_add_co_u32_e32 v30, vcc, 0x58c00000, v24
	s_nop 1
	v_addc_co_u32_e32 v31, vcc, 0, v25, vcc
	v_add_co_u32_e32 v32, vcc, 0x59400000, v24
	s_nop 1
	v_addc_co_u32_e32 v33, vcc, 0, v25, vcc
	v_add_co_u32_e32 v34, vcc, 0x59c00000, v24
	s_nop 1
	v_addc_co_u32_e32 v35, vcc, 0, v25, vcc
	v_add_co_u32_e32 v36, vcc, 0x58401000, v24
	s_nop 1
	v_addc_co_u32_e32 v37, vcc, 0, v25, vcc
	v_add_co_u32_e32 v38, vcc, 0x58c01000, v24
	s_nop 1
	v_addc_co_u32_e32 v39, vcc, 0, v25, vcc
	v_add_co_u32_e32 v42, vcc, 0x59401000, v24
	s_nop 1
	v_addc_co_u32_e32 v43, vcc, 0, v25, vcc
	v_add_co_u32_e32 v44, vcc, 0x59c01000, v24
	s_nop 1
	v_addc_co_u32_e32 v45, vcc, 0, v25, vcc
	v_add_co_u32_e32 v48, vcc, 0xffffe000, v26
	s_nop 1
	v_addc_co_u32_e32 v49, vcc, -1, v27, vcc
	v_add_co_u32_e32 v50, vcc, 0xfffff000, v26
	s_nop 1
	v_addc_co_u32_e32 v51, vcc, -1, v27, vcc
	global_load_dwordx4 v[94:97], v[28:29], off
	global_load_dwordx4 v[98:101], v[30:31], off
	global_load_dwordx4 v[102:105], v[32:33], off
	global_load_dwordx4 v[106:109], v[34:35], off
	global_load_dwordx4 v[110:113], v[48:49], off
	global_load_dwordx4 v[114:117], v[28:29], off offset:1024
	global_load_dwordx4 v[118:121], v[30:31], off offset:1024
	global_load_dwordx4 v[122:125], v[32:33], off offset:1024
	global_load_dwordx4 v[126:129], v[34:35], off offset:1024
	global_load_dwordx4 v[130:133], v[48:49], off offset:1024
	global_load_dwordx4 v[134:137], v[28:29], off offset:2048
	global_load_dwordx4 v[138:141], v[30:31], off offset:2048
	global_load_dwordx4 v[142:145], v[32:33], off offset:2048
	global_load_dwordx4 v[146:149], v[34:35], off offset:2048
	global_load_dwordx4 v[150:153], v[48:49], off offset:2048
	global_load_dwordx4 v[154:157], v[28:29], off offset:3072
	global_load_dwordx4 v[158:161], v[30:31], off offset:3072
	global_load_dwordx4 v[162:165], v[32:33], off offset:3072
	global_load_dwordx4 v[170:173], v[34:35], off offset:3072
	global_load_dwordx4 v[174:177], v[48:49], off offset:3072
	s_waitcnt vmcnt(15)
; #define GAS __attribute__((address_space(1)))
; __device__ __forceinline__ unsigned xpk2(float lo, float hi) { if (XRES_F16) { const f32x2_t v = {lo, hi}; const f16x2_t h = __builtin_convertvector(v, f16x2_t); return __builtin_bit_cast(unsigned, h); } return pk2(lo, hi); }
; __device__ __forceinline__ float xlo(unsigned w) { if (XRES_F16) { const f16x2_t h = __builtin_bit_cast(f16x2_t, w); return (float)h[0]; } return __builtin_bit_cast(float, w << 16); }
; __device__ __forceinline__ float xhi(unsigned w) { if (XRES_F16) { const f16x2_t h = __builtin_bit_cast(f16x2_t, w); return (float)h[1]; } return __builtin_bit_cast(float, w & 0xffff0000u); }
; __device__ __forceinline__ void norm_mod_phase2(const Args& a, Frame& F, const float* gain, const float* modl, int sh_off, int sc_off, int nrows, const float* slab_gate) {
;     ...
;         if (slab_gate != nullptr) { const GAS f32x4* sl = (const GAS f32x4*)((const float*)(a.ws + WS_SLAB) + (size_t)rc * D) + F.lane;
; #pragma unroll
;             for (int j = 0; j < 8; ++j) { const f32x4 p = (sl[64 * j] + sl[64 * j + (size_t)MC * D / 4]) + (sl[64 * j + 2 * ((size_t)MC * D / 4)] + sl[64 * j + 3 * ((size_t)MC * D / 4)]);
;                 const f32x4 x = (f32x4){xlo(r0[j].x), xhi(r0[j].x), xlo(r0[j].y), xhi(r0[j].y)} + *(const GAS f32x4*)(slab_gate + 256 * j + 4 * F.lane) * p;
;                 v2u w; w.x = xpk2(x[0], x[1]); w.y = xpk2(x[2], x[3]); ((GAS v2u*)(X + (size_t)r * D) + F.lane)[64 * j] = w; r0[j] = w; } }
	v_pk_add_f32 v[220:221], v[94:95], v[98:99]
	v_pk_add_f32 v[222:223], v[96:97], v[100:101]
	v_pk_add_f32 v[224:225], v[102:103], v[106:107]
	v_pk_add_f32 v[226:227], v[104:105], v[108:109]
	v_cvt_f32_f16_e32 v232, v22
	v_cvt_f32_f16_sdwa v233, v22 dst_sel:DWORD dst_unused:UNUSED_PAD src0_sel:WORD_1
	v_cvt_f32_f16_e32 v234, v23
	v_cvt_f32_f16_sdwa v235, v23 dst_sel:DWORD dst_unused:UNUSED_PAD src0_sel:WORD_1
	v_pk_add_f32 v[228:229], v[220:221], v[224:225]
	v_pk_add_f32 v[230:231], v[222:223], v[226:227]
	s_nop 1
	v_pk_fma_f32 v[236:237], v[110:111], v[228:229], v[232:233]
	v_pk_fma_f32 v[238:239], v[112:113], v[230:231], v[234:235]
	s_nop 1
	v_cvt_pk_f16_f32 v22, v236, v237
	v_cvt_pk_f16_f32 v23, v238, v239
	global_store_dwordx2 v[18:19], v[22:23], off
	global_load_dwordx4 v[94:97], v[36:37], off
	global_load_dwordx4 v[98:101], v[38:39], off
	global_load_dwordx4 v[102:105], v[42:43], off
	global_load_dwordx4 v[106:109], v[44:45], off
	global_load_dwordx4 v[110:113], v[50:51], off
	s_waitcnt vmcnt(16)
	v_pk_add_f32 v[220:221], v[114:115], v[118:119]
	v_pk_add_f32 v[222:223], v[116:117], v[120:121]
	v_pk_add_f32 v[224:225], v[122:123], v[126:127]
	v_pk_add_f32 v[226:227], v[124:125], v[128:129]
	v_cvt_f32_f16_e32 v232, v20
	v_cvt_f32_f16_sdwa v233, v20 dst_sel:DWORD dst_unused:UNUSED_PAD src0_sel:WORD_1
	v_cvt_f32_f16_e32 v234, v21
	v_cvt_f32_f16_sdwa v235, v21 dst_sel:DWORD dst_unused:UNUSED_PAD src0_sel:WORD_1
	v_pk_add_f32 v[228:229], v[220:221], v[224:225]
	v_pk_add_f32 v[230:231], v[222:223], v[226:227]
	s_nop 1
	v_pk_fma_f32 v[236:237], v[130:131], v[228:229], v[232:233]
	v_pk_fma_f32 v[238:239], v[132:133], v[230:231], v[234:235]
	s_nop 1
	v_cvt_pk_f16_f32 v20, v236, v237
	v_cvt_pk_f16_f32 v21, v238, v239
	global_store_dwordx2 v[18:19], v[20:21], off offset:512
	global_load_dwordx4 v[114:117], v[36:37], off offset:1024
	global_load_dwordx4 v[118:121], v[38:39], off offset:1024
	global_load_dwordx4 v[122:125], v[42:43], off offset:1024
	global_load_dwordx4 v[126:129], v[44:45], off offset:1024
	global_load_dwordx4 v[130:133], v[50:51], off offset:1024
	s_waitcnt vmcnt(17)
	v_pk_add_f32 v[220:221], v[134:135], v[138:139]
	v_pk_add_f32 v[222:223], v[136:137], v[140:141]
	v_pk_add_f32 v[224:225], v[142:143], v[146:147]
	v_pk_add_f32 v[226:227], v[144:145], v[148:149]
	v_cvt_f32_f16_e32 v232, v16
	v_cvt_f32_f16_sdwa v233, v16 dst_sel:DWORD dst_unused:UNUSED_PAD src0_sel:WORD_1
	v_cvt_f32_f16_e32 v234, v17
	v_cvt_f32_f16_sdwa v235, v17 dst_sel:DWORD dst_unused:UNUSED_PAD src0_sel:WORD_1
	v_pk_add_f32 v[228:229], v[220:221], v[224:225]
	v_pk_add_f32 v[230:231], v[222:223], v[226:227]
	s_nop 1
	v_pk_fma_f32 v[236:237], v[150:151], v[228:229], v[232:233]
	v_pk_fma_f32 v[238:239], v[152:153], v[230:231], v[234:235]
	s_nop 1
	v_cvt_pk_f16_f32 v16, v236, v237
	v_cvt_pk_f16_f32 v17, v238, v239
	global_store_dwordx2 v[18:19], v[16:17], off offset:1024
	global_load_dwordx4 v[134:137], v[36:37], off offset:2048
	global_load_dwordx4 v[138:141], v[38:39], off offset:2048
	global_load_dwordx4 v[142:145], v[42:43], off offset:2048
	global_load_dwordx4 v[146:149], v[44:45], off offset:2048
	global_load_dwordx4 v[150:153], v[50:51], off offset:2048
	s_waitcnt vmcnt(18)
; #define GAS __attribute__((address_space(1)))
; __device__ __forceinline__ unsigned xpk2(float lo, float hi) { if (XRES_F16) { const f32x2_t v = {lo, hi}; const f16x2_t h = __builtin_convertvector(v, f16x2_t); return __builtin_bit_cast(unsigned, h); } return pk2(lo, hi); }
; __device__ __forceinline__ float xlo(unsigned w) { if (XRES_F16) { const f16x2_t h = __builtin_bit_cast(f16x2_t, w); return (float)h[0]; } return __builtin_bit_cast(float, w << 16); }
; __device__ __forceinline__ float xhi(unsigned w) { if (XRES_F16) { const f16x2_t h = __builtin_bit_cast(f16x2_t, w); return (float)h[1]; } return __builtin_bit_cast(float, w & 0xffff0000u); }
; __device__ __forceinline__ void norm_mod_phase2(const Args& a, Frame& F, const float* gain, const float* modl, int sh_off, int sc_off, int nrows, const float* slab_gate) {
;     ...
;         if (slab_gate != nullptr) { const GAS f32x4* sl = (const GAS f32x4*)((const float*)(a.ws + WS_SLAB) + (size_t)rc * D) + F.lane;
; #pragma unroll
;             for (int j = 0; j < 8; ++j) { const f32x4 p = (sl[64 * j] + sl[64 * j + (size_t)MC * D / 4]) + (sl[64 * j + 2 * ((size_t)MC * D / 4)] + sl[64 * j + 3 * ((size_t)MC * D / 4)]);
;                 const f32x4 x = (f32x4){xlo(r0[j].x), xhi(r0[j].x), xlo(r0[j].y), xhi(r0[j].y)} + *(const GAS f32x4*)(slab_gate + 256 * j + 4 * F.lane) * p;
;                 v2u w; w.x = xpk2(x[0], x[1]); w.y = xpk2(x[2], x[3]); ((GAS v2u*)(X + (size_t)r * D) + F.lane)[64 * j] = w; r0[j] = w; } }
	v_pk_add_f32 v[220:221], v[154:155], v[158:159]
	v_pk_add_f32 v[222:223], v[156:157], v[160:161]
	v_pk_add_f32 v[224:225], v[162:163], v[170:171]
	v_pk_add_f32 v[226:227], v[164:165], v[172:173]
	v_cvt_f32_f16_e32 v232, v12
	v_cvt_f32_f16_sdwa v233, v12 dst_sel:DWORD dst_unused:UNUSED_PAD src0_sel:WORD_1
	v_cvt_f32_f16_e32 v234, v13
	v_cvt_f32_f16_sdwa v235, v13 dst_sel:DWORD dst_unused:UNUSED_PAD src0_sel:WORD_1
	v_pk_add_f32 v[228:229], v[220:221], v[224:225]
	v_pk_add_f32 v[230:231], v[222:223], v[226:227]
	s_nop 1
	v_pk_fma_f32 v[236:237], v[174:175], v[228:229], v[232:233]
	v_pk_fma_f32 v[238:239], v[176:177], v[230:231], v[234:235]
	s_nop 1
	v_cvt_pk_f16_f32 v12, v236, v237
	v_cvt_pk_f16_f32 v13, v238, v239
	global_store_dwordx2 v[18:19], v[12:13], off offset:1536
	global_load_dwordx4 v[154:157], v[36:37], off offset:3072
	global_load_dwordx4 v[158:161], v[38:39], off offset:3072
	global_load_dwordx4 v[162:165], v[42:43], off offset:3072
	global_load_dwordx4 v[170:173], v[44:45], off offset:3072
	global_load_dwordx4 v[174:177], v[50:51], off offset:3072
	s_waitcnt vmcnt(18)
	v_pk_add_f32 v[220:221], v[94:95], v[98:99]
	v_pk_add_f32 v[222:223], v[96:97], v[100:101]
	v_pk_add_f32 v[224:225], v[102:103], v[106:107]
	v_pk_add_f32 v[226:227], v[104:105], v[108:109]
	v_cvt_f32_f16_e32 v232, v14
	v_cvt_f32_f16_sdwa v233, v14 dst_sel:DWORD dst_unused:UNUSED_PAD src0_sel:WORD_1
	v_cvt_f32_f16_e32 v234, v15
	v_cvt_f32_f16_sdwa v235, v15 dst_sel:DWORD dst_unused:UNUSED_PAD src0_sel:WORD_1
	v_pk_add_f32 v[228:229], v[220:221], v[224:225]
	v_pk_add_f32 v[230:231], v[222:223], v[226:227]
	s_nop 1
	v_pk_fma_f32 v[236:237], v[110:111], v[228:229], v[232:233]
	v_pk_fma_f32 v[238:239], v[112:113], v[230:231], v[234:235]
	s_nop 1
	v_cvt_pk_f16_f32 v14, v236, v237
	v_cvt_pk_f16_f32 v15, v238, v239
	global_store_dwordx2 v[18:19], v[14:15], off offset:2048
	s_waitcnt vmcnt(13)
	v_pk_add_f32 v[220:221], v[114:115], v[118:119]
	v_pk_add_f32 v[222:223], v[116:117], v[120:121]
	v_pk_add_f32 v[224:225], v[122:123], v[126:127]
	v_pk_add_f32 v[226:227], v[124:125], v[128:129]
	v_cvt_f32_f16_e32 v232, v10
	v_cvt_f32_f16_sdwa v233, v10 dst_sel:DWORD dst_unused:UNUSED_PAD src0_sel:WORD_1
	v_cvt_f32_f16_e32 v234, v11
	v_cvt_f32_f16_sdwa v235, v11 dst_sel:DWORD dst_unused:UNUSED_PAD src0_sel:WORD_1
	v_pk_add_f32 v[228:229], v[220:221], v[224:225]
	v_pk_add_f32 v[230:231], v[222:223], v[226:227]
	s_nop 1
	v_pk_fma_f32 v[236:237], v[130:131], v[228:229], v[232:233]
	v_pk_fma_f32 v[238:239], v[132:133], v[230:231], v[234:235]
	s_nop 1
	v_cvt_pk_f16_f32 v10, v236, v237
	v_cvt_pk_f16_f32 v11, v238, v239
	global_store_dwordx2 v[18:19], v[10:11], off offset:2560
	s_waitcnt vmcnt(8)
	v_pk_add_f32 v[220:221], v[134:135], v[138:139]
	v_pk_add_f32 v[222:223], v[136:137], v[140:141]
	v_pk_add_f32 v[224:225], v[142:143], v[146:147]
	v_pk_add_f32 v[226:227], v[144:145], v[148:149]
	v_cvt_f32_f16_e32 v232, v8
	v_cvt_f32_f16_sdwa v233, v8 dst_sel:DWORD dst_unused:UNUSED_PAD src0_sel:WORD_1
	v_cvt_f32_f16_e32 v234, v9
	v_cvt_f32_f16_sdwa v235, v9 dst_sel:DWORD dst_unused:UNUSED_PAD src0_sel:WORD_1
	v_pk_add_f32 v[228:229], v[220:221], v[224:225]
	v_pk_add_f32 v[230:231], v[222:223], v[226:227]
	s_nop 1
	v_pk_fma_f32 v[236:237], v[150:151], v[228:229], v[232:233]
	v_pk_fma_f32 v[238:239], v[152:153], v[230:231], v[234:235]
	s_nop 1
	v_cvt_pk_f16_f32 v8, v236, v237
	v_cvt_pk_f16_f32 v9, v238, v239
	global_store_dwordx2 v[18:19], v[8:9], off offset:3072
	s_waitcnt vmcnt(3)
	v_pk_add_f32 v[220:221], v[154:155], v[158:159]
	v_pk_add_f32 v[222:223], v[156:157], v[160:161]
	v_pk_add_f32 v[224:225], v[162:163], v[170:171]
	v_pk_add_f32 v[226:227], v[164:165], v[172:173]
	v_cvt_f32_f16_e32 v232, v4
	v_cvt_f32_f16_sdwa v233, v4 dst_sel:DWORD dst_unused:UNUSED_PAD src0_sel:WORD_1
	v_cvt_f32_f16_e32 v234, v5
	v_cvt_f32_f16_sdwa v235, v5 dst_sel:DWORD dst_unused:UNUSED_PAD src0_sel:WORD_1
	v_pk_add_f32 v[228:229], v[220:221], v[224:225]
	v_pk_add_f32 v[230:231], v[222:223], v[226:227]
	s_nop 1
	v_pk_fma_f32 v[236:237], v[174:175], v[228:229], v[232:233]
	v_pk_fma_f32 v[238:239], v[176:177], v[230:231], v[234:235]
	s_nop 1
	v_cvt_pk_f16_f32 v4, v236, v237
	v_cvt_pk_f16_f32 v5, v238, v239
	global_store_dwordx2 v[18:19], v[4:5], off offset:3584

; #define GAS __attribute__((address_space(1)))
; #define LAS __attribute__((address_space(3)))
; #define NR_LOAD(dst, k_) do { const GAS v2u* xr_ = (const GAS v2u*)(X + (size_t)(nw + 2048 * (k_)) * D) + F.lane; \
;         _Pragma("unroll") for (int j = 0; j < 8; ++j) dst[j] = __builtin_nontemporal_load(xr_ + 64 * j); } while (0)
; __device__ __forceinline__ void norm_mod_phase2(const Args& a, Frame& F, const float* gain, const float* modl, int sh_off, int sc_off, int nrows, const float* slab_gate) {
;     ...
;     const int nw = F.vcu * NWAVES + F.wave;
;     bf16* X = (bf16*)(a.ws + WS_X); bf16* HN = (bf16*)(a.ws + WS_HN);
;     LAS float* CA = (LAS float*)F.lds; LAS float* CB = CA + 5 * D;
;     v2u r0[8], r1[8], r2[8], r3[8], r4[8], r5[8], r6[8], r7[8];
;     ...
;     NR_LOAD(r0, 0); NR_LOAD(r1, 1); NR_LOAD(r2, 2); NR_LOAD(r3, 3); NR_LOAD(r4, 4); NR_LOAD(r5, 5); NR_LOAD(r6, 6); NR_LOAD(r7, 7);
;     { const GAS f32x4* g4 = (const GAS f32x4*)gain;
;       for (int q = F.tid; q < 5 * D / 4; q += NWAVES * 64) { const int bq = q >> 9, cq = q & 511; const GAS f32x4* mb4 = (const GAS f32x4*)(modl + (size_t)bq * MOD_LD);
;           ((LAS f32x4*)CA)[q] = g4[cq] * (mb4[sc_off / 4 + cq] + 1.0f); ((LAS f32x4*)CB)[q] = mb4[sh_off / 4 + cq]; } }
.LBB0_1042:
	s_andn2_b64 vcc, exec, s[8:9]
	s_cbranch_vccnz .LBB0_1051
	s_getreg_b32 s6, hwreg(HW_REG_HW_ID, 0, 6)
	s_lshl_b32 s6, s6, 2
	s_add_i32 s6, s6, 0
	s_add_i32 s6, s6, 0x20540
	v_mov_b32_e32 v0, s6
	ds_read_b32 v0, v0
	v_mov_b64_e32 v[2:3], s[0:1]
	v_mov_b32_e32 v7, v1
	s_waitcnt lgkmcnt(0)
	v_readfirstlane_b32 s6, v0
	v_mbcnt_lo_u32_b32 v0, -1, 0
	v_mbcnt_hi_u32_b32 v0, -1, v0
	s_nop 1
	v_lshl_add_u32 v142, s6, 6, v0
	v_mov_b32_e32 v136, s72
	v_mov_b32_e32 v137, s73
	v_readfirstlane_b32 s6, v142
	s_ashr_i32 s6, s6, 6
	s_add_i32 s10, s6, s91
	s_mov_b64 s[6:7], 0x400000
	s_ashr_i32 s11, s10, 31
	v_and_b32_e32 v147, 63, v142
	s_add_i32 s78, s10, 0x800
	v_lshlrev_b32_e32 v6, 3, v147
	s_ashr_i32 s79, s78, 31
	s_add_i32 s36, s10, 0x1000
	s_ashr_i32 s37, s36, 31
	s_add_i32 s30, s10, 0x1800
	s_ashr_i32 s31, s30, 31
	s_add_i32 s26, s10, 0x2000
	s_ashr_i32 s27, s26, 31
	s_add_i32 s22, s10, 0x2800
	s_ashr_i32 s23, s22, 31
	s_add_i32 s18, s10, 0x3000
	s_ashr_i32 s19, s18, 31
	s_add_i32 s14, s10, 0x3800
	s_ashr_i32 s15, s14, 31
	s_waitcnt vmcnt(0) lgkmcnt(0)
	v_lshl_add_u64 v[8:9], v[136:137], 0, s[6:7]
	s_lshl_b64 s[6:7], s[10:11], 12
	v_lshl_add_u64 v[2:3], v[8:9], 0, s[6:7]
	v_lshl_add_u64 v[2:3], v[2:3], 0, v[6:7]
	s_lshl_b64 s[6:7], s[78:79], 12
	v_and_b32_e32 v184, 0x1ff, v142
	v_lshlrev_b32_e32 v184, 4, v184
	v_mov_b32_e32 v185, 0
	v_mov_b32_e32 v186, s76
	v_lshlrev_b32_e32 v186, 13, v186
	v_mov_b32_e32 v187, 0
	v_lshl_add_u64 v[188:189], v[74:75], 0, v[186:187]
	v_lshl_add_u64 v[188:189], v[188:189], 0, v[184:185]
	global_load_dwordx4 v[192:195], v[188:189], off
	v_add_u32_e32 v196, 0x8000, v184
	v_add_u32_e32 v201, 0x6000, v184
	v_add_u32_e32 v197, 0x14000, v184
	v_add_u32_e32 v202, 0x12000, v184
	v_add_u32_e32 v198, 0x20000, v184
	v_add_u32_e32 v203, 0x1e000, v184
	v_add_u32_e32 v199, 0x2c000, v184
	v_add_u32_e32 v204, 0x2a000, v184
	v_add_u32_e32 v200, 0x38000, v184
	v_add_u32_e32 v205, 0x36000, v184
	global_load_dwordx4 v[208:211], v196, s[86:87]
	global_load_dwordx4 v[228:231], v201, s[86:87]
	global_load_dwordx4 v[212:215], v197, s[86:87]
	global_load_dwordx4 v[232:235], v202, s[86:87]
	global_load_dwordx4 v[216:219], v198, s[86:87]
	global_load_dwordx4 v[236:239], v203, s[86:87]
	global_load_dwordx4 v[220:223], v199, s[86:87]
	global_load_dwordx4 v[240:243], v204, s[86:87]
	global_load_dwordx4 v[224:227], v200, s[86:87]
	global_load_dwordx4 v[244:247], v205, s[86:87]
	global_load_dwordx2 v[140:141], v[2:3], off nt
	global_load_dwordx2 v[138:139], v[2:3], off offset:512 nt
	global_load_dwordx2 v[134:135], v[2:3], off offset:1024 nt
	global_load_dwordx2 v[132:133], v[2:3], off offset:1536 nt
	global_load_dwordx2 v[130:131], v[2:3], off offset:2048 nt
	global_load_dwordx2 v[128:129], v[2:3], off offset:2560 nt
	global_load_dwordx2 v[126:127], v[2:3], off offset:3072 nt
	global_load_dwordx2 v[124:125], v[2:3], off offset:3584 nt
	v_lshl_add_u64 v[2:3], v[8:9], 0, s[6:7]
	v_lshl_add_u64 v[2:3], v[2:3], 0, v[6:7]
	s_lshl_b64 s[6:7], s[36:37], 12
	global_load_dwordx2 v[122:123], v[2:3], off nt
	global_load_dwordx2 v[120:121], v[2:3], off offset:512 nt
	global_load_dwordx2 v[118:119], v[2:3], off offset:1024 nt
	global_load_dwordx2 v[116:117], v[2:3], off offset:1536 nt
	global_load_dwordx2 v[114:115], v[2:3], off offset:2048 nt
	global_load_dwordx2 v[112:113], v[2:3], off offset:2560 nt
	global_load_dwordx2 v[110:111], v[2:3], off offset:3072 nt
	global_load_dwordx2 v[108:109], v[2:3], off offset:3584 nt
	v_lshl_add_u64 v[2:3], v[8:9], 0, s[6:7]
	v_lshl_add_u64 v[2:3], v[2:3], 0, v[6:7]
	s_lshl_b64 s[6:7], s[30:31], 12
	global_load_dwordx2 v[106:107], v[2:3], off nt
	global_load_dwordx2 v[104:105], v[2:3], off offset:512 nt
	global_load_dwordx2 v[102:103], v[2:3], off offset:1024 nt
	global_load_dwordx2 v[100:101], v[2:3], off offset:1536 nt
	global_load_dwordx2 v[98:99], v[2:3], off offset:2048 nt
	global_load_dwordx2 v[96:97], v[2:3], off offset:2560 nt
	global_load_dwordx2 v[94:95], v[2:3], off offset:3072 nt
	global_load_dwordx2 v[92:93], v[2:3], off offset:3584 nt
	v_lshl_add_u64 v[2:3], v[8:9], 0, s[6:7]
	v_lshl_add_u64 v[2:3], v[2:3], 0, v[6:7]
	s_lshl_b64 s[6:7], s[26:27], 12
	global_load_dwordx2 v[90:91], v[2:3], off nt
	global_load_dwordx2 v[88:89], v[2:3], off offset:512 nt
	global_load_dwordx2 v[86:87], v[2:3], off offset:1024 nt
	global_load_dwordx2 v[84:85], v[2:3], off offset:1536 nt
	global_load_dwordx2 v[82:83], v[2:3], off offset:2048 nt
	global_load_dwordx2 v[80:81], v[2:3], off offset:2560 nt
	global_load_dwordx2 v[78:79], v[2:3], off offset:3072 nt
	global_load_dwordx2 v[76:77], v[2:3], off offset:3584 nt
	v_lshl_add_u64 v[2:3], v[8:9], 0, s[6:7]
	v_lshl_add_u64 v[2:3], v[2:3], 0, v[6:7]
	s_lshl_b64 s[6:7], s[22:23], 12
	global_load_dwordx2 v[72:73], v[2:3], off nt
	global_load_dwordx2 v[70:71], v[2:3], off offset:512 nt
	global_load_dwordx2 v[68:69], v[2:3], off offset:1024 nt
	global_load_dwordx2 v[66:67], v[2:3], off offset:1536 nt
	global_load_dwordx2 v[64:65], v[2:3], off offset:2048 nt
	global_load_dwordx2 v[62:63], v[2:3], off offset:2560 nt
	global_load_dwordx2 v[60:61], v[2:3], off offset:3072 nt
	global_load_dwordx2 v[58:59], v[2:3], off offset:3584 nt
	v_lshl_add_u64 v[2:3], v[8:9], 0, s[6:7]
	v_lshl_add_u64 v[2:3], v[2:3], 0, v[6:7]
	s_lshl_b64 s[6:7], s[18:19], 12
	global_load_dwordx2 v[56:57], v[2:3], off nt
	global_load_dwordx2 v[54:55], v[2:3], off offset:512 nt
	global_load_dwordx2 v[52:53], v[2:3], off offset:1024 nt
	global_load_dwordx2 v[50:51], v[2:3], off offset:1536 nt
	global_load_dwordx2 v[48:49], v[2:3], off offset:2048 nt
	global_load_dwordx2 v[46:47], v[2:3], off offset:2560 nt
	global_load_dwordx2 v[44:45], v[2:3], off offset:3072 nt
	global_load_dwordx2 v[42:43], v[2:3], off offset:3584 nt
	v_lshl_add_u64 v[2:3], v[8:9], 0, s[6:7]
	v_lshl_add_u64 v[2:3], v[2:3], 0, v[6:7]
	s_lshl_b64 s[6:7], s[14:15], 12
	global_load_dwordx2 v[40:41], v[2:3], off nt
	global_load_dwordx2 v[38:39], v[2:3], off offset:512 nt
	global_load_dwordx2 v[36:37], v[2:3], off offset:1024 nt
	global_load_dwordx2 v[34:35], v[2:3], off offset:1536 nt
	global_load_dwordx2 v[32:33], v[2:3], off offset:2048 nt
	global_load_dwordx2 v[30:31], v[2:3], off offset:2560 nt
	global_load_dwordx2 v[28:29], v[2:3], off offset:3072 nt
	global_load_dwordx2 v[26:27], v[2:3], off offset:3584 nt
	v_lshl_add_u64 v[2:3], v[8:9], 0, s[6:7]
	v_lshl_add_u64 v[2:3], v[2:3], 0, v[6:7]
	global_load_dwordx2 v[24:25], v[2:3], off nt
	global_load_dwordx2 v[22:23], v[2:3], off offset:512 nt
	global_load_dwordx2 v[20:21], v[2:3], off offset:1024 nt
	global_load_dwordx2 v[18:19], v[2:3], off offset:1536 nt
	global_load_dwordx2 v[16:17], v[2:3], off offset:2048 nt
	global_load_dwordx2 v[14:15], v[2:3], off offset:2560 nt
	global_load_dwordx2 v[12:13], v[2:3], off offset:3072 nt
	global_load_dwordx2 v[10:11], v[2:3], off offset:3584 nt
	s_waitcnt vmcnt(62)
; #define GAS __attribute__((address_space(1)))
; #define LAS __attribute__((address_space(3)))
; #define NR_LOAD(dst, k_) do { const GAS v2u* xr_ = (const GAS v2u*)(X + (size_t)(nw + 2048 * (k_)) * D) + F.lane; \
;         _Pragma("unroll") for (int j = 0; j < 8; ++j) dst[j] = __builtin_nontemporal_load(xr_ + 64 * j); } while (0)
; __device__ __forceinline__ void norm_mod_phase2(const Args& a, Frame& F, const float* gain, const float* modl, int sh_off, int sc_off, int nrows, const float* slab_gate) {
;     ...
;     NR_LOAD(r0, 0); NR_LOAD(r1, 1); NR_LOAD(r2, 2); NR_LOAD(r3, 3); NR_LOAD(r4, 4); NR_LOAD(r5, 5); NR_LOAD(r6, 6); NR_LOAD(r7, 7);
;     { const GAS f32x4* g4 = (const GAS f32x4*)gain;
;       for (int q = F.tid; q < 5 * D / 4; q += NWAVES * 64) { const int bq = q >> 9, cq = q & 511; const GAS f32x4* mb4 = (const GAS f32x4*)(modl + (size_t)bq * MOD_LD);
;           ((LAS f32x4*)CA)[q] = g4[cq] * (mb4[sc_off / 4 + cq] + 1.0f); ((LAS f32x4*)CB)[q] = mb4[sh_off / 4 + cq]; } }
;     asm volatile("s_waitcnt lgkmcnt(0)" ::: "memory"); __builtin_amdgcn_s_barrier(); asm volatile("" ::: "memory");
	v_lshl_add_u32 v184, v142, 4, 0
	v_add_u32_e32 v185, 0xa000, v184
	v_pk_add_f32 v[210:211], v[210:211], 1.0 op_sel_hi:[1,0]
	v_pk_add_f32 v[208:209], v[208:209], 1.0 op_sel_hi:[1,0]
	v_pk_mul_f32 v[210:211], v[194:195], v[210:211]
	v_pk_mul_f32 v[208:209], v[192:193], v[208:209]
	ds_write_b128 v184, v[208:211]
	ds_write_b128 v185, v[228:231]
	v_pk_add_f32 v[214:215], v[214:215], 1.0 op_sel_hi:[1,0]
	v_pk_add_f32 v[212:213], v[212:213], 1.0 op_sel_hi:[1,0]
	v_pk_mul_f32 v[214:215], v[194:195], v[214:215]
	v_pk_mul_f32 v[212:213], v[192:193], v[212:213]
	ds_write_b128 v184, v[212:215] offset:8192
	ds_write_b128 v185, v[232:235] offset:8192
	v_pk_add_f32 v[218:219], v[218:219], 1.0 op_sel_hi:[1,0]
	v_pk_add_f32 v[216:217], v[216:217], 1.0 op_sel_hi:[1,0]
	v_pk_mul_f32 v[218:219], v[194:195], v[218:219]
	v_pk_mul_f32 v[216:217], v[192:193], v[216:217]
	ds_write_b128 v184, v[216:219] offset:16384
	ds_write_b128 v185, v[236:239] offset:16384
	v_pk_add_f32 v[222:223], v[222:223], 1.0 op_sel_hi:[1,0]
	v_pk_add_f32 v[220:221], v[220:221], 1.0 op_sel_hi:[1,0]
	v_pk_mul_f32 v[222:223], v[194:195], v[222:223]
	v_pk_mul_f32 v[220:221], v[192:193], v[220:221]
	ds_write_b128 v184, v[220:223] offset:24576
	ds_write_b128 v185, v[240:243] offset:24576
	v_pk_add_f32 v[226:227], v[226:227], 1.0 op_sel_hi:[1,0]
	v_pk_add_f32 v[224:225], v[224:225], 1.0 op_sel_hi:[1,0]
	v_pk_mul_f32 v[226:227], v[194:195], v[226:227]
	v_pk_mul_f32 v[224:225], v[192:193], v[224:225]
	ds_write_b128 v184, v[224:227] offset:32768
	ds_write_b128 v185, v[244:247] offset:32768
	s_waitcnt vmcnt(62)
	v_cvt_f32_f16_sdwa v153, v140 dst_sel:DWORD dst_unused:UNUSED_PAD src0_sel:WORD_1
	v_cvt_f32_f16_sdwa v149, v138 dst_sel:DWORD dst_unused:UNUSED_PAD src0_sel:WORD_1
	v_cvt_f32_f16_e32 v152, v140
	v_cvt_f32_f16_sdwa v155, v141 dst_sel:DWORD dst_unused:UNUSED_PAD src0_sel:WORD_1
	v_cvt_f32_f16_e32 v148, v138
	v_cvt_f32_f16_sdwa v151, v139 dst_sel:DWORD dst_unused:UNUSED_PAD src0_sel:WORD_1
	v_cvt_f32_f16_e32 v154, v141
	v_cvt_f32_f16_e32 v150, v139
	s_waitcnt vmcnt(61)
	v_cvt_f32_f16_sdwa v139, v134 dst_sel:DWORD dst_unused:UNUSED_PAD src0_sel:WORD_1
	v_cvt_f32_f16_sdwa v141, v135 dst_sel:DWORD dst_unused:UNUSED_PAD src0_sel:WORD_1
	s_mov_b64 s[6:7], 0x8c00000
	v_mov_b32_e32 v74, v153
	v_mov_b32_e32 v75, v149
	v_cvt_f32_f16_e32 v138, v134
	v_cvt_f32_f16_e32 v140, v135
	v_lshl_add_u64 v[2:3], v[136:137], 0, s[6:7]
	v_mov_b32_e32 v4, v152
	v_mov_b32_e32 v5, v148
	v_pk_mul_f32 v[74:75], v[74:75], v[74:75]
	v_mov_b32_e32 v136, v155
	v_mov_b32_e32 v137, v151
	v_pk_fma_f32 v[4:5], v[4:5], v[4:5], v[74:75]
	v_mov_b32_e32 v74, v154
	v_mov_b32_e32 v75, v150
	v_pk_mul_f32 v[136:137], v[136:137], v[136:137]
	v_mov_b32_e32 v134, v139
	v_pk_fma_f32 v[74:75], v[74:75], v[74:75], v[136:137]
	v_mov_b32_e32 v135, v141
	s_waitcnt vmcnt(60)
	v_cvt_f32_f16_sdwa v143, v132 dst_sel:DWORD dst_unused:UNUSED_PAD src0_sel:WORD_1
	v_pk_add_f32 v[4:5], v[4:5], v[74:75]
	v_mov_b32_e32 v74, v138
	v_mov_b32_e32 v75, v140
	v_pk_mul_f32 v[134:135], v[134:135], v[134:135]
	v_cvt_f32_f16_e32 v142, v132
	v_cvt_f32_f16_sdwa v145, v133 dst_sel:DWORD dst_unused:UNUSED_PAD src0_sel:WORD_1
	v_pk_fma_f32 v[74:75], v[74:75], v[74:75], v[134:135]
	v_cvt_f32_f16_e32 v144, v133
	s_waitcnt vmcnt(59)
	v_cvt_f32_f16_sdwa v133, v130 dst_sel:DWORD dst_unused:UNUSED_PAD src0_sel:WORD_1
	v_cvt_f32_f16_e32 v132, v130
	v_cvt_f32_f16_sdwa v135, v131 dst_sel:DWORD dst_unused:UNUSED_PAD src0_sel:WORD_1
	v_cvt_f32_f16_e32 v134, v131
	v_mul_f32_e32 v0, v143, v143
	v_pk_fma_f32 v[136:137], v[142:143], v[142:143], v[0:1] op_sel_hi:[1,1,0]
	v_mul_f32_e32 v0, v145, v145
	v_pk_add_f32 v[4:5], v[4:5], v[4:5] op_sel:[0,1] op_sel_hi:[1,0]
	v_pk_add_f32 v[74:75], v[74:75], v[74:75] op_sel:[0,1] op_sel_hi:[1,0]
	v_pk_fma_f32 v[156:157], v[144:145], v[144:145], v[0:1] op_sel_hi:[1,1,0]
	v_pk_mul_f32 v[130:131], v[132:133], v[132:133]
	v_pk_mul_f32 v[158:159], v[134:135], v[134:135]
	v_mov_b32_e32 v5, v130
	v_mov_b32_e32 v75, v131
	v_mov_b32_e32 v137, v158
	v_mov_b32_e32 v157, v159
	v_pk_add_f32 v[4:5], v[4:5], v[74:75]
	v_pk_add_f32 v[74:75], v[136:137], v[156:157]
	s_waitcnt vmcnt(58)
	v_cvt_f32_f16_sdwa v131, v128 dst_sel:DWORD dst_unused:UNUSED_PAD src0_sel:WORD_1
	v_cvt_f32_f16_sdwa v137, v129 dst_sel:DWORD dst_unused:UNUSED_PAD src0_sel:WORD_1
	v_cvt_f32_f16_e32 v130, v128
	v_cvt_f32_f16_e32 v136, v129
	v_pk_add_f32 v[4:5], v[4:5], v[74:75]
	v_mov_b32_e32 v74, v131
	v_mov_b32_e32 v75, v137
	v_pk_add_f32 v[156:157], v[4:5], v[4:5] op_sel:[0,1] op_sel_hi:[1,0]
	v_mov_b32_e32 v4, v130
	v_mov_b32_e32 v5, v136
	v_pk_mul_f32 v[74:75], v[74:75], v[74:75]
	s_waitcnt vmcnt(57)
	v_cvt_f32_f16_sdwa v129, v127 dst_sel:DWORD dst_unused:UNUSED_PAD src0_sel:WORD_1
	v_pk_fma_f32 v[4:5], v[4:5], v[4:5], v[74:75]
	v_cvt_f32_f16_e32 v128, v127
	v_pk_add_f32 v[158:159], v[4:5], v[4:5] op_sel:[0,1] op_sel_hi:[1,0]
	v_cvt_f32_f16_sdwa v5, v126 dst_sel:DWORD dst_unused:UNUSED_PAD src0_sel:WORD_1
	v_cvt_f32_f16_e32 v4, v126
	s_waitcnt vmcnt(56)
	v_cvt_f32_f16_sdwa v75, v124 dst_sel:DWORD dst_unused:UNUSED_PAD src0_sel:WORD_1
	v_cvt_f32_f16_e32 v74, v124
	v_cvt_f32_f16_sdwa v127, v125 dst_sel:DWORD dst_unused:UNUSED_PAD src0_sel:WORD_1
	v_cvt_f32_f16_e32 v126, v125
	v_mul_f32_e32 v0, v5, v5
	v_pk_fma_f32 v[160:161], v[4:5], v[4:5], v[0:1] op_sel_hi:[1,1,0]
	v_mul_f32_e32 v0, v129, v129
	v_pk_fma_f32 v[162:163], v[128:129], v[128:129], v[0:1] op_sel_hi:[1,1,0]
	v_pk_mul_f32 v[124:125], v[74:75], v[74:75]
	v_pk_mul_f32 v[164:165], v[126:127], v[126:127]
	v_mov_b32_e32 v157, v124
	v_mov_b32_e32 v159, v125
	v_mov_b32_e32 v161, v164
	v_mov_b32_e32 v163, v165
	v_pk_add_f32 v[124:125], v[156:157], v[158:159]
	v_pk_add_f32 v[156:157], v[160:161], v[162:163]
	s_waitcnt lgkmcnt(0)
	s_barrier
; __device__ __forceinline__ void norm_mod_phase2(const Args& a, Frame& F, const float* gain, const float* modl, int sh_off, int sc_off, int nrows, const float* slab_gate) {
;     ...
;     NR_FINISH(r0, nw,            (nw) >> 12);
	v_pk_add_f32 v[124:125], v[124:125], v[156:157]
	s_lshl_b64 s[12:13], s[10:11], 11
	v_add_f32_e32 v0, v124, v125
	s_lshl_b64 s[48:49], s[78:79], 11
	s_lshl_b64 s[40:41], s[36:37], 11
	v_add_f32_dpp v0, v0, v0 quad_perm:[1,0,3,2] row_mask:0xf bank_mask:0xf bound_ctrl:1
	s_lshl_b64 s[34:35], s[30:31], 11
	s_lshl_b64 s[28:29], s[26:27], 11
	v_add_f32_dpp v0, v0, v0 quad_perm:[2,3,0,1] row_mask:0xf bank_mask:0xf bound_ctrl:1
	s_lshl_b64 s[24:25], s[22:23], 11
	s_lshl_b64 s[20:21], s[18:19], 11
	v_add_f32_dpp v0, v0, v0 row_half_mirror row_mask:0xf bank_mask:0xf bound_ctrl:1
	s_lshl_b64 s[16:17], s[14:15], 11
	s_nop 0
	v_add_f32_dpp v0, v0, v0 row_mirror row_mask:0xf bank_mask:0xf bound_ctrl:1
	s_nop 0
	v_readlane_b32 s8, v0, 16
	v_readlane_b32 s9, v0, 48
	v_readlane_b32 s6, v0, 0
	v_readlane_b32 s7, v0, 32
	v_mov_b32_e32 v124, s8
	v_mov_b32_e32 v125, s9
	v_pk_add_f32 v[124:125], s[6:7], v[124:125]
	s_nop 0
	v_add_f32_e32 v0, v124, v125
	v_fmamk_f32 v0, v0, 0x3a000000, v252
	v_cmp_gt_f32_e32 vcc, s55, v0
	v_mul_f32_e32 v7, 0x4f800000, v0
	s_nop 0
	v_cndmask_b32_e32 v0, v0, v7, vcc
	v_sqrt_f32_e32 v7, v0
	s_nop 0
	v_add_u32_e32 v124, -1, v7
	v_fma_f32 v125, -v124, v7, v0
	v_cmp_ge_f32_e64 s[8:9], 0, v125
	v_add_u32_e32 v125, 1, v7
	s_nop 0
	v_cndmask_b32_e64 v124, v7, v124, s[8:9]
	v_fma_f32 v7, -v125, v7, v0
	v_cmp_lt_f32_e64 s[8:9], 0, v7
	s_nop 1
	v_cndmask_b32_e64 v7, v124, v125, s[8:9]
	v_mul_f32_e32 v124, 0x37800000, v7
	v_cndmask_b32_e32 v7, v7, v124, vcc
	v_cmp_class_f32_e32 vcc, v0, v253
	s_nop 1
	v_cndmask_b32_e32 v0, v7, v0, vcc
	v_div_scale_f32 v7, s[6:7], v0, v0, 1.0
	v_rcp_f32_e32 v124, v7
	s_lshl_b32 s6, s10, 1
	s_and_b32 s6, s6, 0xffffe000
	s_add_i32 s6, s6, 0
	v_fma_f32 v125, -v7, v124, 1.0
	v_fmac_f32_e32 v124, v125, v124
	v_div_scale_f32 v125, vcc, 1.0, v0, 1.0
	v_mul_f32_e32 v146, v125, v124
	v_fma_f32 v156, -v7, v146, v125
	v_fmac_f32_e32 v146, v156, v124
	v_fma_f32 v7, -v7, v146, v125
	v_div_fmas_f32 v7, v7, v124, v146
	v_div_fixup_f32 v146, v7, v0, 1.0
	v_lshlrev_b32_e32 v0, 4, v147
	v_add_u32_e32 v164, s6, v0
	v_pk_mul_f32 v[160:161], v[152:153], v[146:147] op_sel_hi:[1,0]
	v_pk_mul_f32 v[162:163], v[154:155], v[146:147] op_sel_hi:[1,0]
	ds_read_b128 v[152:155], v164
	ds_read_b128 v[156:159], v164 offset:40960
	v_lshl_add_u64 v[124:125], s[12:13], 1, v[2:3]
	v_mov_b32_e32 v7, v1
	v_lshl_add_u64 v[124:125], v[124:125], 0, v[6:7]
	v_pk_mul_f32 v[4:5], v[4:5], v[146:147] op_sel_hi:[1,0]
	s_waitcnt lgkmcnt(0)
	v_pk_fma_f32 v[154:155], v[154:155], v[162:163], v[158:159]
	v_pk_fma_f32 v[152:153], v[152:153], v[160:161], v[156:157]
	v_pk_mul_f32 v[156:157], v[148:149], v[146:147] op_sel_hi:[1,0]
	v_cvt_pk_bf16_f32 v152, v152, v153
	v_cvt_pk_bf16_f32 v153, v154, v155
	global_store_dwordx2 v[124:125], v[152:153], off
	v_pk_mul_f32 v[158:159], v[150:151], v[146:147] op_sel_hi:[1,0]
	ds_read_b128 v[148:151], v164 offset:1024
	ds_read_b128 v[152:155], v164 offset:41984
	s_waitcnt lgkmcnt(0)
	v_pk_fma_f32 v[150:151], v[150:151], v[158:159], v[154:155]
	v_pk_fma_f32 v[148:149], v[148:149], v[156:157], v[152:153]
	v_pk_mul_f32 v[152:153], v[138:139], v[146:147] op_sel_hi:[1,0]
	v_cvt_pk_bf16_f32 v148, v148, v149
	v_cvt_pk_bf16_f32 v149, v150, v151
	global_store_dwordx2 v[124:125], v[148:149], off offset:512
	v_pk_mul_f32 v[154:155], v[140:141], v[146:147] op_sel_hi:[1,0]
	ds_read_b128 v[138:141], v164 offset:2048
	ds_read_b128 v[148:151], v164 offset:43008
	s_waitcnt lgkmcnt(0)
	v_pk_fma_f32 v[140:141], v[140:141], v[154:155], v[150:151]
	v_pk_fma_f32 v[138:139], v[138:139], v[152:153], v[148:149]
	v_pk_mul_f32 v[148:149], v[142:143], v[146:147] op_sel_hi:[1,0]
	v_cvt_pk_bf16_f32 v138, v138, v139
	v_cvt_pk_bf16_f32 v139, v140, v141
	global_store_dwordx2 v[124:125], v[138:139], off offset:1024
	v_pk_mul_f32 v[150:151], v[144:145], v[146:147] op_sel_hi:[1,0]
	ds_read_b128 v[138:141], v164 offset:3072
	ds_read_b128 v[142:145], v164 offset:44032
	s_waitcnt lgkmcnt(0)
	v_pk_fma_f32 v[140:141], v[150:151], v[140:141], v[144:145]
	v_pk_fma_f32 v[138:139], v[148:149], v[138:139], v[142:143]
	v_pk_mul_f32 v[142:143], v[132:133], v[146:147] op_sel_hi:[1,0]
	v_cvt_pk_bf16_f32 v138, v138, v139
	v_cvt_pk_bf16_f32 v139, v140, v141
	global_store_dwordx2 v[124:125], v[138:139], off offset:1536
	v_pk_mul_f32 v[144:145], v[134:135], v[146:147] op_sel_hi:[1,0]
	ds_read_b128 v[132:135], v164 offset:4096
	ds_read_b128 v[138:141], v164 offset:45056
	s_waitcnt lgkmcnt(0)
	v_pk_fma_f32 v[134:135], v[144:145], v[134:135], v[140:141]
	v_pk_fma_f32 v[132:133], v[142:143], v[132:133], v[138:139]
	v_pk_mul_f32 v[138:139], v[130:131], v[146:147] op_sel_hi:[1,0]
	v_cvt_pk_bf16_f32 v132, v132, v133
	v_cvt_pk_bf16_f32 v133, v134, v135
	global_store_dwordx2 v[124:125], v[132:133], off offset:2048
	v_pk_mul_f32 v[140:141], v[136:137], v[146:147] op_sel_hi:[1,0]
	ds_read_b128 v[130:133], v164 offset:5120
	ds_read_b128 v[134:137], v164 offset:46080
	s_waitcnt lgkmcnt(0)
	v_pk_fma_f32 v[132:133], v[140:141], v[132:133], v[136:137]
	v_pk_fma_f32 v[130:131], v[138:139], v[130:131], v[134:135]
	v_pk_mul_f32 v[136:137], v[128:129], v[146:147] op_sel_hi:[1,0]
	v_cvt_pk_bf16_f32 v130, v130, v131
	v_cvt_pk_bf16_f32 v131, v132, v133
	global_store_dwordx2 v[124:125], v[130:131], off offset:2560
	ds_read_b128 v[128:131], v164 offset:6144
	ds_read_b128 v[132:135], v164 offset:47104
	s_waitcnt vmcnt(61)
	v_cvt_f32_f16_sdwa v139, v123 dst_sel:DWORD dst_unused:UNUSED_PAD src0_sel:WORD_1
	v_cvt_f32_f16_e32 v138, v123
	s_waitcnt vmcnt(59)
	v_cvt_f32_f16_sdwa v123, v118 dst_sel:DWORD dst_unused:UNUSED_PAD src0_sel:WORD_1
	s_waitcnt lgkmcnt(0)
; __device__ __forceinline__ void norm_mod_phase2(const Args& a, Frame& F, const float* gain, const float* modl, int sh_off, int sc_off, int nrows, const float* slab_gate) {
;     ...
;     NR_FINISH(r0, nw,            (nw) >> 12);
;     NR_FINISH(r1, nw + 2048,     (nw + 2048) >> 12);
	v_pk_fma_f32 v[130:131], v[136:137], v[130:131], v[134:135]
	v_pk_fma_f32 v[4:5], v[4:5], v[128:129], v[132:133]
	v_cvt_f32_f16_sdwa v137, v122 dst_sel:DWORD dst_unused:UNUSED_PAD src0_sel:WORD_1
	v_cvt_pk_bf16_f32 v4, v4, v5
	v_cvt_pk_bf16_f32 v5, v130, v131
	global_store_dwordx2 v[124:125], v[4:5], off offset:3072
	v_pk_mul_f32 v[4:5], v[74:75], v[146:147] op_sel_hi:[1,0]
	v_pk_mul_f32 v[74:75], v[126:127], v[146:147] op_sel_hi:[1,0]
	ds_read_b128 v[126:129], v164 offset:7168
	ds_read_b128 v[130:133], v164 offset:48128
	v_cvt_f32_f16_e32 v136, v122
	v_cvt_f32_f16_sdwa v135, v121 dst_sel:DWORD dst_unused:UNUSED_PAD src0_sel:WORD_1
	v_cvt_f32_f16_e32 v134, v121
	v_cvt_f32_f16_e32 v122, v118
	s_waitcnt lgkmcnt(0)
	v_pk_fma_f32 v[74:75], v[74:75], v[128:129], v[132:133]
	v_cvt_f32_f16_sdwa v133, v120 dst_sel:DWORD dst_unused:UNUSED_PAD src0_sel:WORD_1
	v_pk_fma_f32 v[4:5], v[4:5], v[126:127], v[130:131]
	v_cvt_f32_f16_e32 v132, v120
	v_cvt_pk_bf16_f32 v4, v4, v5
	v_cvt_pk_bf16_f32 v5, v74, v75
	global_store_dwordx2 v[124:125], v[4:5], off offset:3584
	v_cvt_f32_f16_sdwa v125, v119 dst_sel:DWORD dst_unused:UNUSED_PAD src0_sel:WORD_1
	s_waitcnt vmcnt(60)
	v_cvt_f32_f16_sdwa v127, v116 dst_sel:DWORD dst_unused:UNUSED_PAD src0_sel:WORD_1
	v_mov_b32_e32 v74, v137
	v_mov_b32_e32 v75, v133
	v_cvt_f32_f16_e32 v124, v119
	v_cvt_f32_f16_e32 v126, v116
	v_cvt_f32_f16_sdwa v129, v117 dst_sel:DWORD dst_unused:UNUSED_PAD src0_sel:WORD_1
	v_mov_b32_e32 v4, v136
	v_mov_b32_e32 v5, v132
	v_pk_mul_f32 v[74:75], v[74:75], v[74:75]
	v_mov_b32_e32 v120, v139
	v_mov_b32_e32 v121, v135
	v_cvt_f32_f16_e32 v128, v117
	v_pk_fma_f32 v[4:5], v[4:5], v[4:5], v[74:75]
	v_mov_b32_e32 v74, v138
	v_mov_b32_e32 v75, v134
	v_pk_mul_f32 v[120:121], v[120:121], v[120:121]
	v_mov_b32_e32 v118, v123
	v_pk_fma_f32 v[74:75], v[74:75], v[74:75], v[120:121]
	v_mov_b32_e32 v119, v125
	v_mul_f32_e32 v116, v127, v127
	v_pk_add_f32 v[4:5], v[4:5], v[74:75]
	v_mov_b32_e32 v74, v122
	v_mov_b32_e32 v75, v124
	v_pk_mul_f32 v[118:119], v[118:119], v[118:119]
	v_pk_fma_f32 v[120:121], v[126:127], v[126:127], v[116:117] op_sel_hi:[1,1,0]
	v_mul_f32_e32 v116, v129, v129
	v_pk_fma_f32 v[74:75], v[74:75], v[74:75], v[118:119]
	v_pk_fma_f32 v[130:131], v[128:129], v[128:129], v[116:117] op_sel_hi:[1,1,0]
	s_waitcnt vmcnt(59)
	v_cvt_f32_f16_sdwa v117, v114 dst_sel:DWORD dst_unused:UNUSED_PAD src0_sel:WORD_1
	v_cvt_f32_f16_e32 v116, v114
	v_cvt_f32_f16_sdwa v119, v115 dst_sel:DWORD dst_unused:UNUSED_PAD src0_sel:WORD_1
	v_cvt_f32_f16_e32 v118, v115
	v_pk_add_f32 v[4:5], v[4:5], v[4:5] op_sel:[0,1] op_sel_hi:[1,0]
	v_pk_add_f32 v[74:75], v[74:75], v[74:75] op_sel:[0,1] op_sel_hi:[1,0]
	v_pk_mul_f32 v[114:115], v[116:117], v[116:117]
	v_pk_mul_f32 v[140:141], v[118:119], v[118:119]
	v_mov_b32_e32 v5, v114
	v_mov_b32_e32 v75, v115
	v_mov_b32_e32 v121, v140
	v_mov_b32_e32 v131, v141
	v_pk_add_f32 v[4:5], v[4:5], v[74:75]
	v_pk_add_f32 v[74:75], v[120:121], v[130:131]
	s_waitcnt vmcnt(58)
	v_cvt_f32_f16_sdwa v115, v112 dst_sel:DWORD dst_unused:UNUSED_PAD src0_sel:WORD_1
	v_cvt_f32_f16_sdwa v121, v113 dst_sel:DWORD dst_unused:UNUSED_PAD src0_sel:WORD_1
	v_cvt_f32_f16_e32 v114, v112
	v_cvt_f32_f16_e32 v120, v113
	v_pk_add_f32 v[4:5], v[4:5], v[74:75]
	v_mov_b32_e32 v74, v115
	v_mov_b32_e32 v75, v121
	v_pk_add_f32 v[130:131], v[4:5], v[4:5] op_sel:[0,1] op_sel_hi:[1,0]
	v_mov_b32_e32 v4, v114
	v_mov_b32_e32 v5, v120
	v_pk_mul_f32 v[74:75], v[74:75], v[74:75]
	s_waitcnt vmcnt(57)
	v_cvt_f32_f16_sdwa v113, v111 dst_sel:DWORD dst_unused:UNUSED_PAD src0_sel:WORD_1
	v_pk_fma_f32 v[4:5], v[4:5], v[4:5], v[74:75]
	v_cvt_f32_f16_e32 v112, v111
	v_pk_add_f32 v[140:141], v[4:5], v[4:5] op_sel:[0,1] op_sel_hi:[1,0]
	v_cvt_f32_f16_sdwa v5, v110 dst_sel:DWORD dst_unused:UNUSED_PAD src0_sel:WORD_1
	v_cvt_f32_f16_e32 v4, v110
	s_waitcnt vmcnt(56)
	v_cvt_f32_f16_sdwa v111, v109 dst_sel:DWORD dst_unused:UNUSED_PAD src0_sel:WORD_1
	v_cvt_f32_f16_e32 v110, v109
	v_mul_f32_e32 v74, v5, v5
	v_pk_fma_f32 v[142:143], v[4:5], v[4:5], v[74:75] op_sel_hi:[1,1,0]
	v_mul_f32_e32 v74, v113, v113
	v_pk_fma_f32 v[144:145], v[112:113], v[112:113], v[74:75] op_sel_hi:[1,1,0]
	v_cvt_f32_f16_sdwa v75, v108 dst_sel:DWORD dst_unused:UNUSED_PAD src0_sel:WORD_1
	v_cvt_f32_f16_e32 v74, v108
	v_pk_mul_f32 v[148:149], v[110:111], v[110:111]
	v_pk_mul_f32 v[108:109], v[74:75], v[74:75]
	s_nop 0
	v_mov_b32_e32 v131, v108
	v_mov_b32_e32 v141, v109
	v_mov_b32_e32 v143, v148
	v_mov_b32_e32 v145, v149
	v_pk_add_f32 v[108:109], v[130:131], v[140:141]
	v_pk_add_f32 v[130:131], v[142:143], v[144:145]
	s_nop 0
	v_pk_add_f32 v[108:109], v[108:109], v[130:131]
	s_nop 0
	v_add_f32_e32 v108, v108, v109
	s_nop 1
	v_add_f32_dpp v108, v108, v108 quad_perm:[1,0,3,2] row_mask:0xf bank_mask:0xf bound_ctrl:1
	s_nop 1
	v_add_f32_dpp v108, v108, v108 quad_perm:[2,3,0,1] row_mask:0xf bank_mask:0xf bound_ctrl:1
	s_nop 1
	v_add_f32_dpp v108, v108, v108 row_half_mirror row_mask:0xf bank_mask:0xf bound_ctrl:1
	s_nop 1
	v_add_f32_dpp v108, v108, v108 row_mirror row_mask:0xf bank_mask:0xf bound_ctrl:1
	s_nop 0
	v_readlane_b32 s8, v108, 16
	v_readlane_b32 s9, v108, 48
	v_readlane_b32 s6, v108, 0
	v_readlane_b32 s7, v108, 32
	v_mov_b32_e32 v108, s8
	v_mov_b32_e32 v109, s9
	v_pk_add_f32 v[108:109], s[6:7], v[108:109]
	s_nop 0
	v_add_f32_e32 v108, v108, v109
	v_fmamk_f32 v108, v108, 0x3a000000, v252
	v_cmp_gt_f32_e32 vcc, s55, v108
	v_mul_f32_e32 v109, 0x4f800000, v108
	s_nop 0
	v_cndmask_b32_e32 v108, v108, v109, vcc
	v_sqrt_f32_e32 v109, v108
	s_nop 0
	v_add_u32_e32 v130, -1, v109
	v_fma_f32 v131, -v130, v109, v108
	v_cmp_ge_f32_e64 s[8:9], 0, v131
	v_add_u32_e32 v131, 1, v109
	s_nop 0
	v_cndmask_b32_e64 v130, v109, v130, s[8:9]
	v_fma_f32 v109, -v131, v109, v108
	v_cmp_lt_f32_e64 s[8:9], 0, v109
	s_nop 1
	v_cndmask_b32_e64 v109, v130, v131, s[8:9]
	v_mul_f32_e32 v130, 0x37800000, v109
	v_cndmask_b32_e32 v109, v109, v130, vcc
	v_cmp_class_f32_e32 vcc, v108, v253
	s_nop 1
	v_cndmask_b32_e32 v108, v109, v108, vcc
	v_div_scale_f32 v109, s[6:7], v108, v108, 1.0
	v_rcp_f32_e32 v130, v109
	s_lshl_b32 s6, s78, 1
	s_and_b32 s6, s6, 0xffffe000
	s_add_i32 s6, s6, 0
	v_fma_f32 v131, -v109, v130, 1.0
	v_fmac_f32_e32 v130, v131, v130
	v_div_scale_f32 v131, vcc, 1.0, v108, 1.0
	v_mul_f32_e32 v140, v131, v130
	v_fma_f32 v141, -v109, v140, v131
	v_fmac_f32_e32 v140, v141, v130
	v_fma_f32 v109, -v109, v140, v131
	v_div_fmas_f32 v109, v109, v130, v140
	v_div_fixup_f32 v130, v109, v108, 1.0
	v_pk_mul_f32 v[144:145], v[136:137], v[130:131] op_sel_hi:[1,0]
	v_pk_mul_f32 v[148:149], v[138:139], v[130:131] op_sel_hi:[1,0]
	v_add_u32_e32 v131, s6, v0
	ds_read_b128 v[136:139], v131
	ds_read_b128 v[140:143], v131 offset:40960
	v_lshl_add_u64 v[108:109], s[48:49], 1, v[2:3]
	v_lshl_add_u64 v[108:109], v[108:109], 0, v[6:7]
	v_pk_mul_f32 v[4:5], v[4:5], v[130:131] op_sel_hi:[1,0]
	s_waitcnt lgkmcnt(0)
; __device__ __forceinline__ void norm_mod_phase2(const Args& a, Frame& F, const float* gain, const float* modl, int sh_off, int sc_off, int nrows, const float* slab_gate) {
;     ...
;     NR_FINISH(r1, nw + 2048,     (nw + 2048) >> 12);
;     NR_FINISH(r2, nw + 2 * 2048, (nw + 2 * 2048) >> 12);
	v_pk_fma_f32 v[138:139], v[138:139], v[148:149], v[142:143]
	v_pk_fma_f32 v[136:137], v[136:137], v[144:145], v[140:141]
	v_pk_mul_f32 v[140:141], v[132:133], v[130:131] op_sel_hi:[1,0]
	v_cvt_pk_bf16_f32 v136, v136, v137
	v_cvt_pk_bf16_f32 v137, v138, v139
	global_store_dwordx2 v[108:109], v[136:137], off
	v_pk_mul_f32 v[142:143], v[134:135], v[130:131] op_sel_hi:[1,0]
	ds_read_b128 v[132:135], v131 offset:1024
	ds_read_b128 v[136:139], v131 offset:41984
	s_waitcnt lgkmcnt(0)
	v_pk_fma_f32 v[134:135], v[134:135], v[142:143], v[138:139]
	v_pk_fma_f32 v[132:133], v[132:133], v[140:141], v[136:137]
	v_pk_mul_f32 v[136:137], v[122:123], v[130:131] op_sel_hi:[1,0]
	v_cvt_pk_bf16_f32 v132, v132, v133
	v_cvt_pk_bf16_f32 v133, v134, v135
	global_store_dwordx2 v[108:109], v[132:133], off offset:512
	v_pk_mul_f32 v[138:139], v[124:125], v[130:131] op_sel_hi:[1,0]
	ds_read_b128 v[122:125], v131 offset:2048
	ds_read_b128 v[132:135], v131 offset:43008
	s_waitcnt lgkmcnt(0)
	v_pk_fma_f32 v[124:125], v[124:125], v[138:139], v[134:135]
	v_pk_fma_f32 v[122:123], v[122:123], v[136:137], v[132:133]
	v_pk_mul_f32 v[132:133], v[126:127], v[130:131] op_sel_hi:[1,0]
	v_cvt_pk_bf16_f32 v122, v122, v123
	v_cvt_pk_bf16_f32 v123, v124, v125
	global_store_dwordx2 v[108:109], v[122:123], off offset:1024
	v_pk_mul_f32 v[134:135], v[128:129], v[130:131] op_sel_hi:[1,0]
	ds_read_b128 v[122:125], v131 offset:3072
	ds_read_b128 v[126:129], v131 offset:44032
	s_waitcnt lgkmcnt(0)
	v_pk_fma_f32 v[124:125], v[134:135], v[124:125], v[128:129]
	v_pk_fma_f32 v[122:123], v[132:133], v[122:123], v[126:127]
	v_pk_mul_f32 v[126:127], v[116:117], v[130:131] op_sel_hi:[1,0]
	v_cvt_pk_bf16_f32 v122, v122, v123
	v_cvt_pk_bf16_f32 v123, v124, v125
	global_store_dwordx2 v[108:109], v[122:123], off offset:1536
	v_pk_mul_f32 v[128:129], v[118:119], v[130:131] op_sel_hi:[1,0]
	ds_read_b128 v[116:119], v131 offset:4096
	ds_read_b128 v[122:125], v131 offset:45056
	s_waitcnt lgkmcnt(0)
	v_pk_fma_f32 v[118:119], v[128:129], v[118:119], v[124:125]
	v_pk_fma_f32 v[116:117], v[126:127], v[116:117], v[122:123]
	v_pk_mul_f32 v[122:123], v[114:115], v[130:131] op_sel_hi:[1,0]
	v_cvt_pk_bf16_f32 v116, v116, v117
	v_cvt_pk_bf16_f32 v117, v118, v119
	global_store_dwordx2 v[108:109], v[116:117], off offset:2048
	v_pk_mul_f32 v[124:125], v[120:121], v[130:131] op_sel_hi:[1,0]
	ds_read_b128 v[114:117], v131 offset:5120
	ds_read_b128 v[118:121], v131 offset:46080
	s_waitcnt lgkmcnt(0)
	v_pk_fma_f32 v[116:117], v[124:125], v[116:117], v[120:121]
	v_pk_fma_f32 v[114:115], v[122:123], v[114:115], v[118:119]
	v_pk_mul_f32 v[120:121], v[112:113], v[130:131] op_sel_hi:[1,0]
	v_cvt_pk_bf16_f32 v114, v114, v115
	v_cvt_pk_bf16_f32 v115, v116, v117
	global_store_dwordx2 v[108:109], v[114:115], off offset:2560
	ds_read_b128 v[112:115], v131 offset:6144
	ds_read_b128 v[116:119], v131 offset:47104
	s_waitcnt vmcnt(61)
	v_cvt_f32_f16_sdwa v123, v107 dst_sel:DWORD dst_unused:UNUSED_PAD src0_sel:WORD_1
	v_cvt_f32_f16_e32 v122, v107
	s_waitcnt vmcnt(59)
	v_cvt_f32_f16_sdwa v107, v102 dst_sel:DWORD dst_unused:UNUSED_PAD src0_sel:WORD_1
	s_waitcnt lgkmcnt(0)
	v_pk_fma_f32 v[114:115], v[120:121], v[114:115], v[118:119]
	v_pk_fma_f32 v[4:5], v[4:5], v[112:113], v[116:117]
	v_cvt_f32_f16_sdwa v121, v106 dst_sel:DWORD dst_unused:UNUSED_PAD src0_sel:WORD_1
	v_cvt_pk_bf16_f32 v4, v4, v5
	v_cvt_pk_bf16_f32 v5, v114, v115
	global_store_dwordx2 v[108:109], v[4:5], off offset:3072
	v_pk_mul_f32 v[4:5], v[74:75], v[130:131] op_sel_hi:[1,0]
	v_pk_mul_f32 v[74:75], v[110:111], v[130:131] op_sel_hi:[1,0]
	ds_read_b128 v[110:113], v131 offset:7168
	ds_read_b128 v[114:117], v131 offset:48128
	v_cvt_f32_f16_e32 v120, v106
	v_cvt_f32_f16_sdwa v119, v105 dst_sel:DWORD dst_unused:UNUSED_PAD src0_sel:WORD_1
	v_cvt_f32_f16_e32 v118, v105
	v_cvt_f32_f16_e32 v106, v102
	s_waitcnt lgkmcnt(0)
	v_pk_fma_f32 v[74:75], v[74:75], v[112:113], v[116:117]
	v_cvt_f32_f16_sdwa v117, v104 dst_sel:DWORD dst_unused:UNUSED_PAD src0_sel:WORD_1
	v_pk_fma_f32 v[4:5], v[4:5], v[110:111], v[114:115]
	v_cvt_f32_f16_e32 v116, v104
	v_cvt_pk_bf16_f32 v4, v4, v5
	v_cvt_pk_bf16_f32 v5, v74, v75
	global_store_dwordx2 v[108:109], v[4:5], off offset:3584
	v_cvt_f32_f16_sdwa v109, v103 dst_sel:DWORD dst_unused:UNUSED_PAD src0_sel:WORD_1
	s_waitcnt vmcnt(60)
	v_cvt_f32_f16_sdwa v111, v100 dst_sel:DWORD dst_unused:UNUSED_PAD src0_sel:WORD_1
	v_mov_b32_e32 v74, v121
	v_mov_b32_e32 v75, v117
	v_cvt_f32_f16_e32 v108, v103
	v_cvt_f32_f16_e32 v110, v100
	v_cvt_f32_f16_sdwa v113, v101 dst_sel:DWORD dst_unused:UNUSED_PAD src0_sel:WORD_1
	v_mov_b32_e32 v4, v120
	v_mov_b32_e32 v5, v116
	v_pk_mul_f32 v[74:75], v[74:75], v[74:75]
	v_mov_b32_e32 v104, v123
	v_mov_b32_e32 v105, v119
	v_cvt_f32_f16_e32 v112, v101
	v_pk_fma_f32 v[4:5], v[4:5], v[4:5], v[74:75]
	v_mov_b32_e32 v74, v122
	v_mov_b32_e32 v75, v118
	v_pk_mul_f32 v[104:105], v[104:105], v[104:105]
	v_mov_b32_e32 v102, v107
	v_pk_fma_f32 v[74:75], v[74:75], v[74:75], v[104:105]
	v_mov_b32_e32 v103, v109
	v_mul_f32_e32 v100, v111, v111
	v_pk_add_f32 v[4:5], v[4:5], v[74:75]
	v_mov_b32_e32 v74, v106
	v_mov_b32_e32 v75, v108
	v_pk_mul_f32 v[102:103], v[102:103], v[102:103]
	v_pk_fma_f32 v[104:105], v[110:111], v[110:111], v[100:101] op_sel_hi:[1,1,0]
	v_mul_f32_e32 v100, v113, v113
	v_pk_fma_f32 v[74:75], v[74:75], v[74:75], v[102:103]
	v_pk_fma_f32 v[114:115], v[112:113], v[112:113], v[100:101] op_sel_hi:[1,1,0]
	s_waitcnt vmcnt(59)
; __device__ __forceinline__ void norm_mod_phase2(const Args& a, Frame& F, const float* gain, const float* modl, int sh_off, int sc_off, int nrows, const float* slab_gate) {
;     ...
;     NR_FINISH(r2, nw + 2 * 2048, (nw + 2 * 2048) >> 12);
	v_cvt_f32_f16_sdwa v101, v98 dst_sel:DWORD dst_unused:UNUSED_PAD src0_sel:WORD_1
	v_cvt_f32_f16_e32 v100, v98
	v_cvt_f32_f16_sdwa v103, v99 dst_sel:DWORD dst_unused:UNUSED_PAD src0_sel:WORD_1
	v_cvt_f32_f16_e32 v102, v99
	v_pk_add_f32 v[4:5], v[4:5], v[4:5] op_sel:[0,1] op_sel_hi:[1,0]
	v_pk_add_f32 v[74:75], v[74:75], v[74:75] op_sel:[0,1] op_sel_hi:[1,0]
	v_pk_mul_f32 v[98:99], v[100:101], v[100:101]
	v_pk_mul_f32 v[124:125], v[102:103], v[102:103]
	v_mov_b32_e32 v5, v98
	v_mov_b32_e32 v75, v99
	v_mov_b32_e32 v105, v124
	v_mov_b32_e32 v115, v125
	v_pk_add_f32 v[4:5], v[4:5], v[74:75]
	v_pk_add_f32 v[74:75], v[104:105], v[114:115]
	s_waitcnt vmcnt(58)
	v_cvt_f32_f16_sdwa v99, v96 dst_sel:DWORD dst_unused:UNUSED_PAD src0_sel:WORD_1
	v_cvt_f32_f16_sdwa v105, v97 dst_sel:DWORD dst_unused:UNUSED_PAD src0_sel:WORD_1
	v_cvt_f32_f16_e32 v98, v96
	v_cvt_f32_f16_e32 v104, v97
	v_pk_add_f32 v[4:5], v[4:5], v[74:75]
	v_mov_b32_e32 v74, v99
	v_mov_b32_e32 v75, v105
	v_pk_add_f32 v[114:115], v[4:5], v[4:5] op_sel:[0,1] op_sel_hi:[1,0]
	v_mov_b32_e32 v4, v98
	v_mov_b32_e32 v5, v104
	v_pk_mul_f32 v[74:75], v[74:75], v[74:75]
	s_waitcnt vmcnt(57)
	v_cvt_f32_f16_sdwa v97, v95 dst_sel:DWORD dst_unused:UNUSED_PAD src0_sel:WORD_1
	v_pk_fma_f32 v[4:5], v[4:5], v[4:5], v[74:75]
	v_cvt_f32_f16_e32 v96, v95
	v_pk_add_f32 v[124:125], v[4:5], v[4:5] op_sel:[0,1] op_sel_hi:[1,0]
	v_cvt_f32_f16_sdwa v5, v94 dst_sel:DWORD dst_unused:UNUSED_PAD src0_sel:WORD_1
	v_cvt_f32_f16_e32 v4, v94
	s_waitcnt vmcnt(56)
	v_cvt_f32_f16_sdwa v95, v93 dst_sel:DWORD dst_unused:UNUSED_PAD src0_sel:WORD_1
	v_cvt_f32_f16_e32 v94, v93
	v_mul_f32_e32 v74, v5, v5
	v_pk_fma_f32 v[126:127], v[4:5], v[4:5], v[74:75] op_sel_hi:[1,1,0]
	v_mul_f32_e32 v74, v97, v97
	v_pk_fma_f32 v[128:129], v[96:97], v[96:97], v[74:75] op_sel_hi:[1,1,0]
	v_cvt_f32_f16_sdwa v75, v92 dst_sel:DWORD dst_unused:UNUSED_PAD src0_sel:WORD_1
	v_cvt_f32_f16_e32 v74, v92
	v_pk_mul_f32 v[130:131], v[94:95], v[94:95]
	v_pk_mul_f32 v[92:93], v[74:75], v[74:75]
	s_nop 0
	v_mov_b32_e32 v115, v92
	v_mov_b32_e32 v125, v93
	v_mov_b32_e32 v127, v130
	v_mov_b32_e32 v129, v131
	v_pk_add_f32 v[92:93], v[114:115], v[124:125]
	v_pk_add_f32 v[114:115], v[126:127], v[128:129]
	s_nop 0
	v_pk_add_f32 v[92:93], v[92:93], v[114:115]
	s_nop 0
	v_add_f32_e32 v92, v92, v93
	s_nop 1
	v_add_f32_dpp v92, v92, v92 quad_perm:[1,0,3,2] row_mask:0xf bank_mask:0xf bound_ctrl:1
	s_nop 1
	v_add_f32_dpp v92, v92, v92 quad_perm:[2,3,0,1] row_mask:0xf bank_mask:0xf bound_ctrl:1
	s_nop 1
	v_add_f32_dpp v92, v92, v92 row_half_mirror row_mask:0xf bank_mask:0xf bound_ctrl:1
	s_nop 1
	v_add_f32_dpp v92, v92, v92 row_mirror row_mask:0xf bank_mask:0xf bound_ctrl:1
	s_nop 0
	v_readlane_b32 s8, v92, 16
	v_readlane_b32 s9, v92, 48
	v_readlane_b32 s6, v92, 0
	v_readlane_b32 s7, v92, 32
	v_mov_b32_e32 v92, s8
	v_mov_b32_e32 v93, s9
	v_pk_add_f32 v[92:93], s[6:7], v[92:93]
	s_nop 0
	v_add_f32_e32 v92, v92, v93
	v_fmamk_f32 v92, v92, 0x3a000000, v252
	v_cmp_gt_f32_e32 vcc, s55, v92
	v_mul_f32_e32 v93, 0x4f800000, v92
	s_nop 0
	v_cndmask_b32_e32 v92, v92, v93, vcc
	v_sqrt_f32_e32 v93, v92
	s_nop 0
	v_add_u32_e32 v114, -1, v93
	v_fma_f32 v115, -v114, v93, v92
	v_cmp_ge_f32_e64 s[8:9], 0, v115
	v_add_u32_e32 v115, 1, v93
	s_nop 0
	v_cndmask_b32_e64 v114, v93, v114, s[8:9]
	v_fma_f32 v93, -v115, v93, v92
	v_cmp_lt_f32_e64 s[8:9], 0, v93
	s_nop 1
	v_cndmask_b32_e64 v93, v114, v115, s[8:9]
	v_mul_f32_e32 v114, 0x37800000, v93
	v_cndmask_b32_e32 v93, v93, v114, vcc
	v_cmp_class_f32_e32 vcc, v92, v253
	s_nop 1
	v_cndmask_b32_e32 v92, v93, v92, vcc
	v_div_scale_f32 v93, s[6:7], v92, v92, 1.0
	v_rcp_f32_e32 v114, v93
	s_lshl_b32 s6, s36, 1
	s_and_b32 s6, s6, 0xffffe000
	s_add_i32 s6, s6, 0
	v_fma_f32 v115, -v93, v114, 1.0
	v_fmac_f32_e32 v114, v115, v114
	v_div_scale_f32 v115, vcc, 1.0, v92, 1.0
	v_mul_f32_e32 v124, v115, v114
	v_fma_f32 v125, -v93, v124, v115
	v_fmac_f32_e32 v124, v125, v114
	v_fma_f32 v93, -v93, v124, v115
	v_div_fmas_f32 v93, v93, v114, v124
	v_div_fixup_f32 v114, v93, v92, 1.0
	v_pk_mul_f32 v[128:129], v[120:121], v[114:115] op_sel_hi:[1,0]
	v_pk_mul_f32 v[130:131], v[122:123], v[114:115] op_sel_hi:[1,0]
	v_add_u32_e32 v115, s6, v0
	ds_read_b128 v[120:123], v115
	ds_read_b128 v[124:127], v115 offset:40960
	v_lshl_add_u64 v[92:93], s[40:41], 1, v[2:3]
	v_lshl_add_u64 v[92:93], v[92:93], 0, v[6:7]
	v_pk_mul_f32 v[4:5], v[4:5], v[114:115] op_sel_hi:[1,0]
	s_waitcnt lgkmcnt(0)
	v_pk_fma_f32 v[122:123], v[122:123], v[130:131], v[126:127]
	v_pk_fma_f32 v[120:121], v[120:121], v[128:129], v[124:125]
	v_pk_mul_f32 v[124:125], v[116:117], v[114:115] op_sel_hi:[1,0]
	v_cvt_pk_bf16_f32 v120, v120, v121
	v_cvt_pk_bf16_f32 v121, v122, v123
	global_store_dwordx2 v[92:93], v[120:121], off
	v_pk_mul_f32 v[126:127], v[118:119], v[114:115] op_sel_hi:[1,0]
	ds_read_b128 v[116:119], v115 offset:1024
	ds_read_b128 v[120:123], v115 offset:41984
	s_waitcnt lgkmcnt(0)
	v_pk_fma_f32 v[118:119], v[118:119], v[126:127], v[122:123]
	v_pk_fma_f32 v[116:117], v[116:117], v[124:125], v[120:121]
	v_pk_mul_f32 v[120:121], v[106:107], v[114:115] op_sel_hi:[1,0]
	v_cvt_pk_bf16_f32 v116, v116, v117
	v_cvt_pk_bf16_f32 v117, v118, v119
	global_store_dwordx2 v[92:93], v[116:117], off offset:512
	v_pk_mul_f32 v[122:123], v[108:109], v[114:115] op_sel_hi:[1,0]
	ds_read_b128 v[106:109], v115 offset:2048
	ds_read_b128 v[116:119], v115 offset:43008
	s_waitcnt lgkmcnt(0)
; __device__ __forceinline__ void norm_mod_phase2(const Args& a, Frame& F, const float* gain, const float* modl, int sh_off, int sc_off, int nrows, const float* slab_gate) {
;     ...
;     NR_FINISH(r2, nw + 2 * 2048, (nw + 2 * 2048) >> 12);
;     NR_FINISH(r3, nw + 3 * 2048, (nw + 3 * 2048) >> 12);
	v_pk_fma_f32 v[108:109], v[108:109], v[122:123], v[118:119]
	v_pk_fma_f32 v[106:107], v[106:107], v[120:121], v[116:117]
	v_pk_mul_f32 v[116:117], v[110:111], v[114:115] op_sel_hi:[1,0]
	v_cvt_pk_bf16_f32 v106, v106, v107
	v_cvt_pk_bf16_f32 v107, v108, v109
	global_store_dwordx2 v[92:93], v[106:107], off offset:1024
	v_pk_mul_f32 v[118:119], v[112:113], v[114:115] op_sel_hi:[1,0]
	ds_read_b128 v[106:109], v115 offset:3072
	ds_read_b128 v[110:113], v115 offset:44032
	s_waitcnt lgkmcnt(0)
	v_pk_fma_f32 v[108:109], v[118:119], v[108:109], v[112:113]
	v_pk_fma_f32 v[106:107], v[116:117], v[106:107], v[110:111]
	v_pk_mul_f32 v[110:111], v[100:101], v[114:115] op_sel_hi:[1,0]
	v_cvt_pk_bf16_f32 v106, v106, v107
	v_cvt_pk_bf16_f32 v107, v108, v109
	global_store_dwordx2 v[92:93], v[106:107], off offset:1536
	v_pk_mul_f32 v[112:113], v[102:103], v[114:115] op_sel_hi:[1,0]
	ds_read_b128 v[100:103], v115 offset:4096
	ds_read_b128 v[106:109], v115 offset:45056
	s_waitcnt lgkmcnt(0)
	v_pk_fma_f32 v[102:103], v[112:113], v[102:103], v[108:109]
	v_pk_fma_f32 v[100:101], v[110:111], v[100:101], v[106:107]
	v_pk_mul_f32 v[106:107], v[98:99], v[114:115] op_sel_hi:[1,0]
	v_cvt_pk_bf16_f32 v100, v100, v101
	v_cvt_pk_bf16_f32 v101, v102, v103
	global_store_dwordx2 v[92:93], v[100:101], off offset:2048
	v_pk_mul_f32 v[108:109], v[104:105], v[114:115] op_sel_hi:[1,0]
	ds_read_b128 v[98:101], v115 offset:5120
	ds_read_b128 v[102:105], v115 offset:46080
	s_waitcnt lgkmcnt(0)
	v_pk_fma_f32 v[100:101], v[108:109], v[100:101], v[104:105]
	v_pk_fma_f32 v[98:99], v[106:107], v[98:99], v[102:103]
	v_pk_mul_f32 v[104:105], v[96:97], v[114:115] op_sel_hi:[1,0]
	v_cvt_pk_bf16_f32 v98, v98, v99
	v_cvt_pk_bf16_f32 v99, v100, v101
	global_store_dwordx2 v[92:93], v[98:99], off offset:2560
	ds_read_b128 v[96:99], v115 offset:6144
	ds_read_b128 v[100:103], v115 offset:47104
	s_waitcnt vmcnt(61)
	v_cvt_f32_f16_sdwa v107, v91 dst_sel:DWORD dst_unused:UNUSED_PAD src0_sel:WORD_1
	v_cvt_f32_f16_e32 v106, v91
	s_waitcnt vmcnt(59)
	v_cvt_f32_f16_sdwa v91, v86 dst_sel:DWORD dst_unused:UNUSED_PAD src0_sel:WORD_1
	s_waitcnt lgkmcnt(0)
	v_pk_fma_f32 v[98:99], v[104:105], v[98:99], v[102:103]
	v_pk_fma_f32 v[4:5], v[4:5], v[96:97], v[100:101]
	v_cvt_f32_f16_sdwa v105, v90 dst_sel:DWORD dst_unused:UNUSED_PAD src0_sel:WORD_1
	v_cvt_pk_bf16_f32 v4, v4, v5
	v_cvt_pk_bf16_f32 v5, v98, v99
	global_store_dwordx2 v[92:93], v[4:5], off offset:3072
	v_pk_mul_f32 v[4:5], v[74:75], v[114:115] op_sel_hi:[1,0]
	v_pk_mul_f32 v[74:75], v[94:95], v[114:115] op_sel_hi:[1,0]
	ds_read_b128 v[94:97], v115 offset:7168
	ds_read_b128 v[98:101], v115 offset:48128
	v_cvt_f32_f16_e32 v104, v90
	v_cvt_f32_f16_sdwa v103, v89 dst_sel:DWORD dst_unused:UNUSED_PAD src0_sel:WORD_1
	v_cvt_f32_f16_e32 v102, v89
	v_cvt_f32_f16_e32 v90, v86
	s_waitcnt lgkmcnt(0)
	v_pk_fma_f32 v[74:75], v[74:75], v[96:97], v[100:101]
	v_cvt_f32_f16_sdwa v101, v88 dst_sel:DWORD dst_unused:UNUSED_PAD src0_sel:WORD_1
	v_pk_fma_f32 v[4:5], v[4:5], v[94:95], v[98:99]
	v_cvt_f32_f16_e32 v100, v88
	v_cvt_pk_bf16_f32 v4, v4, v5
	v_cvt_pk_bf16_f32 v5, v74, v75
	global_store_dwordx2 v[92:93], v[4:5], off offset:3584
	v_cvt_f32_f16_sdwa v93, v87 dst_sel:DWORD dst_unused:UNUSED_PAD src0_sel:WORD_1
	s_waitcnt vmcnt(60)
	v_cvt_f32_f16_sdwa v95, v84 dst_sel:DWORD dst_unused:UNUSED_PAD src0_sel:WORD_1
	v_mov_b32_e32 v74, v105
	v_mov_b32_e32 v75, v101
	v_cvt_f32_f16_e32 v92, v87
	v_cvt_f32_f16_e32 v94, v84
	v_cvt_f32_f16_sdwa v97, v85 dst_sel:DWORD dst_unused:UNUSED_PAD src0_sel:WORD_1
	v_mov_b32_e32 v4, v104
	v_mov_b32_e32 v5, v100
	v_pk_mul_f32 v[74:75], v[74:75], v[74:75]
	v_mov_b32_e32 v88, v107
	v_mov_b32_e32 v89, v103
	v_cvt_f32_f16_e32 v96, v85
	v_pk_fma_f32 v[4:5], v[4:5], v[4:5], v[74:75]
	v_mov_b32_e32 v74, v106
	v_mov_b32_e32 v75, v102
	v_pk_mul_f32 v[88:89], v[88:89], v[88:89]
	v_mov_b32_e32 v86, v91
	v_pk_fma_f32 v[74:75], v[74:75], v[74:75], v[88:89]
	v_mov_b32_e32 v87, v93
	v_mul_f32_e32 v84, v95, v95
	v_pk_add_f32 v[4:5], v[4:5], v[74:75]
	v_mov_b32_e32 v74, v90
	v_mov_b32_e32 v75, v92
	v_pk_mul_f32 v[86:87], v[86:87], v[86:87]
	v_pk_fma_f32 v[88:89], v[94:95], v[94:95], v[84:85] op_sel_hi:[1,1,0]
	v_mul_f32_e32 v84, v97, v97
	v_pk_fma_f32 v[74:75], v[74:75], v[74:75], v[86:87]
	v_pk_fma_f32 v[98:99], v[96:97], v[96:97], v[84:85] op_sel_hi:[1,1,0]
	s_waitcnt vmcnt(59)
	v_cvt_f32_f16_sdwa v85, v82 dst_sel:DWORD dst_unused:UNUSED_PAD src0_sel:WORD_1
	v_cvt_f32_f16_e32 v84, v82
	v_cvt_f32_f16_sdwa v87, v83 dst_sel:DWORD dst_unused:UNUSED_PAD src0_sel:WORD_1
	v_cvt_f32_f16_e32 v86, v83
	v_pk_add_f32 v[4:5], v[4:5], v[4:5] op_sel:[0,1] op_sel_hi:[1,0]
	v_pk_add_f32 v[74:75], v[74:75], v[74:75] op_sel:[0,1] op_sel_hi:[1,0]
	v_pk_mul_f32 v[82:83], v[84:85], v[84:85]
	v_pk_mul_f32 v[108:109], v[86:87], v[86:87]
	v_mov_b32_e32 v5, v82
	v_mov_b32_e32 v75, v83
	v_mov_b32_e32 v89, v108
	v_mov_b32_e32 v99, v109
	v_pk_add_f32 v[4:5], v[4:5], v[74:75]
	v_pk_add_f32 v[74:75], v[88:89], v[98:99]
	s_waitcnt vmcnt(58)
	v_cvt_f32_f16_sdwa v83, v80 dst_sel:DWORD dst_unused:UNUSED_PAD src0_sel:WORD_1
	v_cvt_f32_f16_sdwa v89, v81 dst_sel:DWORD dst_unused:UNUSED_PAD src0_sel:WORD_1
	v_cvt_f32_f16_e32 v82, v80
	v_cvt_f32_f16_e32 v88, v81
	v_pk_add_f32 v[4:5], v[4:5], v[74:75]
	v_mov_b32_e32 v74, v83
	v_mov_b32_e32 v75, v89
	v_pk_add_f32 v[98:99], v[4:5], v[4:5] op_sel:[0,1] op_sel_hi:[1,0]
	v_mov_b32_e32 v4, v82
	v_mov_b32_e32 v5, v88
	v_pk_mul_f32 v[74:75], v[74:75], v[74:75]
	s_waitcnt vmcnt(57)
; __device__ __forceinline__ void norm_mod_phase2(const Args& a, Frame& F, const float* gain, const float* modl, int sh_off, int sc_off, int nrows, const float* slab_gate) {
;     ...
;     NR_FINISH(r3, nw + 3 * 2048, (nw + 3 * 2048) >> 12);
	v_cvt_f32_f16_sdwa v81, v79 dst_sel:DWORD dst_unused:UNUSED_PAD src0_sel:WORD_1
	v_pk_fma_f32 v[4:5], v[4:5], v[4:5], v[74:75]
	v_cvt_f32_f16_e32 v80, v79
	v_pk_add_f32 v[108:109], v[4:5], v[4:5] op_sel:[0,1] op_sel_hi:[1,0]
	v_cvt_f32_f16_sdwa v5, v78 dst_sel:DWORD dst_unused:UNUSED_PAD src0_sel:WORD_1
	v_cvt_f32_f16_e32 v4, v78
	s_waitcnt vmcnt(56)
	v_cvt_f32_f16_sdwa v79, v77 dst_sel:DWORD dst_unused:UNUSED_PAD src0_sel:WORD_1
	v_cvt_f32_f16_e32 v78, v77
	v_mul_f32_e32 v74, v5, v5
	v_pk_fma_f32 v[110:111], v[4:5], v[4:5], v[74:75] op_sel_hi:[1,1,0]
	v_mul_f32_e32 v74, v81, v81
	v_pk_fma_f32 v[112:113], v[80:81], v[80:81], v[74:75] op_sel_hi:[1,1,0]
	v_cvt_f32_f16_sdwa v75, v76 dst_sel:DWORD dst_unused:UNUSED_PAD src0_sel:WORD_1
	v_cvt_f32_f16_e32 v74, v76
	v_pk_mul_f32 v[114:115], v[78:79], v[78:79]
	v_pk_mul_f32 v[76:77], v[74:75], v[74:75]
	s_nop 0
	v_mov_b32_e32 v99, v76
	v_mov_b32_e32 v109, v77
	v_mov_b32_e32 v111, v114
	v_mov_b32_e32 v113, v115
	v_pk_add_f32 v[76:77], v[98:99], v[108:109]
	v_pk_add_f32 v[98:99], v[110:111], v[112:113]
	s_nop 0
	v_pk_add_f32 v[76:77], v[76:77], v[98:99]
	s_nop 0
	v_add_f32_e32 v76, v76, v77
	s_nop 1
	v_add_f32_dpp v76, v76, v76 quad_perm:[1,0,3,2] row_mask:0xf bank_mask:0xf bound_ctrl:1
	s_nop 1
	v_add_f32_dpp v76, v76, v76 quad_perm:[2,3,0,1] row_mask:0xf bank_mask:0xf bound_ctrl:1
	s_nop 1
	v_add_f32_dpp v76, v76, v76 row_half_mirror row_mask:0xf bank_mask:0xf bound_ctrl:1
	s_nop 1
	v_add_f32_dpp v76, v76, v76 row_mirror row_mask:0xf bank_mask:0xf bound_ctrl:1
	s_nop 0
	v_readlane_b32 s8, v76, 16
	v_readlane_b32 s9, v76, 48
	v_readlane_b32 s6, v76, 0
	v_readlane_b32 s7, v76, 32
	v_mov_b32_e32 v76, s8
	v_mov_b32_e32 v77, s9
	v_pk_add_f32 v[76:77], s[6:7], v[76:77]
	s_nop 0
	v_add_f32_e32 v76, v76, v77
	v_fmamk_f32 v76, v76, 0x3a000000, v252
	v_cmp_gt_f32_e32 vcc, s55, v76
	v_mul_f32_e32 v77, 0x4f800000, v76
	s_nop 0
	v_cndmask_b32_e32 v76, v76, v77, vcc
	v_sqrt_f32_e32 v77, v76
	s_nop 0
	v_add_u32_e32 v98, -1, v77
	v_fma_f32 v99, -v98, v77, v76
	v_cmp_ge_f32_e64 s[8:9], 0, v99
	v_add_u32_e32 v99, 1, v77
	s_nop 0
	v_cndmask_b32_e64 v98, v77, v98, s[8:9]
	v_fma_f32 v77, -v99, v77, v76
	v_cmp_lt_f32_e64 s[8:9], 0, v77
	s_nop 1
	v_cndmask_b32_e64 v77, v98, v99, s[8:9]
	v_mul_f32_e32 v98, 0x37800000, v77
	v_cndmask_b32_e32 v77, v77, v98, vcc
	v_cmp_class_f32_e32 vcc, v76, v253
	s_nop 1
	v_cndmask_b32_e32 v76, v77, v76, vcc
	v_div_scale_f32 v77, s[6:7], v76, v76, 1.0
	v_rcp_f32_e32 v98, v77
	s_lshl_b32 s6, s30, 1
	s_and_b32 s6, s6, 0xffffe000
	s_add_i32 s6, s6, 0
	v_fma_f32 v99, -v77, v98, 1.0
	v_fmac_f32_e32 v98, v99, v98
	v_div_scale_f32 v99, vcc, 1.0, v76, 1.0
	v_mul_f32_e32 v108, v99, v98
	v_fma_f32 v109, -v77, v108, v99
	v_fmac_f32_e32 v108, v109, v98
	v_fma_f32 v77, -v77, v108, v99
	v_div_fmas_f32 v77, v77, v98, v108
	v_div_fixup_f32 v98, v77, v76, 1.0
	v_pk_mul_f32 v[112:113], v[104:105], v[98:99] op_sel_hi:[1,0]
	v_pk_mul_f32 v[114:115], v[106:107], v[98:99] op_sel_hi:[1,0]
	v_add_u32_e32 v99, s6, v0
	ds_read_b128 v[104:107], v99
	ds_read_b128 v[108:111], v99 offset:40960
	v_lshl_add_u64 v[76:77], s[34:35], 1, v[2:3]
	v_lshl_add_u64 v[76:77], v[76:77], 0, v[6:7]
	v_pk_mul_f32 v[4:5], v[4:5], v[98:99] op_sel_hi:[1,0]
	s_waitcnt lgkmcnt(0)
	v_pk_fma_f32 v[106:107], v[106:107], v[114:115], v[110:111]
	v_pk_fma_f32 v[104:105], v[104:105], v[112:113], v[108:109]
	v_pk_mul_f32 v[108:109], v[100:101], v[98:99] op_sel_hi:[1,0]
	v_cvt_pk_bf16_f32 v104, v104, v105
	v_cvt_pk_bf16_f32 v105, v106, v107
	global_store_dwordx2 v[76:77], v[104:105], off
	v_pk_mul_f32 v[110:111], v[102:103], v[98:99] op_sel_hi:[1,0]
	ds_read_b128 v[100:103], v99 offset:1024
	ds_read_b128 v[104:107], v99 offset:41984
	s_waitcnt lgkmcnt(0)
	v_pk_fma_f32 v[102:103], v[102:103], v[110:111], v[106:107]
	v_pk_fma_f32 v[100:101], v[100:101], v[108:109], v[104:105]
	v_pk_mul_f32 v[104:105], v[90:91], v[98:99] op_sel_hi:[1,0]
	v_cvt_pk_bf16_f32 v100, v100, v101
	v_cvt_pk_bf16_f32 v101, v102, v103
	global_store_dwordx2 v[76:77], v[100:101], off offset:512
	v_pk_mul_f32 v[106:107], v[92:93], v[98:99] op_sel_hi:[1,0]
	ds_read_b128 v[90:93], v99 offset:2048
	ds_read_b128 v[100:103], v99 offset:43008
	s_waitcnt lgkmcnt(0)
	v_pk_fma_f32 v[92:93], v[92:93], v[106:107], v[102:103]
	v_pk_fma_f32 v[90:91], v[90:91], v[104:105], v[100:101]
	v_pk_mul_f32 v[100:101], v[94:95], v[98:99] op_sel_hi:[1,0]
	v_cvt_pk_bf16_f32 v90, v90, v91
	v_cvt_pk_bf16_f32 v91, v92, v93
	global_store_dwordx2 v[76:77], v[90:91], off offset:1024
	v_pk_mul_f32 v[102:103], v[96:97], v[98:99] op_sel_hi:[1,0]
	ds_read_b128 v[90:93], v99 offset:3072
	ds_read_b128 v[94:97], v99 offset:44032
	s_waitcnt lgkmcnt(0)
	v_pk_fma_f32 v[92:93], v[102:103], v[92:93], v[96:97]
	v_pk_fma_f32 v[90:91], v[100:101], v[90:91], v[94:95]
	v_pk_mul_f32 v[94:95], v[84:85], v[98:99] op_sel_hi:[1,0]
	v_cvt_pk_bf16_f32 v90, v90, v91
	v_cvt_pk_bf16_f32 v91, v92, v93
	global_store_dwordx2 v[76:77], v[90:91], off offset:1536
	v_pk_mul_f32 v[96:97], v[86:87], v[98:99] op_sel_hi:[1,0]
	ds_read_b128 v[84:87], v99 offset:4096
	ds_read_b128 v[90:93], v99 offset:45056
	s_waitcnt lgkmcnt(0)
	v_pk_fma_f32 v[86:87], v[96:97], v[86:87], v[92:93]
	v_pk_fma_f32 v[84:85], v[94:95], v[84:85], v[90:91]
	v_pk_mul_f32 v[90:91], v[82:83], v[98:99] op_sel_hi:[1,0]
	v_cvt_pk_bf16_f32 v84, v84, v85
	v_cvt_pk_bf16_f32 v85, v86, v87
	global_store_dwordx2 v[76:77], v[84:85], off offset:2048
	v_pk_mul_f32 v[92:93], v[88:89], v[98:99] op_sel_hi:[1,0]
	ds_read_b128 v[82:85], v99 offset:5120
	ds_read_b128 v[86:89], v99 offset:46080
	s_waitcnt lgkmcnt(0)
; __device__ __forceinline__ void norm_mod_phase2(const Args& a, Frame& F, const float* gain, const float* modl, int sh_off, int sc_off, int nrows, const float* slab_gate) {
;     ...
;     NR_FINISH(r3, nw + 3 * 2048, (nw + 3 * 2048) >> 12);
;     NR_FINISH(r4, nw + 4 * 2048, (nw + 4 * 2048) >> 12);
	v_pk_fma_f32 v[84:85], v[92:93], v[84:85], v[88:89]
	v_pk_fma_f32 v[82:83], v[90:91], v[82:83], v[86:87]
	v_pk_mul_f32 v[88:89], v[80:81], v[98:99] op_sel_hi:[1,0]
	v_cvt_pk_bf16_f32 v82, v82, v83
	v_cvt_pk_bf16_f32 v83, v84, v85
	global_store_dwordx2 v[76:77], v[82:83], off offset:2560
	ds_read_b128 v[80:83], v99 offset:6144
	ds_read_b128 v[84:87], v99 offset:47104
	s_waitcnt vmcnt(61)
	v_cvt_f32_f16_sdwa v91, v73 dst_sel:DWORD dst_unused:UNUSED_PAD src0_sel:WORD_1
	v_cvt_f32_f16_e32 v90, v73
	s_waitcnt lgkmcnt(0)
	v_pk_fma_f32 v[82:83], v[88:89], v[82:83], v[86:87]
	v_pk_fma_f32 v[4:5], v[4:5], v[80:81], v[84:85]
	v_cvt_f32_f16_sdwa v89, v72 dst_sel:DWORD dst_unused:UNUSED_PAD src0_sel:WORD_1
	v_cvt_pk_bf16_f32 v4, v4, v5
	v_cvt_pk_bf16_f32 v5, v82, v83
	global_store_dwordx2 v[76:77], v[4:5], off offset:3072
	v_pk_mul_f32 v[4:5], v[74:75], v[98:99] op_sel_hi:[1,0]
	v_pk_mul_f32 v[74:75], v[78:79], v[98:99] op_sel_hi:[1,0]
	ds_read_b128 v[78:81], v99 offset:7168
	ds_read_b128 v[82:85], v99 offset:48128
	v_cvt_f32_f16_e32 v88, v72
	s_waitcnt vmcnt(61)
	v_cvt_f32_f16_sdwa v87, v71 dst_sel:DWORD dst_unused:UNUSED_PAD src0_sel:WORD_1
	v_cvt_f32_f16_e32 v86, v71
	v_mov_b32_e32 v72, v91
	s_waitcnt lgkmcnt(0)
	v_pk_fma_f32 v[74:75], v[74:75], v[80:81], v[84:85]
	v_cvt_f32_f16_sdwa v85, v70 dst_sel:DWORD dst_unused:UNUSED_PAD src0_sel:WORD_1
	v_cvt_f32_f16_e32 v84, v70
	v_pk_fma_f32 v[4:5], v[4:5], v[78:79], v[82:83]
	v_mov_b32_e32 v70, v89
	v_cvt_pk_bf16_f32 v4, v4, v5
	v_cvt_pk_bf16_f32 v5, v74, v75
	global_store_dwordx2 v[76:77], v[4:5], off offset:3584
	v_mov_b32_e32 v71, v85
	s_waitcnt vmcnt(61)
	v_cvt_f32_f16_sdwa v75, v68 dst_sel:DWORD dst_unused:UNUSED_PAD src0_sel:WORD_1
	v_cvt_f32_f16_sdwa v77, v69 dst_sel:DWORD dst_unused:UNUSED_PAD src0_sel:WORD_1
	v_mov_b32_e32 v4, v88
	v_mov_b32_e32 v5, v84
	v_pk_mul_f32 v[70:71], v[70:71], v[70:71]
	v_mov_b32_e32 v73, v87
	v_cvt_f32_f16_e32 v74, v68
	v_cvt_f32_f16_e32 v76, v69
	s_waitcnt vmcnt(60)
	v_cvt_f32_f16_sdwa v79, v66 dst_sel:DWORD dst_unused:UNUSED_PAD src0_sel:WORD_1
	v_pk_fma_f32 v[4:5], v[4:5], v[4:5], v[70:71]
	v_mov_b32_e32 v70, v90
	v_mov_b32_e32 v71, v86
	v_pk_mul_f32 v[72:73], v[72:73], v[72:73]
	v_cvt_f32_f16_e32 v78, v66
	v_cvt_f32_f16_sdwa v81, v67 dst_sel:DWORD dst_unused:UNUSED_PAD src0_sel:WORD_1
	v_pk_fma_f32 v[70:71], v[70:71], v[70:71], v[72:73]
	v_cvt_f32_f16_e32 v80, v67
	v_pk_add_f32 v[4:5], v[4:5], v[70:71]
	v_mov_b32_e32 v70, v75
	v_mov_b32_e32 v71, v77
	v_mov_b32_e32 v68, v74
	v_mov_b32_e32 v69, v76
	v_pk_mul_f32 v[70:71], v[70:71], v[70:71]
	v_mul_f32_e32 v66, v79, v79
	v_pk_fma_f32 v[68:69], v[68:69], v[68:69], v[70:71]
	v_pk_fma_f32 v[72:73], v[78:79], v[78:79], v[66:67] op_sel_hi:[1,1,0]
	v_mul_f32_e32 v66, v81, v81
	v_pk_add_f32 v[70:71], v[68:69], v[68:69] op_sel:[0,1] op_sel_hi:[1,0]
	v_pk_fma_f32 v[82:83], v[80:81], v[80:81], v[66:67] op_sel_hi:[1,1,0]
	s_waitcnt vmcnt(59)
	v_cvt_f32_f16_sdwa v67, v64 dst_sel:DWORD dst_unused:UNUSED_PAD src0_sel:WORD_1
	v_cvt_f32_f16_e32 v66, v64
	v_cvt_f32_f16_sdwa v69, v65 dst_sel:DWORD dst_unused:UNUSED_PAD src0_sel:WORD_1
	v_cvt_f32_f16_e32 v68, v65
	v_pk_add_f32 v[4:5], v[4:5], v[4:5] op_sel:[0,1] op_sel_hi:[1,0]
	v_pk_mul_f32 v[64:65], v[66:67], v[66:67]
	v_pk_mul_f32 v[92:93], v[68:69], v[68:69]
	v_mov_b32_e32 v5, v64
	v_mov_b32_e32 v71, v65
	v_mov_b32_e32 v73, v92
	v_mov_b32_e32 v83, v93
	v_pk_add_f32 v[4:5], v[4:5], v[70:71]
	v_pk_add_f32 v[64:65], v[72:73], v[82:83]
	s_waitcnt vmcnt(58)
	v_cvt_f32_f16_sdwa v71, v62 dst_sel:DWORD dst_unused:UNUSED_PAD src0_sel:WORD_1
	v_cvt_f32_f16_sdwa v73, v63 dst_sel:DWORD dst_unused:UNUSED_PAD src0_sel:WORD_1
	v_cvt_f32_f16_e32 v70, v62
	v_cvt_f32_f16_e32 v72, v63
	v_pk_add_f32 v[4:5], v[4:5], v[64:65]
	v_mov_b32_e32 v62, v71
	v_mov_b32_e32 v63, v73
	v_pk_add_f32 v[82:83], v[4:5], v[4:5] op_sel:[0,1] op_sel_hi:[1,0]
	v_mov_b32_e32 v4, v70
	v_mov_b32_e32 v5, v72
	v_pk_mul_f32 v[62:63], v[62:63], v[62:63]
	s_waitcnt vmcnt(56)
	v_cvt_f32_f16_sdwa v65, v59 dst_sel:DWORD dst_unused:UNUSED_PAD src0_sel:WORD_1
	v_pk_fma_f32 v[4:5], v[4:5], v[4:5], v[62:63]
	v_cvt_f32_f16_sdwa v63, v61 dst_sel:DWORD dst_unused:UNUSED_PAD src0_sel:WORD_1
	v_pk_add_f32 v[92:93], v[4:5], v[4:5] op_sel:[0,1] op_sel_hi:[1,0]
	v_cvt_f32_f16_sdwa v5, v60 dst_sel:DWORD dst_unused:UNUSED_PAD src0_sel:WORD_1
	v_cvt_f32_f16_e32 v4, v60
	v_cvt_f32_f16_e32 v62, v61
	v_cvt_f32_f16_e32 v64, v59
	v_mul_f32_e32 v60, v5, v5
	v_pk_fma_f32 v[94:95], v[4:5], v[4:5], v[60:61] op_sel_hi:[1,1,0]
	v_mul_f32_e32 v60, v63, v63
	v_pk_fma_f32 v[96:97], v[62:63], v[62:63], v[60:61] op_sel_hi:[1,1,0]
	v_cvt_f32_f16_sdwa v61, v58 dst_sel:DWORD dst_unused:UNUSED_PAD src0_sel:WORD_1
	v_cvt_f32_f16_e32 v60, v58
	v_pk_mul_f32 v[98:99], v[64:65], v[64:65]
	v_pk_mul_f32 v[58:59], v[60:61], v[60:61]
	s_nop 0
	v_mov_b32_e32 v83, v58
	v_mov_b32_e32 v93, v59
	v_mov_b32_e32 v95, v98
	v_mov_b32_e32 v97, v99
	v_pk_add_f32 v[58:59], v[82:83], v[92:93]
	v_pk_add_f32 v[82:83], v[94:95], v[96:97]
	s_nop 0
	v_pk_add_f32 v[58:59], v[58:59], v[82:83]
	s_nop 0
	v_add_f32_e32 v58, v58, v59
	s_nop 1
	v_add_f32_dpp v58, v58, v58 quad_perm:[1,0,3,2] row_mask:0xf bank_mask:0xf bound_ctrl:1
	s_nop 1
	v_add_f32_dpp v58, v58, v58 quad_perm:[2,3,0,1] row_mask:0xf bank_mask:0xf bound_ctrl:1
	s_nop 1
	v_add_f32_dpp v58, v58, v58 row_half_mirror row_mask:0xf bank_mask:0xf bound_ctrl:1
	s_nop 1
	v_add_f32_dpp v58, v58, v58 row_mirror row_mask:0xf bank_mask:0xf bound_ctrl:1
	s_nop 0
	v_readlane_b32 s8, v58, 16
	v_readlane_b32 s9, v58, 48
	v_readlane_b32 s6, v58, 0
	v_readlane_b32 s7, v58, 32
	v_mov_b32_e32 v58, s8
	v_mov_b32_e32 v59, s9
	v_pk_add_f32 v[58:59], s[6:7], v[58:59]
; __device__ __forceinline__ void norm_mod_phase2(const Args& a, Frame& F, const float* gain, const float* modl, int sh_off, int sc_off, int nrows, const float* slab_gate) {
;     ...
;     NR_FINISH(r4, nw + 4 * 2048, (nw + 4 * 2048) >> 12);
;     NR_FINISH(r5, nw + 5 * 2048, (nw + 5 * 2048) >> 12);
	s_nop 0
	v_add_f32_e32 v58, v58, v59
	v_fmamk_f32 v58, v58, 0x3a000000, v252
	v_cmp_gt_f32_e32 vcc, s55, v58
	v_mul_f32_e32 v59, 0x4f800000, v58
	s_nop 0
	v_cndmask_b32_e32 v58, v58, v59, vcc
	v_sqrt_f32_e32 v59, v58
	s_nop 0
	v_add_u32_e32 v82, -1, v59
	v_fma_f32 v83, -v82, v59, v58
	v_cmp_ge_f32_e64 s[8:9], 0, v83
	v_add_u32_e32 v83, 1, v59
	s_nop 0
	v_cndmask_b32_e64 v82, v59, v82, s[8:9]
	v_fma_f32 v59, -v83, v59, v58
	v_cmp_lt_f32_e64 s[8:9], 0, v59
	s_nop 1
	v_cndmask_b32_e64 v59, v82, v83, s[8:9]
	v_mul_f32_e32 v82, 0x37800000, v59
	v_cndmask_b32_e32 v59, v59, v82, vcc
	v_cmp_class_f32_e32 vcc, v58, v253
	s_nop 1
	v_cndmask_b32_e32 v58, v59, v58, vcc
	v_div_scale_f32 v59, s[6:7], v58, v58, 1.0
	v_rcp_f32_e32 v82, v59
	s_lshl_b32 s6, s26, 1
	s_and_b32 s6, s6, 0xffffe000
	s_add_i32 s6, s6, 0
	v_fma_f32 v83, -v59, v82, 1.0
	v_fmac_f32_e32 v82, v83, v82
	v_div_scale_f32 v83, vcc, 1.0, v58, 1.0
	v_mul_f32_e32 v92, v83, v82
	v_fma_f32 v93, -v59, v92, v83
	v_fmac_f32_e32 v92, v93, v82
	v_fma_f32 v59, -v59, v92, v83
	v_div_fmas_f32 v59, v59, v82, v92
	v_div_fixup_f32 v82, v59, v58, 1.0
	v_pk_mul_f32 v[96:97], v[88:89], v[82:83] op_sel_hi:[1,0]
	v_pk_mul_f32 v[98:99], v[90:91], v[82:83] op_sel_hi:[1,0]
	v_add_u32_e32 v83, s6, v0
	ds_read_b128 v[88:91], v83
	ds_read_b128 v[92:95], v83 offset:40960
	v_lshl_add_u64 v[58:59], s[28:29], 1, v[2:3]
	v_lshl_add_u64 v[58:59], v[58:59], 0, v[6:7]
	v_pk_mul_f32 v[4:5], v[4:5], v[82:83] op_sel_hi:[1,0]
	v_pk_mul_f32 v[62:63], v[62:63], v[82:83] op_sel_hi:[1,0]
	s_waitcnt lgkmcnt(0)
	v_pk_fma_f32 v[90:91], v[90:91], v[98:99], v[94:95]
	v_pk_fma_f32 v[88:89], v[88:89], v[96:97], v[92:93]
	v_pk_mul_f32 v[92:93], v[84:85], v[82:83] op_sel_hi:[1,0]
	v_cvt_pk_bf16_f32 v88, v88, v89
	v_cvt_pk_bf16_f32 v89, v90, v91
	global_store_dwordx2 v[58:59], v[88:89], off
	v_pk_mul_f32 v[94:95], v[86:87], v[82:83] op_sel_hi:[1,0]
	ds_read_b128 v[84:87], v83 offset:1024
	ds_read_b128 v[88:91], v83 offset:41984
	s_waitcnt lgkmcnt(0)
	v_pk_fma_f32 v[86:87], v[86:87], v[94:95], v[90:91]
	v_pk_fma_f32 v[84:85], v[84:85], v[92:93], v[88:89]
	v_pk_mul_f32 v[88:89], v[74:75], v[82:83] op_sel_hi:[1,0]
	v_cvt_pk_bf16_f32 v84, v84, v85
	v_cvt_pk_bf16_f32 v85, v86, v87
	global_store_dwordx2 v[58:59], v[84:85], off offset:512
	v_pk_mul_f32 v[90:91], v[76:77], v[82:83] op_sel_hi:[1,0]
	ds_read_b128 v[74:77], v83 offset:2048
	ds_read_b128 v[84:87], v83 offset:43008
	s_waitcnt lgkmcnt(0)
	v_pk_fma_f32 v[76:77], v[76:77], v[90:91], v[86:87]
	v_pk_fma_f32 v[74:75], v[74:75], v[88:89], v[84:85]
	v_pk_mul_f32 v[84:85], v[78:79], v[82:83] op_sel_hi:[1,0]
	v_cvt_pk_bf16_f32 v74, v74, v75
	v_cvt_pk_bf16_f32 v75, v76, v77
	global_store_dwordx2 v[58:59], v[74:75], off offset:1024
	v_pk_mul_f32 v[86:87], v[80:81], v[82:83] op_sel_hi:[1,0]
	ds_read_b128 v[74:77], v83 offset:3072
	ds_read_b128 v[78:81], v83 offset:44032
	s_waitcnt lgkmcnt(0)
	v_pk_fma_f32 v[76:77], v[86:87], v[76:77], v[80:81]
	v_pk_fma_f32 v[74:75], v[84:85], v[74:75], v[78:79]
	v_pk_mul_f32 v[78:79], v[66:67], v[82:83] op_sel_hi:[1,0]
	v_cvt_pk_bf16_f32 v74, v74, v75
	v_cvt_pk_bf16_f32 v75, v76, v77
	global_store_dwordx2 v[58:59], v[74:75], off offset:1536
	v_pk_mul_f32 v[80:81], v[68:69], v[82:83] op_sel_hi:[1,0]
	ds_read_b128 v[66:69], v83 offset:4096
	ds_read_b128 v[74:77], v83 offset:45056
	s_waitcnt lgkmcnt(0)
	v_pk_fma_f32 v[68:69], v[80:81], v[68:69], v[76:77]
	v_pk_fma_f32 v[66:67], v[78:79], v[66:67], v[74:75]
	v_pk_mul_f32 v[74:75], v[70:71], v[82:83] op_sel_hi:[1,0]
	v_cvt_pk_bf16_f32 v66, v66, v67
	v_cvt_pk_bf16_f32 v67, v68, v69
	global_store_dwordx2 v[58:59], v[66:67], off offset:2048
	v_pk_mul_f32 v[76:77], v[72:73], v[82:83] op_sel_hi:[1,0]
	ds_read_b128 v[66:69], v83 offset:5120
	ds_read_b128 v[70:73], v83 offset:46080
	s_waitcnt lgkmcnt(0)
	v_pk_fma_f32 v[68:69], v[76:77], v[68:69], v[72:73]
	v_pk_fma_f32 v[66:67], v[74:75], v[66:67], v[70:71]
	s_waitcnt vmcnt(60)
	v_cvt_f32_f16_sdwa v75, v57 dst_sel:DWORD dst_unused:UNUSED_PAD src0_sel:WORD_1
	v_cvt_pk_bf16_f32 v66, v66, v67
	v_cvt_pk_bf16_f32 v67, v68, v69
	global_store_dwordx2 v[58:59], v[66:67], off offset:2560
	ds_read_b128 v[66:69], v83 offset:6144
	ds_read_b128 v[70:73], v83 offset:47104
	v_cvt_f32_f16_e32 v74, v57
	s_waitcnt lgkmcnt(0)
	v_pk_fma_f32 v[62:63], v[62:63], v[68:69], v[72:73]
	v_pk_fma_f32 v[4:5], v[4:5], v[66:67], v[70:71]
	v_pk_mul_f32 v[68:69], v[64:65], v[82:83] op_sel_hi:[1,0]
	v_cvt_pk_bf16_f32 v4, v4, v5
	v_cvt_pk_bf16_f32 v5, v62, v63
	global_store_dwordx2 v[58:59], v[4:5], off offset:3072
	v_pk_mul_f32 v[4:5], v[60:61], v[82:83] op_sel_hi:[1,0]
	ds_read_b128 v[60:63], v83 offset:7168
	ds_read_b128 v[64:67], v83 offset:48128
	v_cvt_f32_f16_sdwa v73, v56 dst_sel:DWORD dst_unused:UNUSED_PAD src0_sel:WORD_1
	v_cvt_f32_f16_e32 v72, v56
	s_waitcnt vmcnt(61)
	v_cvt_f32_f16_sdwa v71, v55 dst_sel:DWORD dst_unused:UNUSED_PAD src0_sel:WORD_1
	v_cvt_f32_f16_e32 v70, v55
	s_waitcnt lgkmcnt(0)
	v_pk_fma_f32 v[62:63], v[68:69], v[62:63], v[66:67]
	v_cvt_f32_f16_sdwa v69, v54 dst_sel:DWORD dst_unused:UNUSED_PAD src0_sel:WORD_1
	v_cvt_f32_f16_e32 v68, v54
	v_pk_fma_f32 v[4:5], v[4:5], v[60:61], v[64:65]
	v_mov_b32_e32 v54, v73
	v_cvt_pk_bf16_f32 v4, v4, v5
	v_cvt_pk_bf16_f32 v5, v62, v63
	global_store_dwordx2 v[58:59], v[4:5], off offset:3584
	v_mov_b32_e32 v55, v69
	s_waitcnt vmcnt(61)
	v_cvt_f32_f16_sdwa v59, v52 dst_sel:DWORD dst_unused:UNUSED_PAD src0_sel:WORD_1
	v_cvt_f32_f16_sdwa v61, v53 dst_sel:DWORD dst_unused:UNUSED_PAD src0_sel:WORD_1
	v_mov_b32_e32 v4, v72
	v_mov_b32_e32 v5, v68
	v_pk_mul_f32 v[54:55], v[54:55], v[54:55]
	v_mov_b32_e32 v56, v75
	v_mov_b32_e32 v57, v71
	v_cvt_f32_f16_e32 v58, v52
	v_cvt_f32_f16_e32 v60, v53
	s_waitcnt vmcnt(60)
; __device__ __forceinline__ void norm_mod_phase2(const Args& a, Frame& F, const float* gain, const float* modl, int sh_off, int sc_off, int nrows, const float* slab_gate) {
;     ...
;     NR_FINISH(r5, nw + 5 * 2048, (nw + 5 * 2048) >> 12);
	v_cvt_f32_f16_sdwa v63, v50 dst_sel:DWORD dst_unused:UNUSED_PAD src0_sel:WORD_1
	v_pk_fma_f32 v[4:5], v[4:5], v[4:5], v[54:55]
	v_mov_b32_e32 v54, v74
	v_mov_b32_e32 v55, v70
	v_pk_mul_f32 v[56:57], v[56:57], v[56:57]
	v_cvt_f32_f16_e32 v62, v50
	v_cvt_f32_f16_sdwa v65, v51 dst_sel:DWORD dst_unused:UNUSED_PAD src0_sel:WORD_1
	v_pk_fma_f32 v[54:55], v[54:55], v[54:55], v[56:57]
	v_cvt_f32_f16_e32 v64, v51
	v_pk_add_f32 v[4:5], v[4:5], v[54:55]
	v_mov_b32_e32 v54, v59
	v_mov_b32_e32 v55, v61
	v_mov_b32_e32 v52, v58
	v_mov_b32_e32 v53, v60
	v_pk_mul_f32 v[54:55], v[54:55], v[54:55]
	v_mul_f32_e32 v50, v63, v63
	v_pk_fma_f32 v[52:53], v[52:53], v[52:53], v[54:55]
	v_pk_fma_f32 v[56:57], v[62:63], v[62:63], v[50:51] op_sel_hi:[1,1,0]
	v_mul_f32_e32 v50, v65, v65
	v_pk_add_f32 v[54:55], v[52:53], v[52:53] op_sel:[0,1] op_sel_hi:[1,0]
	v_pk_fma_f32 v[66:67], v[64:65], v[64:65], v[50:51] op_sel_hi:[1,1,0]
	s_waitcnt vmcnt(59)
	v_cvt_f32_f16_sdwa v51, v48 dst_sel:DWORD dst_unused:UNUSED_PAD src0_sel:WORD_1
	v_cvt_f32_f16_e32 v50, v48
	v_cvt_f32_f16_sdwa v53, v49 dst_sel:DWORD dst_unused:UNUSED_PAD src0_sel:WORD_1
	v_cvt_f32_f16_e32 v52, v49
	v_pk_add_f32 v[4:5], v[4:5], v[4:5] op_sel:[0,1] op_sel_hi:[1,0]
	v_pk_mul_f32 v[48:49], v[50:51], v[50:51]
	v_pk_mul_f32 v[76:77], v[52:53], v[52:53]
	v_mov_b32_e32 v5, v48
	v_mov_b32_e32 v55, v49
	v_mov_b32_e32 v57, v76
	v_mov_b32_e32 v67, v77
	v_pk_add_f32 v[4:5], v[4:5], v[54:55]
	v_pk_add_f32 v[48:49], v[56:57], v[66:67]
	s_waitcnt vmcnt(58)
	v_cvt_f32_f16_sdwa v55, v46 dst_sel:DWORD dst_unused:UNUSED_PAD src0_sel:WORD_1
	v_cvt_f32_f16_sdwa v57, v47 dst_sel:DWORD dst_unused:UNUSED_PAD src0_sel:WORD_1
	v_cvt_f32_f16_e32 v54, v46
	v_cvt_f32_f16_e32 v56, v47
	v_pk_add_f32 v[4:5], v[4:5], v[48:49]
	v_mov_b32_e32 v46, v55
	v_mov_b32_e32 v47, v57
	v_pk_add_f32 v[66:67], v[4:5], v[4:5] op_sel:[0,1] op_sel_hi:[1,0]
	v_mov_b32_e32 v4, v54
	v_mov_b32_e32 v5, v56
	v_pk_mul_f32 v[46:47], v[46:47], v[46:47]
	s_waitcnt vmcnt(56)
	v_cvt_f32_f16_sdwa v49, v43 dst_sel:DWORD dst_unused:UNUSED_PAD src0_sel:WORD_1
	v_pk_fma_f32 v[4:5], v[4:5], v[4:5], v[46:47]
	v_cvt_f32_f16_sdwa v47, v45 dst_sel:DWORD dst_unused:UNUSED_PAD src0_sel:WORD_1
	v_pk_add_f32 v[76:77], v[4:5], v[4:5] op_sel:[0,1] op_sel_hi:[1,0]
	v_cvt_f32_f16_sdwa v5, v44 dst_sel:DWORD dst_unused:UNUSED_PAD src0_sel:WORD_1
	v_cvt_f32_f16_e32 v4, v44
	v_cvt_f32_f16_e32 v46, v45
	v_cvt_f32_f16_e32 v48, v43
	v_mul_f32_e32 v44, v5, v5
	v_pk_fma_f32 v[78:79], v[4:5], v[4:5], v[44:45] op_sel_hi:[1,1,0]
	v_mul_f32_e32 v44, v47, v47
	v_pk_fma_f32 v[80:81], v[46:47], v[46:47], v[44:45] op_sel_hi:[1,1,0]
	v_cvt_f32_f16_sdwa v45, v42 dst_sel:DWORD dst_unused:UNUSED_PAD src0_sel:WORD_1
	v_cvt_f32_f16_e32 v44, v42
	v_pk_mul_f32 v[82:83], v[48:49], v[48:49]
	v_pk_mul_f32 v[42:43], v[44:45], v[44:45]
	s_nop 0
	v_mov_b32_e32 v67, v42
	v_mov_b32_e32 v77, v43
	v_mov_b32_e32 v79, v82
	v_mov_b32_e32 v81, v83
	v_pk_add_f32 v[42:43], v[66:67], v[76:77]
	v_pk_add_f32 v[66:67], v[78:79], v[80:81]
	s_nop 0
	v_pk_add_f32 v[42:43], v[42:43], v[66:67]
	s_nop 0
	v_add_f32_e32 v42, v42, v43
	s_nop 1
	v_add_f32_dpp v42, v42, v42 quad_perm:[1,0,3,2] row_mask:0xf bank_mask:0xf bound_ctrl:1
	s_nop 1
	v_add_f32_dpp v42, v42, v42 quad_perm:[2,3,0,1] row_mask:0xf bank_mask:0xf bound_ctrl:1
	s_nop 1
	v_add_f32_dpp v42, v42, v42 row_half_mirror row_mask:0xf bank_mask:0xf bound_ctrl:1
	s_nop 1
	v_add_f32_dpp v42, v42, v42 row_mirror row_mask:0xf bank_mask:0xf bound_ctrl:1
	s_nop 0
	v_readlane_b32 s8, v42, 16
	v_readlane_b32 s9, v42, 48
	v_readlane_b32 s6, v42, 0
	v_readlane_b32 s7, v42, 32
	v_mov_b32_e32 v42, s8
	v_mov_b32_e32 v43, s9
	v_pk_add_f32 v[42:43], s[6:7], v[42:43]
	s_nop 0
	v_add_f32_e32 v42, v42, v43
	v_fmamk_f32 v42, v42, 0x3a000000, v252
	v_cmp_gt_f32_e32 vcc, s55, v42
	v_mul_f32_e32 v43, 0x4f800000, v42
	s_nop 0
	v_cndmask_b32_e32 v42, v42, v43, vcc
	v_sqrt_f32_e32 v43, v42
	s_nop 0
	v_add_u32_e32 v66, -1, v43
	v_fma_f32 v67, -v66, v43, v42
	v_cmp_ge_f32_e64 s[8:9], 0, v67
	v_add_u32_e32 v67, 1, v43
	s_nop 0
	v_cndmask_b32_e64 v66, v43, v66, s[8:9]
	v_fma_f32 v43, -v67, v43, v42
	v_cmp_lt_f32_e64 s[8:9], 0, v43
	s_nop 1
	v_cndmask_b32_e64 v43, v66, v67, s[8:9]
	v_mul_f32_e32 v66, 0x37800000, v43
	v_cndmask_b32_e32 v43, v43, v66, vcc
	v_cmp_class_f32_e32 vcc, v42, v253
	s_nop 1
	v_cndmask_b32_e32 v42, v43, v42, vcc
	v_div_scale_f32 v43, s[6:7], v42, v42, 1.0
	v_rcp_f32_e32 v66, v43
	s_lshl_b32 s6, s22, 1
	s_and_b32 s6, s6, 0xffffe000
	s_add_i32 s6, s6, 0
	v_fma_f32 v67, -v43, v66, 1.0
	v_fmac_f32_e32 v66, v67, v66
	v_div_scale_f32 v67, vcc, 1.0, v42, 1.0
	v_mul_f32_e32 v76, v67, v66
	v_fma_f32 v77, -v43, v76, v67
	v_fmac_f32_e32 v76, v77, v66
	v_fma_f32 v43, -v43, v76, v67
	v_div_fmas_f32 v43, v43, v66, v76
	v_div_fixup_f32 v66, v43, v42, 1.0
	v_pk_mul_f32 v[80:81], v[72:73], v[66:67] op_sel_hi:[1,0]
	v_pk_mul_f32 v[82:83], v[74:75], v[66:67] op_sel_hi:[1,0]
	v_add_u32_e32 v67, s6, v0
	ds_read_b128 v[72:75], v67
	ds_read_b128 v[76:79], v67 offset:40960
	v_lshl_add_u64 v[42:43], s[24:25], 1, v[2:3]
	v_lshl_add_u64 v[42:43], v[42:43], 0, v[6:7]
	v_pk_mul_f32 v[4:5], v[4:5], v[66:67] op_sel_hi:[1,0]
	v_pk_mul_f32 v[46:47], v[46:47], v[66:67] op_sel_hi:[1,0]
	s_waitcnt lgkmcnt(0)
	v_pk_fma_f32 v[74:75], v[74:75], v[82:83], v[78:79]
	v_pk_fma_f32 v[72:73], v[72:73], v[80:81], v[76:77]
	v_pk_mul_f32 v[76:77], v[68:69], v[66:67] op_sel_hi:[1,0]
	v_cvt_pk_bf16_f32 v72, v72, v73
	v_cvt_pk_bf16_f32 v73, v74, v75
	global_store_dwordx2 v[42:43], v[72:73], off
	v_pk_mul_f32 v[78:79], v[70:71], v[66:67] op_sel_hi:[1,0]
	ds_read_b128 v[68:71], v67 offset:1024
	ds_read_b128 v[72:75], v67 offset:41984
	s_waitcnt lgkmcnt(0)
; __device__ __forceinline__ void norm_mod_phase2(const Args& a, Frame& F, const float* gain, const float* modl, int sh_off, int sc_off, int nrows, const float* slab_gate) {
;     ...
;     NR_FINISH(r5, nw + 5 * 2048, (nw + 5 * 2048) >> 12);
;     NR_FINISH(r6, nw + 6 * 2048, (nw + 6 * 2048) >> 12);
	v_pk_fma_f32 v[70:71], v[70:71], v[78:79], v[74:75]
	v_pk_fma_f32 v[68:69], v[68:69], v[76:77], v[72:73]
	v_pk_mul_f32 v[72:73], v[58:59], v[66:67] op_sel_hi:[1,0]
	v_cvt_pk_bf16_f32 v68, v68, v69
	v_cvt_pk_bf16_f32 v69, v70, v71
	global_store_dwordx2 v[42:43], v[68:69], off offset:512
	v_pk_mul_f32 v[74:75], v[60:61], v[66:67] op_sel_hi:[1,0]
	ds_read_b128 v[58:61], v67 offset:2048
	ds_read_b128 v[68:71], v67 offset:43008
	s_waitcnt lgkmcnt(0)
	v_pk_fma_f32 v[60:61], v[60:61], v[74:75], v[70:71]
	v_pk_fma_f32 v[58:59], v[58:59], v[72:73], v[68:69]
	v_pk_mul_f32 v[68:69], v[62:63], v[66:67] op_sel_hi:[1,0]
	v_cvt_pk_bf16_f32 v58, v58, v59
	v_cvt_pk_bf16_f32 v59, v60, v61
	global_store_dwordx2 v[42:43], v[58:59], off offset:1024
	v_pk_mul_f32 v[70:71], v[64:65], v[66:67] op_sel_hi:[1,0]
	ds_read_b128 v[58:61], v67 offset:3072
	ds_read_b128 v[62:65], v67 offset:44032
	s_waitcnt lgkmcnt(0)
	v_pk_fma_f32 v[60:61], v[70:71], v[60:61], v[64:65]
	v_pk_fma_f32 v[58:59], v[68:69], v[58:59], v[62:63]
	v_pk_mul_f32 v[62:63], v[50:51], v[66:67] op_sel_hi:[1,0]
	v_cvt_pk_bf16_f32 v58, v58, v59
	v_cvt_pk_bf16_f32 v59, v60, v61
	global_store_dwordx2 v[42:43], v[58:59], off offset:1536
	v_pk_mul_f32 v[64:65], v[52:53], v[66:67] op_sel_hi:[1,0]
	ds_read_b128 v[50:53], v67 offset:4096
	ds_read_b128 v[58:61], v67 offset:45056
	s_waitcnt lgkmcnt(0)
	v_pk_fma_f32 v[52:53], v[64:65], v[52:53], v[60:61]
	v_pk_fma_f32 v[50:51], v[62:63], v[50:51], v[58:59]
	v_pk_mul_f32 v[58:59], v[54:55], v[66:67] op_sel_hi:[1,0]
	v_cvt_pk_bf16_f32 v50, v50, v51
	v_cvt_pk_bf16_f32 v51, v52, v53
	global_store_dwordx2 v[42:43], v[50:51], off offset:2048
	v_pk_mul_f32 v[60:61], v[56:57], v[66:67] op_sel_hi:[1,0]
	ds_read_b128 v[50:53], v67 offset:5120
	ds_read_b128 v[54:57], v67 offset:46080
	s_waitcnt lgkmcnt(0)
	v_pk_fma_f32 v[52:53], v[60:61], v[52:53], v[56:57]
	v_pk_fma_f32 v[50:51], v[58:59], v[50:51], v[54:55]
	s_waitcnt vmcnt(60)
	v_cvt_f32_f16_sdwa v59, v41 dst_sel:DWORD dst_unused:UNUSED_PAD src0_sel:WORD_1
	v_cvt_pk_bf16_f32 v50, v50, v51
	v_cvt_pk_bf16_f32 v51, v52, v53
	global_store_dwordx2 v[42:43], v[50:51], off offset:2560
	ds_read_b128 v[50:53], v67 offset:6144
	ds_read_b128 v[54:57], v67 offset:47104
	v_cvt_f32_f16_e32 v58, v41
	s_waitcnt lgkmcnt(0)
	v_pk_fma_f32 v[46:47], v[46:47], v[52:53], v[56:57]
	v_pk_fma_f32 v[4:5], v[4:5], v[50:51], v[54:55]
	v_pk_mul_f32 v[52:53], v[48:49], v[66:67] op_sel_hi:[1,0]
	v_cvt_pk_bf16_f32 v4, v4, v5
	v_cvt_pk_bf16_f32 v5, v46, v47
	global_store_dwordx2 v[42:43], v[4:5], off offset:3072
	v_pk_mul_f32 v[4:5], v[44:45], v[66:67] op_sel_hi:[1,0]
	ds_read_b128 v[44:47], v67 offset:7168
	ds_read_b128 v[48:51], v67 offset:48128
	v_cvt_f32_f16_sdwa v57, v40 dst_sel:DWORD dst_unused:UNUSED_PAD src0_sel:WORD_1
	v_cvt_f32_f16_e32 v56, v40
	s_waitcnt vmcnt(61)
	v_cvt_f32_f16_sdwa v55, v39 dst_sel:DWORD dst_unused:UNUSED_PAD src0_sel:WORD_1
	v_cvt_f32_f16_e32 v54, v39
	s_waitcnt lgkmcnt(0)
	v_pk_fma_f32 v[46:47], v[52:53], v[46:47], v[50:51]
	v_cvt_f32_f16_sdwa v53, v38 dst_sel:DWORD dst_unused:UNUSED_PAD src0_sel:WORD_1
	v_cvt_f32_f16_e32 v52, v38
	v_pk_fma_f32 v[4:5], v[4:5], v[44:45], v[48:49]
	v_mov_b32_e32 v38, v57
	v_cvt_pk_bf16_f32 v4, v4, v5
	v_cvt_pk_bf16_f32 v5, v46, v47
	global_store_dwordx2 v[42:43], v[4:5], off offset:3584
	v_mov_b32_e32 v39, v53
	s_waitcnt vmcnt(61)
	v_cvt_f32_f16_sdwa v43, v36 dst_sel:DWORD dst_unused:UNUSED_PAD src0_sel:WORD_1
	v_cvt_f32_f16_sdwa v45, v37 dst_sel:DWORD dst_unused:UNUSED_PAD src0_sel:WORD_1
	v_mov_b32_e32 v4, v56
	v_mov_b32_e32 v5, v52
	v_pk_mul_f32 v[38:39], v[38:39], v[38:39]
	v_mov_b32_e32 v40, v59
	v_mov_b32_e32 v41, v55
	v_cvt_f32_f16_e32 v42, v36
	v_cvt_f32_f16_e32 v44, v37
	s_waitcnt vmcnt(60)
	v_cvt_f32_f16_sdwa v47, v34 dst_sel:DWORD dst_unused:UNUSED_PAD src0_sel:WORD_1
	v_pk_fma_f32 v[4:5], v[4:5], v[4:5], v[38:39]
	v_mov_b32_e32 v38, v58
	v_mov_b32_e32 v39, v54
	v_pk_mul_f32 v[40:41], v[40:41], v[40:41]
	v_cvt_f32_f16_e32 v46, v34
	v_cvt_f32_f16_sdwa v49, v35 dst_sel:DWORD dst_unused:UNUSED_PAD src0_sel:WORD_1
	v_pk_fma_f32 v[38:39], v[38:39], v[38:39], v[40:41]
	v_cvt_f32_f16_e32 v48, v35
	v_pk_add_f32 v[4:5], v[4:5], v[38:39]
	v_mov_b32_e32 v38, v43
	v_mov_b32_e32 v39, v45
	v_mov_b32_e32 v36, v42
	v_mov_b32_e32 v37, v44
	v_pk_mul_f32 v[38:39], v[38:39], v[38:39]
	v_mul_f32_e32 v34, v47, v47
	v_pk_fma_f32 v[36:37], v[36:37], v[36:37], v[38:39]
	v_pk_fma_f32 v[40:41], v[46:47], v[46:47], v[34:35] op_sel_hi:[1,1,0]
	v_mul_f32_e32 v34, v49, v49
	v_pk_add_f32 v[38:39], v[36:37], v[36:37] op_sel:[0,1] op_sel_hi:[1,0]
	v_pk_fma_f32 v[50:51], v[48:49], v[48:49], v[34:35] op_sel_hi:[1,1,0]
	s_waitcnt vmcnt(59)
	v_cvt_f32_f16_sdwa v35, v32 dst_sel:DWORD dst_unused:UNUSED_PAD src0_sel:WORD_1
	v_cvt_f32_f16_e32 v34, v32
	v_cvt_f32_f16_sdwa v37, v33 dst_sel:DWORD dst_unused:UNUSED_PAD src0_sel:WORD_1
	v_cvt_f32_f16_e32 v36, v33
	v_pk_add_f32 v[4:5], v[4:5], v[4:5] op_sel:[0,1] op_sel_hi:[1,0]
	v_pk_mul_f32 v[32:33], v[34:35], v[34:35]
	v_pk_mul_f32 v[60:61], v[36:37], v[36:37]
	v_mov_b32_e32 v5, v32
	v_mov_b32_e32 v39, v33
	v_mov_b32_e32 v41, v60
	v_mov_b32_e32 v51, v61
	v_pk_add_f32 v[4:5], v[4:5], v[38:39]
	v_pk_add_f32 v[32:33], v[40:41], v[50:51]
	s_waitcnt vmcnt(58)
	v_cvt_f32_f16_sdwa v39, v30 dst_sel:DWORD dst_unused:UNUSED_PAD src0_sel:WORD_1
	v_cvt_f32_f16_sdwa v41, v31 dst_sel:DWORD dst_unused:UNUSED_PAD src0_sel:WORD_1
	v_cvt_f32_f16_e32 v38, v30
	v_cvt_f32_f16_e32 v40, v31
	v_pk_add_f32 v[4:5], v[4:5], v[32:33]
	v_mov_b32_e32 v30, v39
	v_mov_b32_e32 v31, v41
	v_pk_add_f32 v[50:51], v[4:5], v[4:5] op_sel:[0,1] op_sel_hi:[1,0]
	v_mov_b32_e32 v4, v38
	v_mov_b32_e32 v5, v40
	v_pk_mul_f32 v[30:31], v[30:31], v[30:31]
	s_waitcnt vmcnt(56)
; __device__ __forceinline__ void norm_mod_phase2(const Args& a, Frame& F, const float* gain, const float* modl, int sh_off, int sc_off, int nrows, const float* slab_gate) {
;     ...
;     NR_FINISH(r6, nw + 6 * 2048, (nw + 6 * 2048) >> 12);
	v_cvt_f32_f16_sdwa v33, v27 dst_sel:DWORD dst_unused:UNUSED_PAD src0_sel:WORD_1
	v_pk_fma_f32 v[4:5], v[4:5], v[4:5], v[30:31]
	v_cvt_f32_f16_sdwa v31, v29 dst_sel:DWORD dst_unused:UNUSED_PAD src0_sel:WORD_1
	v_pk_add_f32 v[60:61], v[4:5], v[4:5] op_sel:[0,1] op_sel_hi:[1,0]
	v_cvt_f32_f16_sdwa v5, v28 dst_sel:DWORD dst_unused:UNUSED_PAD src0_sel:WORD_1
	v_cvt_f32_f16_e32 v4, v28
	v_cvt_f32_f16_e32 v30, v29
	v_cvt_f32_f16_e32 v32, v27
	v_mul_f32_e32 v28, v5, v5
	v_pk_fma_f32 v[62:63], v[4:5], v[4:5], v[28:29] op_sel_hi:[1,1,0]
	v_mul_f32_e32 v28, v31, v31
	v_pk_fma_f32 v[64:65], v[30:31], v[30:31], v[28:29] op_sel_hi:[1,1,0]
	v_cvt_f32_f16_sdwa v29, v26 dst_sel:DWORD dst_unused:UNUSED_PAD src0_sel:WORD_1
	v_cvt_f32_f16_e32 v28, v26
	v_pk_mul_f32 v[66:67], v[32:33], v[32:33]
	v_pk_mul_f32 v[26:27], v[28:29], v[28:29]
	s_nop 0
	v_mov_b32_e32 v51, v26
	v_mov_b32_e32 v61, v27
	v_mov_b32_e32 v63, v66
	v_mov_b32_e32 v65, v67
	v_pk_add_f32 v[26:27], v[50:51], v[60:61]
	v_pk_add_f32 v[50:51], v[62:63], v[64:65]
	s_nop 0
	v_pk_add_f32 v[26:27], v[26:27], v[50:51]
	s_nop 0
	v_add_f32_e32 v26, v26, v27
	s_nop 1
	v_add_f32_dpp v26, v26, v26 quad_perm:[1,0,3,2] row_mask:0xf bank_mask:0xf bound_ctrl:1
	s_nop 1
	v_add_f32_dpp v26, v26, v26 quad_perm:[2,3,0,1] row_mask:0xf bank_mask:0xf bound_ctrl:1
	s_nop 1
	v_add_f32_dpp v26, v26, v26 row_half_mirror row_mask:0xf bank_mask:0xf bound_ctrl:1
	s_nop 1
	v_add_f32_dpp v26, v26, v26 row_mirror row_mask:0xf bank_mask:0xf bound_ctrl:1
	s_nop 0
	v_readlane_b32 s8, v26, 16
	v_readlane_b32 s9, v26, 48
	v_readlane_b32 s6, v26, 0
	v_readlane_b32 s7, v26, 32
	v_mov_b32_e32 v26, s8
	v_mov_b32_e32 v27, s9
	v_pk_add_f32 v[26:27], s[6:7], v[26:27]
	s_nop 0
	v_add_f32_e32 v26, v26, v27
	v_fmamk_f32 v26, v26, 0x3a000000, v252
	v_cmp_gt_f32_e32 vcc, s55, v26
	v_mul_f32_e32 v27, 0x4f800000, v26
	s_nop 0
	v_cndmask_b32_e32 v26, v26, v27, vcc
	v_sqrt_f32_e32 v27, v26
	s_nop 0
	v_add_u32_e32 v50, -1, v27
	v_fma_f32 v51, -v50, v27, v26
	v_cmp_ge_f32_e64 s[8:9], 0, v51
	v_add_u32_e32 v51, 1, v27
	s_nop 0
	v_cndmask_b32_e64 v50, v27, v50, s[8:9]
	v_fma_f32 v27, -v51, v27, v26
	v_cmp_lt_f32_e64 s[8:9], 0, v27
	s_nop 1
	v_cndmask_b32_e64 v27, v50, v51, s[8:9]
	v_mul_f32_e32 v50, 0x37800000, v27
	v_cndmask_b32_e32 v27, v27, v50, vcc
	v_cmp_class_f32_e32 vcc, v26, v253
	s_nop 1
	v_cndmask_b32_e32 v26, v27, v26, vcc
	v_div_scale_f32 v27, s[6:7], v26, v26, 1.0
	v_rcp_f32_e32 v50, v27
	s_lshl_b32 s6, s18, 1
	s_and_b32 s6, s6, 0xffffe000
	s_add_i32 s6, s6, 0
	v_fma_f32 v51, -v27, v50, 1.0
	v_fmac_f32_e32 v50, v51, v50
	v_div_scale_f32 v51, vcc, 1.0, v26, 1.0
	v_mul_f32_e32 v60, v51, v50
	v_fma_f32 v61, -v27, v60, v51
	v_fmac_f32_e32 v60, v61, v50
	v_fma_f32 v27, -v27, v60, v51
	v_div_fmas_f32 v27, v27, v50, v60
	v_div_fixup_f32 v50, v27, v26, 1.0
	v_pk_mul_f32 v[64:65], v[56:57], v[50:51] op_sel_hi:[1,0]
	v_pk_mul_f32 v[66:67], v[58:59], v[50:51] op_sel_hi:[1,0]
	v_add_u32_e32 v51, s6, v0
	ds_read_b128 v[56:59], v51
	ds_read_b128 v[60:63], v51 offset:40960
	v_lshl_add_u64 v[26:27], s[20:21], 1, v[2:3]
	v_lshl_add_u64 v[26:27], v[26:27], 0, v[6:7]
	v_pk_mul_f32 v[4:5], v[4:5], v[50:51] op_sel_hi:[1,0]
	v_pk_mul_f32 v[30:31], v[30:31], v[50:51] op_sel_hi:[1,0]
	s_waitcnt lgkmcnt(0)
	v_pk_fma_f32 v[58:59], v[58:59], v[66:67], v[62:63]
	v_pk_fma_f32 v[56:57], v[56:57], v[64:65], v[60:61]
	v_pk_mul_f32 v[60:61], v[52:53], v[50:51] op_sel_hi:[1,0]
	v_cvt_pk_bf16_f32 v56, v56, v57
	v_cvt_pk_bf16_f32 v57, v58, v59
	global_store_dwordx2 v[26:27], v[56:57], off
	v_pk_mul_f32 v[62:63], v[54:55], v[50:51] op_sel_hi:[1,0]
	ds_read_b128 v[52:55], v51 offset:1024
	ds_read_b128 v[56:59], v51 offset:41984
	s_waitcnt lgkmcnt(0)
	v_pk_fma_f32 v[54:55], v[54:55], v[62:63], v[58:59]
	v_pk_fma_f32 v[52:53], v[52:53], v[60:61], v[56:57]
	v_pk_mul_f32 v[56:57], v[42:43], v[50:51] op_sel_hi:[1,0]
	v_cvt_pk_bf16_f32 v52, v52, v53
	v_cvt_pk_bf16_f32 v53, v54, v55
	global_store_dwordx2 v[26:27], v[52:53], off offset:512
	v_pk_mul_f32 v[58:59], v[44:45], v[50:51] op_sel_hi:[1,0]
	ds_read_b128 v[42:45], v51 offset:2048
	ds_read_b128 v[52:55], v51 offset:43008
	s_waitcnt lgkmcnt(0)
	v_pk_fma_f32 v[44:45], v[44:45], v[58:59], v[54:55]
	v_pk_fma_f32 v[42:43], v[42:43], v[56:57], v[52:53]
	v_pk_mul_f32 v[52:53], v[46:47], v[50:51] op_sel_hi:[1,0]
	v_cvt_pk_bf16_f32 v42, v42, v43
	v_cvt_pk_bf16_f32 v43, v44, v45
	global_store_dwordx2 v[26:27], v[42:43], off offset:1024
	v_pk_mul_f32 v[54:55], v[48:49], v[50:51] op_sel_hi:[1,0]
	ds_read_b128 v[42:45], v51 offset:3072
	ds_read_b128 v[46:49], v51 offset:44032
	s_waitcnt lgkmcnt(0)
	v_pk_fma_f32 v[44:45], v[54:55], v[44:45], v[48:49]
	v_pk_fma_f32 v[42:43], v[52:53], v[42:43], v[46:47]
	v_pk_mul_f32 v[46:47], v[34:35], v[50:51] op_sel_hi:[1,0]
	v_cvt_pk_bf16_f32 v42, v42, v43
	v_cvt_pk_bf16_f32 v43, v44, v45
	global_store_dwordx2 v[26:27], v[42:43], off offset:1536
	v_pk_mul_f32 v[48:49], v[36:37], v[50:51] op_sel_hi:[1,0]
	ds_read_b128 v[34:37], v51 offset:4096
	ds_read_b128 v[42:45], v51 offset:45056
	s_waitcnt lgkmcnt(0)
	v_pk_fma_f32 v[36:37], v[48:49], v[36:37], v[44:45]
	v_pk_fma_f32 v[34:35], v[46:47], v[34:35], v[42:43]
	v_pk_mul_f32 v[42:43], v[38:39], v[50:51] op_sel_hi:[1,0]
	v_cvt_pk_bf16_f32 v34, v34, v35
	v_cvt_pk_bf16_f32 v35, v36, v37
	global_store_dwordx2 v[26:27], v[34:35], off offset:2048
	v_pk_mul_f32 v[44:45], v[40:41], v[50:51] op_sel_hi:[1,0]
	ds_read_b128 v[34:37], v51 offset:5120
	ds_read_b128 v[38:41], v51 offset:46080
	s_waitcnt lgkmcnt(0)
	v_pk_fma_f32 v[36:37], v[44:45], v[36:37], v[40:41]
	v_pk_fma_f32 v[34:35], v[42:43], v[34:35], v[38:39]
	s_waitcnt vmcnt(60)
; __device__ __forceinline__ void norm_mod_phase2(const Args& a, Frame& F, const float* gain, const float* modl, int sh_off, int sc_off, int nrows, const float* slab_gate) {
;     ...
;     NR_FINISH(r6, nw + 6 * 2048, (nw + 6 * 2048) >> 12);
;     NR_FINISH(r7, nw + 7 * 2048, (nw + 7 * 2048) >> 12);
	v_cvt_f32_f16_sdwa v43, v25 dst_sel:DWORD dst_unused:UNUSED_PAD src0_sel:WORD_1
	v_cvt_pk_bf16_f32 v34, v34, v35
	v_cvt_pk_bf16_f32 v35, v36, v37
	global_store_dwordx2 v[26:27], v[34:35], off offset:2560
	ds_read_b128 v[34:37], v51 offset:6144
	ds_read_b128 v[38:41], v51 offset:47104
	v_cvt_f32_f16_e32 v42, v25
	s_waitcnt lgkmcnt(0)
	v_pk_fma_f32 v[30:31], v[30:31], v[36:37], v[40:41]
	v_pk_fma_f32 v[4:5], v[4:5], v[34:35], v[38:39]
	v_pk_mul_f32 v[36:37], v[32:33], v[50:51] op_sel_hi:[1,0]
	v_cvt_pk_bf16_f32 v4, v4, v5
	v_cvt_pk_bf16_f32 v5, v30, v31
	global_store_dwordx2 v[26:27], v[4:5], off offset:3072
	v_pk_mul_f32 v[4:5], v[28:29], v[50:51] op_sel_hi:[1,0]
	ds_read_b128 v[28:31], v51 offset:7168
	ds_read_b128 v[32:35], v51 offset:48128
	v_cvt_f32_f16_sdwa v41, v24 dst_sel:DWORD dst_unused:UNUSED_PAD src0_sel:WORD_1
	v_cvt_f32_f16_e32 v40, v24
	s_waitcnt vmcnt(61)
	v_cvt_f32_f16_sdwa v39, v23 dst_sel:DWORD dst_unused:UNUSED_PAD src0_sel:WORD_1
	v_cvt_f32_f16_e32 v38, v23
	s_waitcnt lgkmcnt(0)
	v_pk_fma_f32 v[30:31], v[36:37], v[30:31], v[34:35]
	v_cvt_f32_f16_sdwa v37, v22 dst_sel:DWORD dst_unused:UNUSED_PAD src0_sel:WORD_1
	v_cvt_f32_f16_e32 v36, v22
	v_pk_fma_f32 v[4:5], v[4:5], v[28:29], v[32:33]
	v_mov_b32_e32 v22, v41
	v_cvt_pk_bf16_f32 v4, v4, v5
	v_cvt_pk_bf16_f32 v5, v30, v31
	global_store_dwordx2 v[26:27], v[4:5], off offset:3584
	v_mov_b32_e32 v23, v37
	s_waitcnt vmcnt(61)
	v_cvt_f32_f16_sdwa v27, v20 dst_sel:DWORD dst_unused:UNUSED_PAD src0_sel:WORD_1
	v_cvt_f32_f16_sdwa v29, v21 dst_sel:DWORD dst_unused:UNUSED_PAD src0_sel:WORD_1
	v_mov_b32_e32 v4, v40
	v_mov_b32_e32 v5, v36
	v_pk_mul_f32 v[22:23], v[22:23], v[22:23]
	v_mov_b32_e32 v24, v43
	v_mov_b32_e32 v25, v39
	v_cvt_f32_f16_e32 v26, v20
	v_cvt_f32_f16_e32 v28, v21
	s_waitcnt vmcnt(60)
	v_cvt_f32_f16_sdwa v31, v18 dst_sel:DWORD dst_unused:UNUSED_PAD src0_sel:WORD_1
	v_pk_fma_f32 v[4:5], v[4:5], v[4:5], v[22:23]
	v_mov_b32_e32 v22, v42
	v_mov_b32_e32 v23, v38
	v_pk_mul_f32 v[24:25], v[24:25], v[24:25]
	v_cvt_f32_f16_e32 v30, v18
	v_cvt_f32_f16_sdwa v33, v19 dst_sel:DWORD dst_unused:UNUSED_PAD src0_sel:WORD_1
	v_pk_fma_f32 v[22:23], v[22:23], v[22:23], v[24:25]
	v_cvt_f32_f16_e32 v32, v19
	v_pk_add_f32 v[4:5], v[4:5], v[22:23]
	v_mov_b32_e32 v22, v27
	v_mov_b32_e32 v23, v29
	v_mov_b32_e32 v20, v26
	v_mov_b32_e32 v21, v28
	v_pk_mul_f32 v[22:23], v[22:23], v[22:23]
	v_mul_f32_e32 v18, v31, v31
	v_pk_fma_f32 v[20:21], v[20:21], v[20:21], v[22:23]
	v_pk_fma_f32 v[24:25], v[30:31], v[30:31], v[18:19] op_sel_hi:[1,1,0]
	v_mul_f32_e32 v18, v33, v33
	v_pk_add_f32 v[22:23], v[20:21], v[20:21] op_sel:[0,1] op_sel_hi:[1,0]
	v_pk_fma_f32 v[34:35], v[32:33], v[32:33], v[18:19] op_sel_hi:[1,1,0]
	s_waitcnt vmcnt(59)
	v_cvt_f32_f16_sdwa v19, v16 dst_sel:DWORD dst_unused:UNUSED_PAD src0_sel:WORD_1
	v_cvt_f32_f16_e32 v18, v16
	v_cvt_f32_f16_sdwa v21, v17 dst_sel:DWORD dst_unused:UNUSED_PAD src0_sel:WORD_1
	v_cvt_f32_f16_e32 v20, v17
	v_pk_add_f32 v[4:5], v[4:5], v[4:5] op_sel:[0,1] op_sel_hi:[1,0]
	v_pk_mul_f32 v[16:17], v[18:19], v[18:19]
	v_pk_mul_f32 v[44:45], v[20:21], v[20:21]
	v_mov_b32_e32 v5, v16
	v_mov_b32_e32 v23, v17
	v_mov_b32_e32 v25, v44
	v_mov_b32_e32 v35, v45
	v_pk_add_f32 v[4:5], v[4:5], v[22:23]
	v_pk_add_f32 v[16:17], v[24:25], v[34:35]
	s_waitcnt vmcnt(58)
	v_cvt_f32_f16_sdwa v23, v14 dst_sel:DWORD dst_unused:UNUSED_PAD src0_sel:WORD_1
	v_cvt_f32_f16_sdwa v25, v15 dst_sel:DWORD dst_unused:UNUSED_PAD src0_sel:WORD_1
	v_cvt_f32_f16_e32 v22, v14
	v_cvt_f32_f16_e32 v24, v15
	v_pk_add_f32 v[4:5], v[4:5], v[16:17]
	v_mov_b32_e32 v14, v23
	v_mov_b32_e32 v15, v25
	v_pk_add_f32 v[34:35], v[4:5], v[4:5] op_sel:[0,1] op_sel_hi:[1,0]
	v_mov_b32_e32 v4, v22
	v_mov_b32_e32 v5, v24
	v_pk_mul_f32 v[14:15], v[14:15], v[14:15]
	s_waitcnt vmcnt(56)
	v_cvt_f32_f16_sdwa v17, v11 dst_sel:DWORD dst_unused:UNUSED_PAD src0_sel:WORD_1
	v_pk_fma_f32 v[4:5], v[4:5], v[4:5], v[14:15]
	v_cvt_f32_f16_sdwa v15, v13 dst_sel:DWORD dst_unused:UNUSED_PAD src0_sel:WORD_1
	v_pk_add_f32 v[44:45], v[4:5], v[4:5] op_sel:[0,1] op_sel_hi:[1,0]
	v_cvt_f32_f16_sdwa v5, v12 dst_sel:DWORD dst_unused:UNUSED_PAD src0_sel:WORD_1
	v_cvt_f32_f16_e32 v4, v12
	v_cvt_f32_f16_e32 v14, v13
	v_cvt_f32_f16_e32 v16, v11
	v_mul_f32_e32 v12, v5, v5
	v_pk_fma_f32 v[46:47], v[4:5], v[4:5], v[12:13] op_sel_hi:[1,1,0]
	v_mul_f32_e32 v12, v15, v15
	v_pk_fma_f32 v[48:49], v[14:15], v[14:15], v[12:13] op_sel_hi:[1,1,0]
	v_cvt_f32_f16_sdwa v13, v10 dst_sel:DWORD dst_unused:UNUSED_PAD src0_sel:WORD_1
	v_cvt_f32_f16_e32 v12, v10
	v_pk_mul_f32 v[50:51], v[16:17], v[16:17]
	v_pk_mul_f32 v[10:11], v[12:13], v[12:13]
	s_nop 0
	v_mov_b32_e32 v35, v10
	v_mov_b32_e32 v45, v11
	v_mov_b32_e32 v47, v50
	v_mov_b32_e32 v49, v51
	v_pk_add_f32 v[10:11], v[34:35], v[44:45]
	v_pk_add_f32 v[34:35], v[46:47], v[48:49]
	s_nop 0
	v_pk_add_f32 v[10:11], v[10:11], v[34:35]
	s_nop 0
	v_add_f32_e32 v10, v10, v11
	s_nop 1
	v_add_f32_dpp v10, v10, v10 quad_perm:[1,0,3,2] row_mask:0xf bank_mask:0xf bound_ctrl:1
	s_nop 1
	v_add_f32_dpp v10, v10, v10 quad_perm:[2,3,0,1] row_mask:0xf bank_mask:0xf bound_ctrl:1
	s_nop 1
	v_add_f32_dpp v10, v10, v10 row_half_mirror row_mask:0xf bank_mask:0xf bound_ctrl:1
	s_nop 1
	v_add_f32_dpp v10, v10, v10 row_mirror row_mask:0xf bank_mask:0xf bound_ctrl:1
	s_nop 0
	v_readlane_b32 s8, v10, 16
	v_readlane_b32 s9, v10, 48
	v_readlane_b32 s6, v10, 0
	v_readlane_b32 s7, v10, 32
	v_mov_b32_e32 v10, s8
	v_mov_b32_e32 v11, s9
	v_pk_add_f32 v[10:11], s[6:7], v[10:11]
	s_nop 0
	v_add_f32_e32 v10, v10, v11
	v_fmamk_f32 v10, v10, 0x3a000000, v252
	v_cmp_gt_f32_e32 vcc, s55, v10
	v_mul_f32_e32 v11, 0x4f800000, v10
	s_nop 0
; #define GAS __attribute__((address_space(1)))
; __device__ __forceinline__ void norm_mod_phase2(const Args& a, Frame& F, const float* gain, const float* modl, int sh_off, int sc_off, int nrows, const float* slab_gate) {
;     ...
;     NR_FINISH(r7, nw + 7 * 2048, (nw + 7 * 2048) >> 12);
;     if (ML + nw < nrows) {
;         const int r = ML + nw, rc = nw;
;         const GAS v2u* xr = (const GAS v2u*)(X + (size_t)r * D) + F.lane;
; #pragma unroll
;         for (int j = 0; j < 8; ++j) r0[j] = xr[64 * j];
	v_cndmask_b32_e32 v10, v10, v11, vcc
	v_sqrt_f32_e32 v11, v10
	s_nop 0
	v_add_u32_e32 v34, -1, v11
	v_fma_f32 v35, -v34, v11, v10
	v_cmp_ge_f32_e64 s[8:9], 0, v35
	v_add_u32_e32 v35, 1, v11
	s_nop 0
	v_cndmask_b32_e64 v34, v11, v34, s[8:9]
	v_fma_f32 v11, -v35, v11, v10
	v_cmp_lt_f32_e64 s[8:9], 0, v11
	s_nop 1
	v_cndmask_b32_e64 v11, v34, v35, s[8:9]
	v_mul_f32_e32 v34, 0x37800000, v11
	v_cndmask_b32_e32 v11, v11, v34, vcc
	v_cmp_class_f32_e32 vcc, v10, v253
	s_lshr_b32 s8, s10, 1
	s_addk_i32 s8, 0x4000
	s_nop 0
	v_cndmask_b32_e32 v10, v11, v10, vcc
	v_div_scale_f32 v11, s[6:7], v10, v10, 1.0
	v_rcp_f32_e32 v34, v11
	s_lshl_b32 s6, s14, 1
	s_and_b32 s6, s6, 0xffffe000
	s_add_i32 s6, s6, 0
	v_fma_f32 v35, -v11, v34, 1.0
	v_fmac_f32_e32 v34, v35, v34
	v_div_scale_f32 v35, vcc, 1.0, v10, 1.0
	v_mul_f32_e32 v44, v35, v34
	v_fma_f32 v45, -v11, v44, v35
	v_fmac_f32_e32 v44, v45, v34
	v_fma_f32 v11, -v11, v44, v35
	v_div_fmas_f32 v11, v11, v34, v44
	v_div_fixup_f32 v34, v11, v10, 1.0
	v_pk_mul_f32 v[48:49], v[40:41], v[34:35] op_sel_hi:[1,0]
	v_pk_mul_f32 v[50:51], v[42:43], v[34:35] op_sel_hi:[1,0]
	v_add_u32_e32 v35, s6, v0
	ds_read_b128 v[40:43], v35
	ds_read_b128 v[44:47], v35 offset:40960
	v_lshl_add_u64 v[10:11], s[16:17], 1, v[2:3]
	v_lshl_add_u64 v[10:11], v[10:11], 0, v[6:7]
	v_pk_mul_f32 v[4:5], v[4:5], v[34:35] op_sel_hi:[1,0]
	v_pk_mul_f32 v[14:15], v[14:15], v[34:35] op_sel_hi:[1,0]
	s_waitcnt lgkmcnt(0)
	v_pk_fma_f32 v[42:43], v[42:43], v[50:51], v[46:47]
	v_pk_fma_f32 v[40:41], v[40:41], v[48:49], v[44:45]
	v_pk_mul_f32 v[44:45], v[36:37], v[34:35] op_sel_hi:[1,0]
	v_cvt_pk_bf16_f32 v40, v40, v41
	v_cvt_pk_bf16_f32 v41, v42, v43
	global_store_dwordx2 v[10:11], v[40:41], off
	v_pk_mul_f32 v[46:47], v[38:39], v[34:35] op_sel_hi:[1,0]
	ds_read_b128 v[36:39], v35 offset:1024
	ds_read_b128 v[40:43], v35 offset:41984
	s_bitcmp1_b32 s10, 0
	s_cselect_b32 s6, 0x7fffffff, s8
	s_cmp_lt_i32 s6, s47
	s_waitcnt lgkmcnt(0)
	v_pk_fma_f32 v[38:39], v[38:39], v[46:47], v[42:43]
	v_pk_fma_f32 v[36:37], v[36:37], v[44:45], v[40:41]
	v_pk_mul_f32 v[40:41], v[26:27], v[34:35] op_sel_hi:[1,0]
	v_cvt_pk_bf16_f32 v36, v36, v37
	v_cvt_pk_bf16_f32 v37, v38, v39
	global_store_dwordx2 v[10:11], v[36:37], off offset:512
	v_pk_mul_f32 v[42:43], v[28:29], v[34:35] op_sel_hi:[1,0]
	ds_read_b128 v[26:29], v35 offset:2048
	ds_read_b128 v[36:39], v35 offset:43008
	s_waitcnt lgkmcnt(0)
	v_pk_fma_f32 v[28:29], v[28:29], v[42:43], v[38:39]
	v_pk_fma_f32 v[26:27], v[26:27], v[40:41], v[36:37]
	v_pk_mul_f32 v[36:37], v[30:31], v[34:35] op_sel_hi:[1,0]
	v_cvt_pk_bf16_f32 v26, v26, v27
	v_cvt_pk_bf16_f32 v27, v28, v29
	global_store_dwordx2 v[10:11], v[26:27], off offset:1024
	v_pk_mul_f32 v[38:39], v[32:33], v[34:35] op_sel_hi:[1,0]
	ds_read_b128 v[26:29], v35 offset:3072
	ds_read_b128 v[30:33], v35 offset:44032
	s_waitcnt lgkmcnt(0)
	v_pk_fma_f32 v[28:29], v[38:39], v[28:29], v[32:33]
	v_pk_fma_f32 v[26:27], v[36:37], v[26:27], v[30:31]
	v_pk_mul_f32 v[30:31], v[18:19], v[34:35] op_sel_hi:[1,0]
	v_cvt_pk_bf16_f32 v26, v26, v27
	v_cvt_pk_bf16_f32 v27, v28, v29
	global_store_dwordx2 v[10:11], v[26:27], off offset:1536
	v_pk_mul_f32 v[32:33], v[20:21], v[34:35] op_sel_hi:[1,0]
	ds_read_b128 v[18:21], v35 offset:4096
	ds_read_b128 v[26:29], v35 offset:45056
	s_waitcnt lgkmcnt(0)
	v_pk_fma_f32 v[20:21], v[32:33], v[20:21], v[28:29]
	v_pk_fma_f32 v[18:19], v[30:31], v[18:19], v[26:27]
	v_pk_mul_f32 v[26:27], v[22:23], v[34:35] op_sel_hi:[1,0]
	v_cvt_pk_bf16_f32 v18, v18, v19
	v_cvt_pk_bf16_f32 v19, v20, v21
	global_store_dwordx2 v[10:11], v[18:19], off offset:2048
	v_pk_mul_f32 v[28:29], v[24:25], v[34:35] op_sel_hi:[1,0]
	ds_read_b128 v[18:21], v35 offset:5120
	ds_read_b128 v[22:25], v35 offset:46080
	s_waitcnt lgkmcnt(0)
	v_pk_fma_f32 v[20:21], v[28:29], v[20:21], v[24:25]
	v_pk_fma_f32 v[18:19], v[26:27], v[18:19], v[22:23]
	s_nop 0
	v_cvt_pk_bf16_f32 v18, v18, v19
	v_cvt_pk_bf16_f32 v19, v20, v21
	global_store_dwordx2 v[10:11], v[18:19], off offset:2560
	ds_read_b128 v[18:21], v35 offset:6144
	ds_read_b128 v[22:25], v35 offset:47104
	s_waitcnt lgkmcnt(0)
	v_pk_fma_f32 v[14:15], v[14:15], v[20:21], v[24:25]
	v_pk_fma_f32 v[4:5], v[4:5], v[18:19], v[22:23]
	v_pk_mul_f32 v[20:21], v[16:17], v[34:35] op_sel_hi:[1,0]
	v_cvt_pk_bf16_f32 v4, v4, v5
	v_cvt_pk_bf16_f32 v5, v14, v15
	global_store_dwordx2 v[10:11], v[4:5], off offset:3072
	v_pk_mul_f32 v[4:5], v[12:13], v[34:35] op_sel_hi:[1,0]
	ds_read_b128 v[12:15], v35 offset:7168
	ds_read_b128 v[16:19], v35 offset:48128
	s_waitcnt lgkmcnt(0)
	v_pk_fma_f32 v[14:15], v[20:21], v[14:15], v[18:19]
	v_pk_fma_f32 v[4:5], v[4:5], v[12:13], v[16:17]
	s_nop 0
	v_cvt_pk_bf16_f32 v4, v4, v5
	v_cvt_pk_bf16_f32 v5, v14, v15
	global_store_dwordx2 v[10:11], v[4:5], off offset:3584
	s_cbranch_scc0 .LBB0_1050
	s_ashr_i32 s9, s8, 31
	s_lshl_b64 s[6:7], s[8:9], 12
	v_lshl_add_u64 v[4:5], v[8:9], 0, s[6:7]
	v_lshl_add_u64 v[18:19], v[4:5], 0, v[6:7]
	global_load_dwordx2 v[22:23], v[18:19], off
	global_load_dwordx2 v[20:21], v[18:19], off offset:512
	global_load_dwordx2 v[16:17], v[18:19], off offset:1024
	global_load_dwordx2 v[12:13], v[18:19], off offset:1536
	global_load_dwordx2 v[14:15], v[18:19], off offset:2048
	global_load_dwordx2 v[10:11], v[18:19], off offset:2560
	global_load_dwordx2 v[8:9], v[18:19], off offset:3072
	global_load_dwordx2 v[4:5], v[18:19], off offset:3584
	s_andn2_b64 vcc, exec, s[4:5]
	v_lshlrev_b32_e32 v46, 2, v147
	s_cbranch_vccnz .LBB0_1049
; #define GAS __attribute__((address_space(1)))
; __device__ __forceinline__ unsigned xpk2(float lo, float hi) { if (XRES_F16) { const f32x2_t v = {lo, hi}; const f16x2_t h = __builtin_convertvector(v, f16x2_t); return __builtin_bit_cast(unsigned, h); } return pk2(lo, hi); }
; __device__ __forceinline__ float xlo(unsigned w) { if (XRES_F16) { const f16x2_t h = __builtin_bit_cast(f16x2_t, w); return (float)h[0]; } return __builtin_bit_cast(float, w << 16); }
; __device__ __forceinline__ float xhi(unsigned w) { if (XRES_F16) { const f16x2_t h = __builtin_bit_cast(f16x2_t, w); return (float)h[1]; } return __builtin_bit_cast(float, w & 0xffff0000u); }
; __device__ __forceinline__ void norm_mod_phase2(const Args& a, Frame& F, const float* gain, const float* modl, int sh_off, int sc_off, int nrows, const float* slab_gate) {
;     ...
;         if (slab_gate != nullptr) { const GAS f32x4* sl = (const GAS f32x4*)((const float*)(a.ws + WS_SLAB) + (size_t)rc * D) + F.lane;
; #pragma unroll
;             for (int j = 0; j < 8; ++j) { const f32x4 p = (sl[64 * j] + sl[64 * j + (size_t)MC * D / 4]) + (sl[64 * j + 2 * ((size_t)MC * D / 4)] + sl[64 * j + 3 * ((size_t)MC * D / 4)]);
;                 const f32x4 x = (f32x4){xlo(r0[j].x), xhi(r0[j].x), xlo(r0[j].y), xhi(r0[j].y)} + *(const GAS f32x4*)(slab_gate + 256 * j + 4 * F.lane) * p;
;                 v2u w; w.x = xpk2(x[0], x[1]); w.y = xpk2(x[2], x[3]); ((GAS v2u*)(X + (size_t)r * D) + F.lane)[64 * j] = w; r0[j] = w; } }
	s_sub_i32 s6, s8, 0x4000
	s_lshl_b32 s6, s6, 11
	s_mov_b32 s7, 0
	v_mov_b32_e32 v24, s72
	v_mov_b32_e32 v25, s73
	v_lshl_add_u64 v[24:25], s[6:7], 2, v[24:25]
	v_lshl_add_u64 v[24:25], v[24:25], 0, v[0:1]
	v_lshlrev_b32_e32 v0, 2, v46
	v_lshl_add_u64 v[26:27], s[86:87], 0, v[0:1]
	v_add_co_u32_e32 v28, vcc, 0x58400000, v24
	s_nop 1
	v_addc_co_u32_e32 v29, vcc, 0, v25, vcc
	v_add_co_u32_e32 v30, vcc, 0x58c00000, v24
	s_nop 1
	v_addc_co_u32_e32 v31, vcc, 0, v25, vcc
	v_add_co_u32_e32 v32, vcc, 0x59400000, v24
	s_nop 1
	v_addc_co_u32_e32 v33, vcc, 0, v25, vcc
	v_add_co_u32_e32 v34, vcc, 0x59c00000, v24
	s_nop 1
	v_addc_co_u32_e32 v35, vcc, 0, v25, vcc
	v_add_co_u32_e32 v36, vcc, 0x58401000, v24
	s_nop 1
	v_addc_co_u32_e32 v37, vcc, 0, v25, vcc
	v_add_co_u32_e32 v38, vcc, 0x58c01000, v24
	s_nop 1
	v_addc_co_u32_e32 v39, vcc, 0, v25, vcc
	v_add_co_u32_e32 v42, vcc, 0x59401000, v24
	s_nop 1
	v_addc_co_u32_e32 v43, vcc, 0, v25, vcc
	v_add_co_u32_e32 v44, vcc, 0x59c01000, v24
	s_nop 1
	v_addc_co_u32_e32 v45, vcc, 0, v25, vcc
	v_add_co_u32_e32 v48, vcc, 0x34000, v26
	s_nop 1
	v_addc_co_u32_e32 v49, vcc, 0, v27, vcc
	v_add_co_u32_e32 v50, vcc, 0x35000, v26
	s_nop 1
	v_addc_co_u32_e32 v51, vcc, 0, v27, vcc
	global_load_dwordx4 v[94:97], v[28:29], off
	global_load_dwordx4 v[98:101], v[30:31], off
	global_load_dwordx4 v[102:105], v[32:33], off
	global_load_dwordx4 v[106:109], v[34:35], off
	global_load_dwordx4 v[110:113], v[48:49], off
	global_load_dwordx4 v[114:117], v[28:29], off offset:1024
	global_load_dwordx4 v[118:121], v[30:31], off offset:1024
	global_load_dwordx4 v[122:125], v[32:33], off offset:1024
	global_load_dwordx4 v[126:129], v[34:35], off offset:1024
	global_load_dwordx4 v[130:133], v[48:49], off offset:1024
	global_load_dwordx4 v[134:137], v[28:29], off offset:2048
	global_load_dwordx4 v[138:141], v[30:31], off offset:2048
	global_load_dwordx4 v[142:145], v[32:33], off offset:2048
	global_load_dwordx4 v[146:149], v[34:35], off offset:2048
	global_load_dwordx4 v[150:153], v[48:49], off offset:2048
	global_load_dwordx4 v[154:157], v[28:29], off offset:3072
	global_load_dwordx4 v[158:161], v[30:31], off offset:3072
	global_load_dwordx4 v[162:165], v[32:33], off offset:3072
	global_load_dwordx4 v[170:173], v[34:35], off offset:3072
	global_load_dwordx4 v[174:177], v[48:49], off offset:3072
	s_waitcnt vmcnt(15)
	v_pk_add_f32 v[220:221], v[94:95], v[98:99]
	v_pk_add_f32 v[222:223], v[96:97], v[100:101]
	v_pk_add_f32 v[224:225], v[102:103], v[106:107]
	v_pk_add_f32 v[226:227], v[104:105], v[108:109]
	v_cvt_f32_f16_e32 v232, v22
	v_cvt_f32_f16_sdwa v233, v22 dst_sel:DWORD dst_unused:UNUSED_PAD src0_sel:WORD_1
	v_cvt_f32_f16_e32 v234, v23
	v_cvt_f32_f16_sdwa v235, v23 dst_sel:DWORD dst_unused:UNUSED_PAD src0_sel:WORD_1
	v_pk_add_f32 v[228:229], v[220:221], v[224:225]
	v_pk_add_f32 v[230:231], v[222:223], v[226:227]
	s_nop 1
	v_pk_fma_f32 v[236:237], v[110:111], v[228:229], v[232:233]
	v_pk_fma_f32 v[238:239], v[112:113], v[230:231], v[234:235]
	s_nop 1
	v_cvt_pk_f16_f32 v22, v236, v237
	v_cvt_pk_f16_f32 v23, v238, v239
	global_store_dwordx2 v[18:19], v[22:23], off
	global_load_dwordx4 v[94:97], v[36:37], off
	global_load_dwordx4 v[98:101], v[38:39], off
	global_load_dwordx4 v[102:105], v[42:43], off
	global_load_dwordx4 v[106:109], v[44:45], off
	global_load_dwordx4 v[110:113], v[50:51], off
	s_waitcnt vmcnt(16)
	v_pk_add_f32 v[220:221], v[114:115], v[118:119]
	v_pk_add_f32 v[222:223], v[116:117], v[120:121]
	v_pk_add_f32 v[224:225], v[122:123], v[126:127]
	v_pk_add_f32 v[226:227], v[124:125], v[128:129]
	v_cvt_f32_f16_e32 v232, v20
	v_cvt_f32_f16_sdwa v233, v20 dst_sel:DWORD dst_unused:UNUSED_PAD src0_sel:WORD_1
	v_cvt_f32_f16_e32 v234, v21
	v_cvt_f32_f16_sdwa v235, v21 dst_sel:DWORD dst_unused:UNUSED_PAD src0_sel:WORD_1
	v_pk_add_f32 v[228:229], v[220:221], v[224:225]
	v_pk_add_f32 v[230:231], v[222:223], v[226:227]
	s_nop 1
	v_pk_fma_f32 v[236:237], v[130:131], v[228:229], v[232:233]
	v_pk_fma_f32 v[238:239], v[132:133], v[230:231], v[234:235]
	s_nop 1
	v_cvt_pk_f16_f32 v20, v236, v237
	v_cvt_pk_f16_f32 v21, v238, v239
	global_store_dwordx2 v[18:19], v[20:21], off offset:512
	global_load_dwordx4 v[114:117], v[36:37], off offset:1024
	global_load_dwordx4 v[118:121], v[38:39], off offset:1024
	global_load_dwordx4 v[122:125], v[42:43], off offset:1024
	global_load_dwordx4 v[126:129], v[44:45], off offset:1024
	global_load_dwordx4 v[130:133], v[50:51], off offset:1024
	s_waitcnt vmcnt(17)
; #define GAS __attribute__((address_space(1)))
; __device__ __forceinline__ unsigned xpk2(float lo, float hi) { if (XRES_F16) { const f32x2_t v = {lo, hi}; const f16x2_t h = __builtin_convertvector(v, f16x2_t); return __builtin_bit_cast(unsigned, h); } return pk2(lo, hi); }
; __device__ __forceinline__ float xlo(unsigned w) { if (XRES_F16) { const f16x2_t h = __builtin_bit_cast(f16x2_t, w); return (float)h[0]; } return __builtin_bit_cast(float, w << 16); }
; __device__ __forceinline__ float xhi(unsigned w) { if (XRES_F16) { const f16x2_t h = __builtin_bit_cast(f16x2_t, w); return (float)h[1]; } return __builtin_bit_cast(float, w & 0xffff0000u); }
; __device__ __forceinline__ void norm_mod_phase2(const Args& a, Frame& F, const float* gain, const float* modl, int sh_off, int sc_off, int nrows, const float* slab_gate) {
;     ...
;         if (slab_gate != nullptr) { const GAS f32x4* sl = (const GAS f32x4*)((const float*)(a.ws + WS_SLAB) + (size_t)rc * D) + F.lane;
; #pragma unroll
;             for (int j = 0; j < 8; ++j) { const f32x4 p = (sl[64 * j] + sl[64 * j + (size_t)MC * D / 4]) + (sl[64 * j + 2 * ((size_t)MC * D / 4)] + sl[64 * j + 3 * ((size_t)MC * D / 4)]);
;                 const f32x4 x = (f32x4){xlo(r0[j].x), xhi(r0[j].x), xlo(r0[j].y), xhi(r0[j].y)} + *(const GAS f32x4*)(slab_gate + 256 * j + 4 * F.lane) * p;
;                 v2u w; w.x = xpk2(x[0], x[1]); w.y = xpk2(x[2], x[3]); ((GAS v2u*)(X + (size_t)r * D) + F.lane)[64 * j] = w; r0[j] = w; } }
	v_pk_add_f32 v[220:221], v[134:135], v[138:139]
	v_pk_add_f32 v[222:223], v[136:137], v[140:141]
	v_pk_add_f32 v[224:225], v[142:143], v[146:147]
	v_pk_add_f32 v[226:227], v[144:145], v[148:149]
	v_cvt_f32_f16_e32 v232, v16
	v_cvt_f32_f16_sdwa v233, v16 dst_sel:DWORD dst_unused:UNUSED_PAD src0_sel:WORD_1
	v_cvt_f32_f16_e32 v234, v17
	v_cvt_f32_f16_sdwa v235, v17 dst_sel:DWORD dst_unused:UNUSED_PAD src0_sel:WORD_1
	v_pk_add_f32 v[228:229], v[220:221], v[224:225]
	v_pk_add_f32 v[230:231], v[222:223], v[226:227]
	s_nop 1
	v_pk_fma_f32 v[236:237], v[150:151], v[228:229], v[232:233]
	v_pk_fma_f32 v[238:239], v[152:153], v[230:231], v[234:235]
	s_nop 1
	v_cvt_pk_f16_f32 v16, v236, v237
	v_cvt_pk_f16_f32 v17, v238, v239
	global_store_dwordx2 v[18:19], v[16:17], off offset:1024
	global_load_dwordx4 v[134:137], v[36:37], off offset:2048
	global_load_dwordx4 v[138:141], v[38:39], off offset:2048
	global_load_dwordx4 v[142:145], v[42:43], off offset:2048
	global_load_dwordx4 v[146:149], v[44:45], off offset:2048
	global_load_dwordx4 v[150:153], v[50:51], off offset:2048
	s_waitcnt vmcnt(18)
	v_pk_add_f32 v[220:221], v[154:155], v[158:159]
	v_pk_add_f32 v[222:223], v[156:157], v[160:161]
	v_pk_add_f32 v[224:225], v[162:163], v[170:171]
	v_pk_add_f32 v[226:227], v[164:165], v[172:173]
	v_cvt_f32_f16_e32 v232, v12
	v_cvt_f32_f16_sdwa v233, v12 dst_sel:DWORD dst_unused:UNUSED_PAD src0_sel:WORD_1
	v_cvt_f32_f16_e32 v234, v13
	v_cvt_f32_f16_sdwa v235, v13 dst_sel:DWORD dst_unused:UNUSED_PAD src0_sel:WORD_1
	v_pk_add_f32 v[228:229], v[220:221], v[224:225]
	v_pk_add_f32 v[230:231], v[222:223], v[226:227]
	s_nop 1
	v_pk_fma_f32 v[236:237], v[174:175], v[228:229], v[232:233]
	v_pk_fma_f32 v[238:239], v[176:177], v[230:231], v[234:235]
	s_nop 1
	v_cvt_pk_f16_f32 v12, v236, v237
	v_cvt_pk_f16_f32 v13, v238, v239
	global_store_dwordx2 v[18:19], v[12:13], off offset:1536
	global_load_dwordx4 v[154:157], v[36:37], off offset:3072
	global_load_dwordx4 v[158:161], v[38:39], off offset:3072
	global_load_dwordx4 v[162:165], v[42:43], off offset:3072
	global_load_dwordx4 v[170:173], v[44:45], off offset:3072
	global_load_dwordx4 v[174:177], v[50:51], off offset:3072
	s_waitcnt vmcnt(18)
	v_pk_add_f32 v[220:221], v[94:95], v[98:99]
	v_pk_add_f32 v[222:223], v[96:97], v[100:101]
	v_pk_add_f32 v[224:225], v[102:103], v[106:107]
	v_pk_add_f32 v[226:227], v[104:105], v[108:109]
	v_cvt_f32_f16_e32 v232, v14
	v_cvt_f32_f16_sdwa v233, v14 dst_sel:DWORD dst_unused:UNUSED_PAD src0_sel:WORD_1
	v_cvt_f32_f16_e32 v234, v15
	v_cvt_f32_f16_sdwa v235, v15 dst_sel:DWORD dst_unused:UNUSED_PAD src0_sel:WORD_1
	v_pk_add_f32 v[228:229], v[220:221], v[224:225]
	v_pk_add_f32 v[230:231], v[222:223], v[226:227]
	s_nop 1
	v_pk_fma_f32 v[236:237], v[110:111], v[228:229], v[232:233]
	v_pk_fma_f32 v[238:239], v[112:113], v[230:231], v[234:235]
	s_nop 1
	v_cvt_pk_f16_f32 v14, v236, v237
	v_cvt_pk_f16_f32 v15, v238, v239
	global_store_dwordx2 v[18:19], v[14:15], off offset:2048
	s_waitcnt vmcnt(13)
	v_pk_add_f32 v[220:221], v[114:115], v[118:119]
	v_pk_add_f32 v[222:223], v[116:117], v[120:121]
	v_pk_add_f32 v[224:225], v[122:123], v[126:127]
	v_pk_add_f32 v[226:227], v[124:125], v[128:129]
	v_cvt_f32_f16_e32 v232, v10
	v_cvt_f32_f16_sdwa v233, v10 dst_sel:DWORD dst_unused:UNUSED_PAD src0_sel:WORD_1
	v_cvt_f32_f16_e32 v234, v11
	v_cvt_f32_f16_sdwa v235, v11 dst_sel:DWORD dst_unused:UNUSED_PAD src0_sel:WORD_1
	v_pk_add_f32 v[228:229], v[220:221], v[224:225]
	v_pk_add_f32 v[230:231], v[222:223], v[226:227]
	s_nop 1
	v_pk_fma_f32 v[236:237], v[130:131], v[228:229], v[232:233]
	v_pk_fma_f32 v[238:239], v[132:133], v[230:231], v[234:235]
	s_nop 1
	v_cvt_pk_f16_f32 v10, v236, v237
	v_cvt_pk_f16_f32 v11, v238, v239
	global_store_dwordx2 v[18:19], v[10:11], off offset:2560
	s_waitcnt vmcnt(8)
	v_pk_add_f32 v[220:221], v[134:135], v[138:139]
	v_pk_add_f32 v[222:223], v[136:137], v[140:141]
	v_pk_add_f32 v[224:225], v[142:143], v[146:147]
	v_pk_add_f32 v[226:227], v[144:145], v[148:149]
	v_cvt_f32_f16_e32 v232, v8
	v_cvt_f32_f16_sdwa v233, v8 dst_sel:DWORD dst_unused:UNUSED_PAD src0_sel:WORD_1
	v_cvt_f32_f16_e32 v234, v9
	v_cvt_f32_f16_sdwa v235, v9 dst_sel:DWORD dst_unused:UNUSED_PAD src0_sel:WORD_1
	v_pk_add_f32 v[228:229], v[220:221], v[224:225]
	v_pk_add_f32 v[230:231], v[222:223], v[226:227]
	s_nop 1
	v_pk_fma_f32 v[236:237], v[150:151], v[228:229], v[232:233]
	v_pk_fma_f32 v[238:239], v[152:153], v[230:231], v[234:235]
	s_nop 1
	v_cvt_pk_f16_f32 v8, v236, v237
	v_cvt_pk_f16_f32 v9, v238, v239
	global_store_dwordx2 v[18:19], v[8:9], off offset:3072
	s_waitcnt vmcnt(3)
	v_pk_add_f32 v[220:221], v[154:155], v[158:159]
	v_pk_add_f32 v[222:223], v[156:157], v[160:161]
	v_pk_add_f32 v[224:225], v[162:163], v[170:171]
	v_pk_add_f32 v[226:227], v[164:165], v[172:173]
	v_cvt_f32_f16_e32 v232, v4
	v_cvt_f32_f16_sdwa v233, v4 dst_sel:DWORD dst_unused:UNUSED_PAD src0_sel:WORD_1
	v_cvt_f32_f16_e32 v234, v5
	v_cvt_f32_f16_sdwa v235, v5 dst_sel:DWORD dst_unused:UNUSED_PAD src0_sel:WORD_1
	v_pk_add_f32 v[228:229], v[220:221], v[224:225]
	v_pk_add_f32 v[230:231], v[222:223], v[226:227]
	s_nop 1
	v_pk_fma_f32 v[236:237], v[174:175], v[228:229], v[232:233]
	v_pk_fma_f32 v[238:239], v[176:177], v[230:231], v[234:235]
	s_nop 1
	v_cvt_pk_f16_f32 v4, v236, v237
	v_cvt_pk_f16_f32 v5, v238, v239
	global_store_dwordx2 v[18:19], v[4:5], off offset:3584
